# lru_m1 conv: 32 shifted row loads per item replaced by 10 loads at item start + DPP row shifts; jb waits vmcnt(10)
# speedup vs baseline: 1.0130x; 1.0043x over previous
; #define LAS __attribute__((address_space(3)))
; __device__ __forceinline__ void ld8bf(const bf16_t* p, float (&o)[8]) { unpack8(*(const u32x4*)p, o); }
; __device__ __forceinline__ const float* in_ptr(const Args& a, int i) { asm volatile("" : "+s"(i)); return a.in[i]; }
; __device__ __forceinline__ void w_lru_m1(const Args& a, int l, unsigned char* ws, const bf16_t* proj, bf16_t* y, LAS unsigned char* wl, int b, int ck_, int h, int lane) {
;     LAS float* xcf = (LAS float*)wl;
;     const int row0 = b * SEQ + 64 * ck_, lo = lane & 15, fq = lane >> 4;
;     const float* cw = in_ptr(a, I_LCW) + (size_t)l * 4 * 512; const float* cbias = in_ptr(a, I_LCB) + l * 512;
;     const bf16_t* gwt = (const bf16_t*)(ws + WS_GATE) + (size_t)l * 65536;
;     const bf16_t* waT = gwt + h * 4096; const bf16_t* wxT = gwt + 32768 + h * 4096;
;     const float* ba = in_ptr(a, I_BA) + l * 512 + 64 * h; const float* bx = in_ptr(a, I_BX) + l * 512 + 64 * h; const float* lam = in_ptr(a, I_LAM) + l * 512 + 64 * h;
;     bf16x8 nWa[2], nWx[2]; f32x4 nba, nbx, nlam;
; #pragma unroll
;     for (int kk = 0; kk < 2; ++kk) { nWa[kk] = *(const bf16x8*)(waT + lo * 64 + 32 * kk + 8 * fq); nWx[kk] = *(const bf16x8*)(wxT + lo * 64 + 32 * kk + 8 * fq); }
;     nba = *(const f32x4*)(ba + 4 * fq); nbx = *(const f32x4*)(bx + 4 * fq); nlam = *(const f32x4*)(lam + 4 * fq);
;     bf16x8 Xf[4][2];
; #pragma unroll
;     for (int kk = 0; kk < 2; ++kk) { const int ch0 = 64 * h + 32 * kk + 8 * fq; float w[4][8], bs[8];
; #pragma unroll
;         for (int j = 0; j < 8; ++j) { bs[j] = cbias[ch0 + j];
; #pragma unroll
;             for (int k = 0; k < 4; ++k) w[k][j] = cw[k * 512 + ch0 + j]; }
; #pragma unroll
;         for (int tb = 0; tb < 4; ++tb) { const int tok = 16 * tb + lo, t = 64 * ck_ + tok; float s[8];
; #pragma unroll
;             for (int j = 0; j < 8; ++j) s[j] = bs[j];
; #pragma unroll
;             for (int k = 0; k < 4; ++k) { const int tt = t - 3 + k; float x[8];
;                 ld8bf(proj + (size_t)(b * SEQ + (tt >= 0 ? tt : 0)) * NIN + C_LX + ch0, x);
.LBB0_520:
	s_lshr_b32 s20, s24, 8
	s_lshr_b32 s21, s24, 9
	s_add_i32 s20, s20, s24
	s_and_b32 s21, s21, 12
	s_add_i32 s20, s20, s21
	s_and_b32 s91, s20, 15
	s_cmp_gt_u32 s91, 7
	s_cbranch_scc1 .LBB0_519
	s_ashr_i32 s20, s24, 31
	s_ashr_i32 s90, s24, 4
	s_lshr_b32 s20, s20, 25
	s_add_i32 s27, s90, s20
	s_and_b32 s20, s27, 0xffffff80
	v_mov_b32_e32 v122, v144
	s_mov_b32 s34, 3
	s_sub_i32 s46, s90, s20
	s_ashr_i32 s35, s34, 31
	s_lshl_b32 s20, s46, 6
	s_lshl_b64 s[34:35], s[34:35], 3
	s_add_u32 s34, s0, s34
	s_addc_u32 s35, s1, s35
	s_load_dwordx2 s[40:41], s[34:35], 0x0
	s_mov_b32 s34, 4
	s_ashr_i32 s35, s34, 31
	s_lshl_b64 s[34:35], s[34:35], 3
	s_add_u32 s34, s0, s34
	s_addc_u32 s35, s1, s35
	s_lshl_b32 s21, s91, 13
	s_add_u32 s92, s2, s21
	s_addc_u32 s93, s3, 0
	s_load_dwordx2 s[42:43], s[34:35], 0x0
	s_add_u32 s34, s68, s21
	s_mov_b32 s44, 6
	s_addc_u32 s35, s70, 0
	s_ashr_i32 s45, s44, 31
	s_lshl_b64 s[44:45], s[44:45], 3
	s_add_u32 s44, s0, s44
	s_addc_u32 s45, s1, s45
	s_waitcnt lgkmcnt(0)
	s_mov_b32 s48, 8
	s_load_dwordx2 s[44:45], s[44:45], 0x0
	s_ashr_i32 s49, s48, 31
	s_lshl_b32 s21, s91, 6
	s_lshl_b64 s[48:49], s[48:49], 3
	s_add_u32 s48, s0, s48
	s_addc_u32 s49, s1, s49
	s_load_dwordx2 s[48:49], s[48:49], 0x0
	v_ashrrev_i32_e32 v8, 4, v122
	v_and_b32_e32 v136, 15, v122
	v_lshlrev_b32_e32 v4, 3, v8
	v_lshlrev_b32_e32 v2, 7, v136
	s_waitcnt lgkmcnt(0)
	s_add_u32 s47, s48, s88
	s_mov_b32 s48, 9
	s_addc_u32 s50, s49, s89
	s_ashr_i32 s49, s48, 31
	s_lshl_b64 s[48:49], s[48:49], 3
	s_add_u32 s48, s0, s48
	s_addc_u32 s49, s1, s49
	s_add_u32 s48, s78, 0x3b00000
	s_addc_u32 s49, s79, 0x0
	v_ashrrev_i32_e32 v5, 31, v4
	v_lshl_add_u64 v[0:1], s[92:93], 0, v[2:3]
	v_lshlrev_b64 v[100:101], 1, v[4:5]
	v_lshl_add_u64 v[0:1], v[0:1], 0, v[100:101]
	s_waitcnt lgkmcnt(0)
	s_add_u32 s51, s48, s88
	s_addc_u32 s52, s49, s89
	s_lshl_b32 s27, s27, 6
	s_and_b32 s27, s27, 0xffffe000
	s_add_u32 s48, s40, s96
	s_addc_u32 s49, s41, s97
	s_add_u32 s42, s42, s88
	s_addc_u32 s43, s43, s89
	s_add_u32 s40, s44, s88
	s_addc_u32 s41, s45, s89
	s_lshl_b32 s53, s91, 8
	s_add_u32 s40, s40, s53
	v_lshl_add_u64 v[6:7], s[34:35], 0, v[2:3]
	s_addc_u32 s41, s41, 0
	v_lshl_add_u64 v[6:7], v[6:7], 0, v[100:101]
	flat_load_dwordx4 v[52:55], v[0:1]
	flat_load_dwordx4 v[56:59], v[6:7]
	flat_load_dwordx4 v[60:63], v[0:1] offset:64
	flat_load_dwordx4 v[64:67], v[6:7] offset:64
	s_add_u32 s44, s47, s53
	v_lshlrev_b32_e32 v0, 2, v8
	s_addc_u32 s45, s50, 0
	v_ashrrev_i32_e32 v1, 31, v0
	s_add_u32 s50, s51, s53
	v_lshlrev_b64 v[6:7], 2, v[0:1]
	s_addc_u32 s51, s52, 0
	v_lshl_add_u64 v[108:109], s[40:41], 0, v[6:7]
	s_add_i32 s40, s20, -3
	v_add_u32_e32 v78, s21, v4
	v_lshl_add_u64 v[110:111], s[44:45], 0, v[6:7]
	v_lshl_add_u64 v[112:113], s[50:51], 0, v[6:7]
	v_ashrrev_i32_e32 v79, 31, v78
	v_add_u32_e32 v6, s40, v136
	v_lshlrev_b64 v[4:5], 2, v[78:79]
	v_cmp_lt_i32_e64 s[50:51], -1, v6
	v_lshl_add_u64 v[76:77], s[42:43], 0, v[4:5]
	v_lshl_add_u64 v[86:87], s[48:49], 0, v[4:5]
	s_mov_b64 s[42:43], 0x1000
	v_cndmask_b32_e64 v4, 0, v6, s[50:51]
	v_lshl_add_u64 v[36:37], v[86:87], 0, s[42:43]
	s_mov_b64 s[42:43], 0x1800
	v_lshl_add_u64 v[80:81], v[78:79], 1, s[8:9]
	v_add_u32_e32 v79, s27, v4
	v_lshl_add_u64 v[82:83], v[86:87], 0, s[42:43]
	v_max_i32_e32 v4, -1, v6
	s_or_b32 s80, s27, 1
	v_add_u32_e32 v92, s80, v4
	v_max_i32_e32 v4, -2, v6
	s_or_b32 s81, s27, 2
	v_add_u32_e32 v93, s81, v4
	s_cmp_gt_i32 s46, -1
	v_or_b32_e32 v4, s20, v136
	s_cselect_b64 s[42:43], -1, 0
	v_cndmask_b32_e64 v4, 0, v4, s[42:43]
	v_add_u32_e32 v94, s27, v4
	global_load_dwordx4 v[48:51], v[108:109], off
	global_load_dwordx4 v[44:47], v[110:111], off
	global_load_dwordx4 v[88:91], v[112:113], off
	v_lshl_add_u32 v95, v8, 5, s6
	v_cmp_lt_i32_e64 s[48:49], -2, v6
	v_cmp_lt_i32_e64 s[44:45], -3, v6
	global_load_dwordx4 v[20:23], v[76:77], off offset:16
	s_nop 0
	global_load_dwordx4 v[4:7], v[76:77], off
	global_load_dwordx4 v[24:27], v[86:87], off offset:16
	global_load_dwordx4 v[32:35], v[86:87], off
	global_load_dwordx4 v[28:31], v[86:87], off offset:2064
	global_load_dwordx4 v[40:43], v[86:87], off offset:2048
	v_add_co_u32_e32 v96, vcc, s73, v86
	v_mad_u32_u24 v121, v136, s76, v95
	s_nop 0
	v_addc_co_u32_e32 v97, vcc, 0, v87, vcc
	global_load_dwordx4 v[68:71], v[96:97], off
	s_nop 0
	global_load_dwordx4 v[36:39], v[36:37], off offset:16
	s_nop 0
	global_load_dwordx4 v[104:107], v[96:97], off offset:2048
	global_load_dwordx4 v[114:117], v[82:83], off offset:16
	v_add_u32_e32 v186, s20, v136
	v_add_u32_e32 v187, -16, v186
	v_max_i32_e32 v187, 0, v187
	v_add_u32_e32 v187, s27, v187
	v_add_u32_e32 v186, s27, v186
	v_mad_i64_i32 v[188:189], s[46:47], v187, s72, v[80:81]
	global_load_dwordx4 v[222:225], v[188:189], off
	global_load_dwordx4 v[242:245], v[188:189], off offset:64
	v_mad_i64_i32 v[188:189], s[46:47], v186, s72, v[80:81]
	global_load_dwordx4 v[226:229], v[188:189], off
	global_load_dwordx4 v[246:249], v[188:189], off offset:64
	v_add_u32_e32 v187, 16, v186
	v_mad_i64_i32 v[188:189], s[46:47], v187, s72, v[80:81]
	global_load_dwordx4 v[230:233], v[188:189], off
	global_load_dwordx4 v[250:253], v[188:189], off offset:64
	v_add_u32_e32 v187, 32, v186
	v_mad_i64_i32 v[188:189], s[46:47], v187, s72, v[80:81]
	global_load_dwordx4 v[234:237], v[188:189], off
	global_load_dwordx4 v[190:193], v[188:189], off offset:64
	v_add_u32_e32 v187, 48, v186
	v_mad_i64_i32 v[188:189], s[46:47], v187, s72, v[80:81]
	global_load_dwordx4 v[238:241], v[188:189], off
	global_load_dwordx4 v[194:197], v[188:189], off offset:64
	v_or_b32_e32 v140, 16, v136
	v_or_b32_e32 v139, 32, v136
	v_or_b32_e32 v137, 48, v136
	v_mov_b64_e32 v[102:103], s[8:9]
	s_waitcnt vmcnt(0) lgkmcnt(0)
; __device__ __forceinline__ void ld8bf(const bf16_t* p, float (&o)[8]) { unpack8(*(const u32x4*)p, o); }
; __device__ __forceinline__ bf16x8 pack_frag(const float (&v)[8]) { return __builtin_bit_cast(bf16x8, pack8(v)); }
; __device__ __forceinline__ void w_lru_m1(const Args& a, int l, unsigned char* ws, const bf16_t* proj, bf16_t* y, LAS unsigned char* wl, int b, int ck_, int h, int lane) {
;     ...
;         for (int tb = 0; tb < 4; ++tb) { const int tok = 16 * tb + lo, t = 64 * ck_ + tok; float s[8];
; #pragma unroll
;             for (int j = 0; j < 8; ++j) s[j] = bs[j];
; #pragma unroll
;             for (int k = 0; k < 4; ++k) { const int tt = t - 3 + k; float x[8];
;                 ld8bf(proj + (size_t)(b * SEQ + (tt >= 0 ? tt : 0)) * NIN + C_LX + ch0, x);
; #pragma unroll
;                 for (int j = 0; j < 8; ++j) s[j] += (tt >= 0 ? w[k][j] : 0.f) * x[j]; }
;             Xf[tb][kk] = pack_frag(s);
; #pragma unroll
;             for (int j = 0; j < 8; ++j) xcf[tok * 65 + 32 * kk + 8 * fq + j] = s[j]; }
	v_mov_b32_dpp v72, v222 row_ror:3 row_mask:0xf bank_mask:0xf
	v_mov_b32_dpp v73, v223 row_ror:3 row_mask:0xf bank_mask:0xf
	v_mov_b32_dpp v74, v224 row_ror:3 row_mask:0xf bank_mask:0xf
	v_mov_b32_dpp v75, v225 row_ror:3 row_mask:0xf bank_mask:0xf
	v_mov_b32_dpp v72, v226 row_shr:3 row_mask:0xf bank_mask:0xf
	v_mov_b32_dpp v73, v227 row_shr:3 row_mask:0xf bank_mask:0xf
	v_mov_b32_dpp v74, v228 row_shr:3 row_mask:0xf bank_mask:0xf
	v_mov_b32_dpp v75, v229 row_shr:3 row_mask:0xf bank_mask:0xf
	v_mov_b32_dpp v16, v222 row_ror:2 row_mask:0xf bank_mask:0xf
	v_mov_b32_dpp v17, v223 row_ror:2 row_mask:0xf bank_mask:0xf
	v_mov_b32_dpp v18, v224 row_ror:2 row_mask:0xf bank_mask:0xf
	v_mov_b32_dpp v19, v225 row_ror:2 row_mask:0xf bank_mask:0xf
	v_mov_b32_dpp v16, v226 row_shr:2 row_mask:0xf bank_mask:0xf
	v_mov_b32_dpp v17, v227 row_shr:2 row_mask:0xf bank_mask:0xf
	v_mov_b32_dpp v18, v228 row_shr:2 row_mask:0xf bank_mask:0xf
	v_mov_b32_dpp v19, v229 row_shr:2 row_mask:0xf bank_mask:0xf
	v_mov_b32_dpp v12, v222 row_ror:1 row_mask:0xf bank_mask:0xf
	v_mov_b32_dpp v13, v223 row_ror:1 row_mask:0xf bank_mask:0xf
	v_mov_b32_dpp v14, v224 row_ror:1 row_mask:0xf bank_mask:0xf
	v_mov_b32_dpp v15, v225 row_ror:1 row_mask:0xf bank_mask:0xf
	v_mov_b32_dpp v12, v226 row_shr:1 row_mask:0xf bank_mask:0xf
	v_mov_b32_dpp v13, v227 row_shr:1 row_mask:0xf bank_mask:0xf
	v_mov_b32_dpp v14, v228 row_shr:1 row_mask:0xf bank_mask:0xf
	v_mov_b32_dpp v15, v229 row_shr:1 row_mask:0xf bank_mask:0xf
	v_mov_b64_e32 v[8:9], v[226:227]
	v_mov_b64_e32 v[10:11], v[228:229]
	v_lshlrev_b32_e32 v82, 16, v72
	v_lshlrev_b32_e32 v84, 16, v73
	v_and_b32_e32 v83, 0xffff0000, v72
	v_and_b32_e32 v85, 0xffff0000, v73
	v_cndmask_b32_e64 v73, 0, v33, s[50:51]
	v_cndmask_b32_e64 v72, 0, v32, s[50:51]
	v_cndmask_b32_e64 v99, 0, v35, s[50:51]
	v_cndmask_b32_e64 v98, 0, v34, s[50:51]
	v_pk_fma_f32 v[84:85], v[98:99], v[84:85], v[6:7]
	v_pk_fma_f32 v[72:73], v[72:73], v[82:83], v[4:5]
	v_lshlrev_b32_e32 v82, 16, v17
	v_lshlrev_b32_e32 v98, 16, v16
	v_and_b32_e32 v83, 0xffff0000, v17
	v_and_b32_e32 v99, 0xffff0000, v16
	v_cndmask_b32_e64 v17, 0, v43, s[48:49]
	v_cndmask_b32_e64 v16, 0, v42, s[48:49]
	v_cndmask_b32_e64 v119, 0, v41, s[48:49]
	v_cndmask_b32_e64 v118, 0, v40, s[48:49]
	v_pk_fma_f32 v[72:73], v[118:119], v[98:99], v[72:73]
	v_pk_fma_f32 v[16:17], v[16:17], v[82:83], v[84:85]
	v_lshlrev_b32_e32 v82, 16, v12
	v_lshlrev_b32_e32 v84, 16, v13
	v_and_b32_e32 v83, 0xffff0000, v12
	v_and_b32_e32 v85, 0xffff0000, v13
	v_cndmask_b32_e64 v13, 0, v69, s[44:45]
	v_cndmask_b32_e64 v12, 0, v68, s[44:45]
	v_cndmask_b32_e64 v99, 0, v71, s[44:45]
	v_cndmask_b32_e64 v98, 0, v70, s[44:45]
	v_pk_fma_f32 v[16:17], v[98:99], v[84:85], v[16:17]
	v_pk_fma_f32 v[12:13], v[12:13], v[82:83], v[72:73]
	v_lshlrev_b32_e32 v84, 16, v9
	v_lshlrev_b32_e32 v98, 16, v8
	v_and_b32_e32 v85, 0xffff0000, v9
	v_and_b32_e32 v99, 0xffff0000, v8
	v_cndmask_b32_e64 v73, 0, v107, s[42:43]
	v_cndmask_b32_e64 v72, 0, v106, s[42:43]
	v_cndmask_b32_e64 v83, 0, v105, s[42:43]
	v_cndmask_b32_e64 v82, 0, v104, s[42:43]
	v_pk_fma_f32 v[8:9], v[82:83], v[98:99], v[12:13]
	v_pk_fma_f32 v[12:13], v[72:73], v[84:85], v[16:17]
	v_cvt_pk_bf16_f32 v16, v8, v9
	v_cvt_pk_bf16_f32 v17, v12, v13
	ds_write2_b32 v121, v12, v13 offset0:2 offset1:3
	ds_write2_b32 v121, v8, v9 offset1:1
	v_lshlrev_b32_e32 v8, 16, v74
	v_lshlrev_b32_e32 v12, 16, v75
	v_and_b32_e32 v9, 0xffff0000, v74
	v_and_b32_e32 v13, 0xffff0000, v75
	v_cndmask_b32_e64 v75, 0, v25, s[50:51]
	v_cndmask_b32_e64 v74, 0, v24, s[50:51]
	v_cndmask_b32_e64 v85, 0, v27, s[50:51]
	v_cndmask_b32_e64 v84, 0, v26, s[50:51]
	v_pk_fma_f32 v[12:13], v[84:85], v[12:13], v[22:23]
	v_pk_fma_f32 v[8:9], v[74:75], v[8:9], v[20:21]
	v_lshlrev_b32_e32 v74, 16, v19
	v_lshlrev_b32_e32 v84, 16, v18
	v_and_b32_e32 v75, 0xffff0000, v19
	v_and_b32_e32 v85, 0xffff0000, v18
	v_cndmask_b32_e64 v19, 0, v31, s[48:49]
	v_cndmask_b32_e64 v18, 0, v30, s[48:49]
	v_cndmask_b32_e64 v99, 0, v29, s[48:49]
	v_cndmask_b32_e64 v98, 0, v28, s[48:49]
	v_pk_fma_f32 v[8:9], v[98:99], v[84:85], v[8:9]
	v_pk_fma_f32 v[12:13], v[18:19], v[74:75], v[12:13]
	v_lshlrev_b32_e32 v18, 16, v14
	v_lshlrev_b32_e32 v74, 16, v15
	v_and_b32_e32 v19, 0xffff0000, v14
	v_and_b32_e32 v75, 0xffff0000, v15
	v_cndmask_b32_e64 v15, 0, v37, s[44:45]
	v_cndmask_b32_e64 v14, 0, v36, s[44:45]
	v_cndmask_b32_e64 v85, 0, v39, s[44:45]
	v_cndmask_b32_e64 v84, 0, v38, s[44:45]
	v_pk_fma_f32 v[12:13], v[84:85], v[74:75], v[12:13]
	v_pk_fma_f32 v[8:9], v[14:15], v[18:19], v[8:9]
	v_lshlrev_b32_e32 v14, 16, v11
	v_lshlrev_b32_e32 v18, 16, v10
	v_and_b32_e32 v15, 0xffff0000, v11
	v_and_b32_e32 v19, 0xffff0000, v10
	v_cndmask_b32_e64 v75, 0, v117, s[42:43]
	v_cndmask_b32_e64 v74, 0, v116, s[42:43]
	v_cndmask_b32_e64 v85, 0, v115, s[42:43]
	v_cndmask_b32_e64 v84, 0, v114, s[42:43]
	v_add_u32_e32 v98, s40, v140
	v_pk_fma_f32 v[8:9], v[84:85], v[18:19], v[8:9]
	v_pk_fma_f32 v[10:11], v[74:75], v[14:15], v[12:13]
	v_cmp_lt_i32_e64 s[62:63], -1, v98
	v_cvt_pk_bf16_f32 v18, v8, v9
	ds_write2_b32 v121, v10, v11 offset0:6 offset1:7
	ds_write2_b32 v121, v8, v9 offset0:4 offset1:5
	v_cndmask_b32_e64 v8, 0, v98, s[62:63]
	v_cmp_lt_i32_e64 s[60:61], -2, v98
	v_max_i32_e32 v12, -1, v98
	v_cmp_lt_i32_e64 s[58:59], -3, v98
	v_max_i32_e32 v98, -2, v98
	v_add_u32_e32 v142, s81, v98
	v_add_u32_e32 v134, s27, v8
	v_add_u32_e32 v135, s80, v12
	v_mov_b32_dpp v104, v226 row_ror:1 row_mask:0xf bank_mask:0xf
	v_mov_b32_dpp v105, v227 row_ror:1 row_mask:0xf bank_mask:0xf
	v_mov_b32_dpp v106, v228 row_ror:1 row_mask:0xf bank_mask:0xf
	v_mov_b32_dpp v107, v229 row_ror:1 row_mask:0xf bank_mask:0xf
; __device__ __forceinline__ void ld8bf(const bf16_t* p, float (&o)[8]) { unpack8(*(const u32x4*)p, o); }
; __device__ __forceinline__ bf16x8 pack_frag(const float (&v)[8]) { return __builtin_bit_cast(bf16x8, pack8(v)); }
; __device__ __forceinline__ void w_lru_m1(const Args& a, int l, unsigned char* ws, const bf16_t* proj, bf16_t* y, LAS unsigned char* wl, int b, int ck_, int h, int lane) {
;     ...
;         for (int tb = 0; tb < 4; ++tb) { const int tok = 16 * tb + lo, t = 64 * ck_ + tok; float s[8];
; #pragma unroll
;             for (int j = 0; j < 8; ++j) s[j] = bs[j];
; #pragma unroll
;             for (int k = 0; k < 4; ++k) { const int tt = t - 3 + k; float x[8];
;                 ld8bf(proj + (size_t)(b * SEQ + (tt >= 0 ? tt : 0)) * NIN + C_LX + ch0, x);
; #pragma unroll
;                 for (int j = 0; j < 8; ++j) s[j] += (tt >= 0 ? w[k][j] : 0.f) * x[j]; }
;             Xf[tb][kk] = pack_frag(s);
; #pragma unroll
;             for (int j = 0; j < 8; ++j) xcf[tok * 65 + 32 * kk + 8 * fq + j] = s[j]; }
	v_mov_b32_dpp v104, v230 row_shr:1 row_mask:0xf bank_mask:0xf
	v_mov_b32_dpp v105, v231 row_shr:1 row_mask:0xf bank_mask:0xf
	v_mov_b32_dpp v106, v232 row_shr:1 row_mask:0xf bank_mask:0xf
	v_mov_b32_dpp v107, v233 row_shr:1 row_mask:0xf bank_mask:0xf
	v_or_b32_e32 v98, s20, v140
	v_cvt_pk_bf16_f32 v19, v10, v11
	v_mov_b32_dpp v8, v226 row_ror:3 row_mask:0xf bank_mask:0xf
	v_mov_b32_dpp v9, v227 row_ror:3 row_mask:0xf bank_mask:0xf
	v_mov_b32_dpp v10, v228 row_ror:3 row_mask:0xf bank_mask:0xf
	v_mov_b32_dpp v11, v229 row_ror:3 row_mask:0xf bank_mask:0xf
	v_mov_b32_dpp v8, v230 row_shr:3 row_mask:0xf bank_mask:0xf
	v_mov_b32_dpp v9, v231 row_shr:3 row_mask:0xf bank_mask:0xf
	v_mov_b32_dpp v10, v232 row_shr:3 row_mask:0xf bank_mask:0xf
	v_mov_b32_dpp v11, v233 row_shr:3 row_mask:0xf bank_mask:0xf
	v_cndmask_b32_e64 v98, 0, v98, s[42:43]
	v_mov_b32_dpp v12, v226 row_ror:2 row_mask:0xf bank_mask:0xf
	v_mov_b32_dpp v13, v227 row_ror:2 row_mask:0xf bank_mask:0xf
	v_mov_b32_dpp v14, v228 row_ror:2 row_mask:0xf bank_mask:0xf
	v_mov_b32_dpp v15, v229 row_ror:2 row_mask:0xf bank_mask:0xf
	v_mov_b32_dpp v12, v230 row_shr:2 row_mask:0xf bank_mask:0xf
	v_mov_b32_dpp v13, v231 row_shr:2 row_mask:0xf bank_mask:0xf
	v_mov_b32_dpp v14, v232 row_shr:2 row_mask:0xf bank_mask:0xf
	v_mov_b32_dpp v15, v233 row_shr:2 row_mask:0xf bank_mask:0xf
	v_add_u32_e32 v143, s27, v98
	v_mov_b64_e32 v[114:115], v[230:231]
	v_mov_b64_e32 v[116:117], v[232:233]
	v_mov_b32_e32 v98, 0x1040
	v_mad_u32_u24 v123, v136, s76, v98
	v_cndmask_b32_e64 v127, 0, v35, s[62:63]
	v_cndmask_b32_e64 v126, 0, v34, s[62:63]
	v_cndmask_b32_e64 v129, 0, v41, s[60:61]
	v_cndmask_b32_e64 v128, 0, v40, s[60:61]
	v_add_u32_e32 v125, v95, v123
	s_waitcnt vmcnt(0) lgkmcnt(0)
	v_lshlrev_b32_e32 v98, 16, v8
	v_lshlrev_b32_e32 v118, 16, v9
	v_and_b32_e32 v99, 0xffff0000, v8
	v_and_b32_e32 v119, 0xffff0000, v9
	v_cndmask_b32_e64 v9, 0, v33, s[62:63]
	v_cndmask_b32_e64 v8, 0, v32, s[62:63]
	v_pk_fma_f32 v[118:119], v[126:127], v[118:119], v[6:7]
	v_pk_fma_f32 v[8:9], v[8:9], v[98:99], v[4:5]
	v_lshlrev_b32_e32 v98, 16, v13
	v_lshlrev_b32_e32 v126, 16, v12
	v_and_b32_e32 v99, 0xffff0000, v13
	v_and_b32_e32 v127, 0xffff0000, v12
	v_cndmask_b32_e64 v13, 0, v43, s[60:61]
	v_cndmask_b32_e64 v12, 0, v42, s[60:61]
	v_pk_fma_f32 v[8:9], v[128:129], v[126:127], v[8:9]
	v_pk_fma_f32 v[12:13], v[12:13], v[98:99], v[118:119]
	v_lshlrev_b32_e32 v98, 16, v104
	v_lshlrev_b32_e32 v118, 16, v105
	v_and_b32_e32 v99, 0xffff0000, v104
	v_and_b32_e32 v119, 0xffff0000, v105
	v_cndmask_b32_e64 v105, 0, v69, s[58:59]
	v_cndmask_b32_e64 v104, 0, v68, s[58:59]
	v_cndmask_b32_e64 v127, 0, v71, s[58:59]
	v_cndmask_b32_e64 v126, 0, v70, s[58:59]
	v_pk_fma_f32 v[12:13], v[126:127], v[118:119], v[12:13]
	v_pk_fma_f32 v[8:9], v[104:105], v[98:99], v[8:9]
	v_lshlrev_b32_e32 v98, 16, v115
	v_lshlrev_b32_e32 v104, 16, v114
	v_and_b32_e32 v99, 0xffff0000, v115
	v_and_b32_e32 v105, 0xffff0000, v114
	v_pk_fma_f32 v[8:9], v[82:83], v[104:105], v[8:9]
	v_pk_fma_f32 v[98:99], v[72:73], v[98:99], v[12:13]
	v_cvt_pk_bf16_f32 v12, v8, v9
	v_cvt_pk_bf16_f32 v13, v98, v99
	ds_write2_b32 v125, v98, v99 offset0:2 offset1:3
	ds_write2_b32 v125, v8, v9 offset1:1
	v_lshlrev_b32_e32 v8, 16, v10
	v_lshlrev_b32_e32 v98, 16, v11
	v_and_b32_e32 v9, 0xffff0000, v10
	v_and_b32_e32 v99, 0xffff0000, v11
	v_cndmask_b32_e64 v11, 0, v25, s[62:63]
	v_cndmask_b32_e64 v10, 0, v24, s[62:63]
	v_cndmask_b32_e64 v105, 0, v27, s[62:63]
	v_cndmask_b32_e64 v104, 0, v26, s[62:63]
	v_pk_fma_f32 v[98:99], v[104:105], v[98:99], v[22:23]
	v_pk_fma_f32 v[8:9], v[10:11], v[8:9], v[20:21]
	v_lshlrev_b32_e32 v10, 16, v15
	v_lshlrev_b32_e32 v104, 16, v14
	v_and_b32_e32 v11, 0xffff0000, v15
	v_and_b32_e32 v105, 0xffff0000, v14
	v_cndmask_b32_e64 v15, 0, v31, s[60:61]
	v_cndmask_b32_e64 v14, 0, v30, s[60:61]
	v_cndmask_b32_e64 v115, 0, v29, s[60:61]
	v_cndmask_b32_e64 v114, 0, v28, s[60:61]
	v_pk_fma_f32 v[8:9], v[114:115], v[104:105], v[8:9]
	v_pk_fma_f32 v[10:11], v[14:15], v[10:11], v[98:99]
	v_lshlrev_b32_e32 v14, 16, v106
	v_lshlrev_b32_e32 v98, 16, v107
	v_and_b32_e32 v15, 0xffff0000, v106
	v_and_b32_e32 v99, 0xffff0000, v107
	v_cndmask_b32_e64 v105, 0, v37, s[58:59]
	v_cndmask_b32_e64 v104, 0, v36, s[58:59]
	v_cndmask_b32_e64 v107, 0, v39, s[58:59]
	v_cndmask_b32_e64 v106, 0, v38, s[58:59]
	v_pk_fma_f32 v[10:11], v[106:107], v[98:99], v[10:11]
	v_pk_fma_f32 v[8:9], v[104:105], v[14:15], v[8:9]
	v_lshlrev_b32_e32 v14, 16, v117
	v_lshlrev_b32_e32 v98, 16, v116
	v_and_b32_e32 v15, 0xffff0000, v117
	v_and_b32_e32 v99, 0xffff0000, v116
	v_add_u32_e32 v114, s40, v139
	v_pk_fma_f32 v[8:9], v[84:85], v[98:99], v[8:9]
	v_pk_fma_f32 v[10:11], v[74:75], v[14:15], v[10:11]
	v_cmp_lt_i32_e64 s[56:57], -1, v114
	v_cvt_pk_bf16_f32 v14, v8, v9
	ds_write2_b32 v125, v10, v11 offset0:6 offset1:7
	ds_write2_b32 v125, v8, v9 offset0:4 offset1:5
	v_cndmask_b32_e64 v8, 0, v114, s[56:57]
	v_max_i32_e32 v98, -1, v114
	v_add_u32_e32 v130, s27, v8
	v_add_u32_e32 v131, s80, v98
	v_cvt_pk_bf16_f32 v15, v10, v11
	v_mov_b32_dpp v8, v230 row_ror:3 row_mask:0xf bank_mask:0xf
	v_mov_b32_dpp v9, v231 row_ror:3 row_mask:0xf bank_mask:0xf
	v_mov_b32_dpp v10, v232 row_ror:3 row_mask:0xf bank_mask:0xf
	v_mov_b32_dpp v11, v233 row_ror:3 row_mask:0xf bank_mask:0xf
	v_mov_b32_dpp v8, v234 row_shr:3 row_mask:0xf bank_mask:0xf
	v_mov_b32_dpp v9, v235 row_shr:3 row_mask:0xf bank_mask:0xf
	v_mov_b32_dpp v10, v236 row_shr:3 row_mask:0xf bank_mask:0xf
	v_mov_b32_dpp v11, v237 row_shr:3 row_mask:0xf bank_mask:0xf
	v_cmp_lt_i32_e64 s[54:55], -2, v114
	v_mov_b32_dpp v104, v230 row_ror:2 row_mask:0xf bank_mask:0xf
; __device__ __forceinline__ void ld8bf(const bf16_t* p, float (&o)[8]) { unpack8(*(const u32x4*)p, o); }
; __device__ __forceinline__ bf16x8 pack_frag(const float (&v)[8]) { return __builtin_bit_cast(bf16x8, pack8(v)); }
; __device__ __forceinline__ void w_lru_m1(const Args& a, int l, unsigned char* ws, const bf16_t* proj, bf16_t* y, LAS unsigned char* wl, int b, int ck_, int h, int lane) {
;     ...
;         for (int tb = 0; tb < 4; ++tb) { const int tok = 16 * tb + lo, t = 64 * ck_ + tok; float s[8];
; #pragma unroll
;             for (int j = 0; j < 8; ++j) s[j] = bs[j];
; #pragma unroll
;             for (int k = 0; k < 4; ++k) { const int tt = t - 3 + k; float x[8];
;                 ld8bf(proj + (size_t)(b * SEQ + (tt >= 0 ? tt : 0)) * NIN + C_LX + ch0, x);
; #pragma unroll
;                 for (int j = 0; j < 8; ++j) s[j] += (tt >= 0 ? w[k][j] : 0.f) * x[j]; }
;             Xf[tb][kk] = pack_frag(s);
; #pragma unroll
;             for (int j = 0; j < 8; ++j) xcf[tok * 65 + 32 * kk + 8 * fq + j] = s[j]; }
	v_mov_b32_dpp v105, v231 row_ror:2 row_mask:0xf bank_mask:0xf
	v_mov_b32_dpp v106, v232 row_ror:2 row_mask:0xf bank_mask:0xf
	v_mov_b32_dpp v107, v233 row_ror:2 row_mask:0xf bank_mask:0xf
	v_mov_b32_dpp v104, v234 row_shr:2 row_mask:0xf bank_mask:0xf
	v_mov_b32_dpp v105, v235 row_shr:2 row_mask:0xf bank_mask:0xf
	v_mov_b32_dpp v106, v236 row_shr:2 row_mask:0xf bank_mask:0xf
	v_mov_b32_dpp v107, v237 row_shr:2 row_mask:0xf bank_mask:0xf
	v_max_i32_e32 v98, -2, v114
	v_add_u32_e32 v132, s81, v98
	v_cmp_lt_i32_e64 s[52:53], -3, v114
	v_mov_b32_dpp v114, v230 row_ror:1 row_mask:0xf bank_mask:0xf
	v_mov_b32_dpp v115, v231 row_ror:1 row_mask:0xf bank_mask:0xf
	v_mov_b32_dpp v116, v232 row_ror:1 row_mask:0xf bank_mask:0xf
	v_mov_b32_dpp v117, v233 row_ror:1 row_mask:0xf bank_mask:0xf
	v_mov_b32_dpp v114, v234 row_shr:1 row_mask:0xf bank_mask:0xf
	v_mov_b32_dpp v115, v235 row_shr:1 row_mask:0xf bank_mask:0xf
	v_mov_b32_dpp v116, v236 row_shr:1 row_mask:0xf bank_mask:0xf
	v_mov_b32_dpp v117, v237 row_shr:1 row_mask:0xf bank_mask:0xf
	v_or_b32_e32 v98, s20, v139
	v_cndmask_b32_e64 v98, 0, v98, s[42:43]
	v_add_u32_e32 v133, s27, v98
	v_mov_b64_e32 v[126:127], v[234:235]
	v_mov_b64_e32 v[128:129], v[236:237]
	v_mov_b32_e32 v98, 0x2080
	v_mad_u32_u24 v141, v136, s76, v98
	v_cndmask_b32_e64 v147, 0, v35, s[56:57]
	v_cndmask_b32_e64 v146, 0, v34, s[56:57]
	v_cndmask_b32_e64 v149, 0, v41, s[54:55]
	v_cndmask_b32_e64 v148, 0, v40, s[54:55]
	v_add_u32_e32 v124, v95, v141
	s_waitcnt vmcnt(0) lgkmcnt(0)
	v_lshlrev_b32_e32 v98, 16, v8
	v_lshlrev_b32_e32 v118, 16, v9
	v_and_b32_e32 v99, 0xffff0000, v8
	v_and_b32_e32 v119, 0xffff0000, v9
	v_cndmask_b32_e64 v9, 0, v33, s[56:57]
	v_cndmask_b32_e64 v8, 0, v32, s[56:57]
	v_pk_fma_f32 v[118:119], v[146:147], v[118:119], v[6:7]
	v_pk_fma_f32 v[8:9], v[8:9], v[98:99], v[4:5]
	v_lshlrev_b32_e32 v98, 16, v105
	v_lshlrev_b32_e32 v146, 16, v104
	v_and_b32_e32 v99, 0xffff0000, v105
	v_and_b32_e32 v147, 0xffff0000, v104
	v_cndmask_b32_e64 v105, 0, v43, s[54:55]
	v_cndmask_b32_e64 v104, 0, v42, s[54:55]
	v_pk_fma_f32 v[8:9], v[148:149], v[146:147], v[8:9]
	v_pk_fma_f32 v[98:99], v[104:105], v[98:99], v[118:119]
	v_lshlrev_b32_e32 v104, 16, v114
	v_lshlrev_b32_e32 v118, 16, v115
	v_and_b32_e32 v105, 0xffff0000, v114
	v_and_b32_e32 v119, 0xffff0000, v115
	v_cndmask_b32_e64 v115, 0, v69, s[52:53]
	v_cndmask_b32_e64 v114, 0, v68, s[52:53]
	v_cndmask_b32_e64 v147, 0, v71, s[52:53]
	v_cndmask_b32_e64 v146, 0, v70, s[52:53]
	v_pk_fma_f32 v[98:99], v[146:147], v[118:119], v[98:99]
	v_pk_fma_f32 v[8:9], v[114:115], v[104:105], v[8:9]
	v_lshlrev_b32_e32 v104, 16, v127
	v_lshlrev_b32_e32 v114, 16, v126
	v_and_b32_e32 v105, 0xffff0000, v127
	v_and_b32_e32 v115, 0xffff0000, v126
	v_pk_fma_f32 v[114:115], v[82:83], v[114:115], v[8:9]
	v_pk_fma_f32 v[98:99], v[72:73], v[104:105], v[98:99]
	v_cvt_pk_bf16_f32 v8, v114, v115
	v_cvt_pk_bf16_f32 v9, v98, v99
	ds_write2_b32 v124, v98, v99 offset0:2 offset1:3
	ds_write2_b32 v124, v114, v115 offset1:1
	v_lshlrev_b32_e32 v98, 16, v10
	v_lshlrev_b32_e32 v104, 16, v11
	v_and_b32_e32 v99, 0xffff0000, v10
	v_and_b32_e32 v105, 0xffff0000, v11
	v_cndmask_b32_e64 v11, 0, v25, s[56:57]
	v_cndmask_b32_e64 v10, 0, v24, s[56:57]
	v_cndmask_b32_e64 v115, 0, v27, s[56:57]
	v_cndmask_b32_e64 v114, 0, v26, s[56:57]
	v_pk_fma_f32 v[104:105], v[114:115], v[104:105], v[22:23]
	v_pk_fma_f32 v[10:11], v[10:11], v[98:99], v[20:21]
	v_lshlrev_b32_e32 v98, 16, v107
	v_lshlrev_b32_e32 v114, 16, v106
	v_and_b32_e32 v99, 0xffff0000, v107
	v_and_b32_e32 v115, 0xffff0000, v106
	v_cndmask_b32_e64 v107, 0, v31, s[54:55]
	v_cndmask_b32_e64 v106, 0, v30, s[54:55]
	v_cndmask_b32_e64 v119, 0, v29, s[54:55]
	v_cndmask_b32_e64 v118, 0, v28, s[54:55]
	v_pk_fma_f32 v[10:11], v[118:119], v[114:115], v[10:11]
	v_pk_fma_f32 v[98:99], v[106:107], v[98:99], v[104:105]
	v_lshlrev_b32_e32 v104, 16, v116
	v_lshlrev_b32_e32 v106, 16, v117
	v_and_b32_e32 v105, 0xffff0000, v116
	v_and_b32_e32 v107, 0xffff0000, v117
	v_cndmask_b32_e64 v115, 0, v37, s[52:53]
	v_cndmask_b32_e64 v114, 0, v36, s[52:53]
	v_cndmask_b32_e64 v117, 0, v39, s[52:53]
	v_cndmask_b32_e64 v116, 0, v38, s[52:53]
	v_pk_fma_f32 v[98:99], v[116:117], v[106:107], v[98:99]
	v_pk_fma_f32 v[10:11], v[114:115], v[104:105], v[10:11]
	v_lshlrev_b32_e32 v104, 16, v129
	v_and_b32_e32 v105, 0xffff0000, v129
	v_add_u32_e32 v118, s40, v137
	v_lshlrev_b32_e32 v106, 16, v128
	v_and_b32_e32 v107, 0xffff0000, v128
	v_pk_fma_f32 v[98:99], v[74:75], v[104:105], v[98:99]
	v_cmp_lt_i32_e64 s[46:47], -1, v118
	v_pk_fma_f32 v[106:107], v[84:85], v[106:107], v[10:11]
	v_cvt_pk_bf16_f32 v11, v98, v99
	ds_write2_b32 v124, v98, v99 offset0:6 offset1:7
	ds_write2_b32 v124, v106, v107 offset0:4 offset1:5
	v_cndmask_b32_e64 v98, 0, v118, s[46:47]
	v_add_u32_e32 v126, s27, v98
	v_cvt_pk_bf16_f32 v10, v106, v107
	v_mov_b32_dpp v104, v234 row_ror:3 row_mask:0xf bank_mask:0xf
	v_mov_b32_dpp v105, v235 row_ror:3 row_mask:0xf bank_mask:0xf
	v_mov_b32_dpp v106, v236 row_ror:3 row_mask:0xf bank_mask:0xf
	v_mov_b32_dpp v107, v237 row_ror:3 row_mask:0xf bank_mask:0xf
	v_mov_b32_dpp v104, v238 row_shr:3 row_mask:0xf bank_mask:0xf
	v_mov_b32_dpp v105, v239 row_shr:3 row_mask:0xf bank_mask:0xf
	v_mov_b32_dpp v106, v240 row_shr:3 row_mask:0xf bank_mask:0xf
	v_mov_b32_dpp v107, v241 row_shr:3 row_mask:0xf bank_mask:0xf
	v_max_i32_e32 v98, -1, v118
	v_add_u32_e32 v127, s80, v98
	v_mov_b32_dpp v114, v234 row_ror:2 row_mask:0xf bank_mask:0xf
	v_mov_b32_dpp v115, v235 row_ror:2 row_mask:0xf bank_mask:0xf
	v_mov_b32_dpp v116, v236 row_ror:2 row_mask:0xf bank_mask:0xf
	v_mov_b32_dpp v117, v237 row_ror:2 row_mask:0xf bank_mask:0xf
; __device__ __forceinline__ void ld8bf(const bf16_t* p, float (&o)[8]) { unpack8(*(const u32x4*)p, o); }
; __device__ __forceinline__ bf16x8 pack_frag(const float (&v)[8]) { return __builtin_bit_cast(bf16x8, pack8(v)); }
; __device__ __forceinline__ void w_lru_m1(const Args& a, int l, unsigned char* ws, const bf16_t* proj, bf16_t* y, LAS unsigned char* wl, int b, int ck_, int h, int lane) {
;     ...
;         for (int tb = 0; tb < 4; ++tb) { const int tok = 16 * tb + lo, t = 64 * ck_ + tok; float s[8];
; #pragma unroll
;             for (int j = 0; j < 8; ++j) s[j] = bs[j];
; #pragma unroll
;             for (int k = 0; k < 4; ++k) { const int tt = t - 3 + k; float x[8];
;                 ld8bf(proj + (size_t)(b * SEQ + (tt >= 0 ? tt : 0)) * NIN + C_LX + ch0, x);
; #pragma unroll
;                 for (int j = 0; j < 8; ++j) s[j] += (tt >= 0 ? w[k][j] : 0.f) * x[j]; }
;             Xf[tb][kk] = pack_frag(s);
; #pragma unroll
;             for (int j = 0; j < 8; ++j) xcf[tok * 65 + 32 * kk + 8 * fq + j] = s[j]; }
	v_mov_b32_dpp v114, v238 row_shr:2 row_mask:0xf bank_mask:0xf
	v_mov_b32_dpp v115, v239 row_shr:2 row_mask:0xf bank_mask:0xf
	v_mov_b32_dpp v116, v240 row_shr:2 row_mask:0xf bank_mask:0xf
	v_mov_b32_dpp v117, v241 row_shr:2 row_mask:0xf bank_mask:0xf
	v_max_i32_e32 v98, -2, v118
	v_add_u32_e32 v128, s81, v98
	v_mov_b32_dpp v146, v234 row_ror:1 row_mask:0xf bank_mask:0xf
	v_mov_b32_dpp v147, v235 row_ror:1 row_mask:0xf bank_mask:0xf
	v_mov_b32_dpp v148, v236 row_ror:1 row_mask:0xf bank_mask:0xf
	v_mov_b32_dpp v149, v237 row_ror:1 row_mask:0xf bank_mask:0xf
	v_mov_b32_dpp v146, v238 row_shr:1 row_mask:0xf bank_mask:0xf
	v_mov_b32_dpp v147, v239 row_shr:1 row_mask:0xf bank_mask:0xf
	v_mov_b32_dpp v148, v240 row_shr:1 row_mask:0xf bank_mask:0xf
	v_mov_b32_dpp v149, v241 row_shr:1 row_mask:0xf bank_mask:0xf
	v_or_b32_e32 v98, s20, v137
	v_cndmask_b32_e64 v98, 0, v98, s[42:43]
	v_add_u32_e32 v129, s27, v98
	v_mov_b64_e32 v[150:151], v[238:239]
	v_mov_b64_e32 v[152:153], v[240:241]
	v_mov_b32_e32 v80, 0x30c0
	v_cmp_lt_i32_e64 s[40:41], -2, v118
	v_mad_u32_u24 v138, v136, s76, v80
	v_cndmask_b32_e64 v33, 0, v33, s[46:47]
	v_cndmask_b32_e64 v32, 0, v32, s[46:47]
	v_cndmask_b32_e64 v35, 0, v35, s[46:47]
	v_cndmask_b32_e64 v34, 0, v34, s[46:47]
	v_cmp_lt_i32_e32 vcc, -3, v118
	v_cndmask_b32_e64 v43, 0, v43, s[40:41]
	v_cndmask_b32_e64 v42, 0, v42, s[40:41]
	v_cndmask_b32_e64 v41, 0, v41, s[40:41]
	v_cndmask_b32_e64 v40, 0, v40, s[40:41]
	v_add_u32_e32 v120, v95, v138
	v_cndmask_b32_e64 v25, 0, v25, s[46:47]
	v_cndmask_b32_e64 v24, 0, v24, s[46:47]
	v_cndmask_b32_e64 v27, 0, v27, s[46:47]
	v_cndmask_b32_e64 v26, 0, v26, s[46:47]
	v_cndmask_b32_e64 v29, 0, v29, s[40:41]
	v_cndmask_b32_e64 v28, 0, v28, s[40:41]
	s_mov_b64 s[80:81], 0x1080
	s_waitcnt vmcnt(0) lgkmcnt(0)
	v_lshlrev_b32_e32 v80, 16, v104
	v_lshlrev_b32_e32 v98, 16, v105
	v_and_b32_e32 v81, 0xffff0000, v104
	v_and_b32_e32 v99, 0xffff0000, v105
	v_pk_fma_f32 v[6:7], v[34:35], v[98:99], v[6:7]
	v_pk_fma_f32 v[4:5], v[32:33], v[80:81], v[4:5]
	v_lshlrev_b32_e32 v32, 16, v115
	v_lshlrev_b32_e32 v34, 16, v114
	v_and_b32_e32 v33, 0xffff0000, v115
	v_and_b32_e32 v35, 0xffff0000, v114
	v_pk_fma_f32 v[4:5], v[40:41], v[34:35], v[4:5]
	v_pk_fma_f32 v[6:7], v[42:43], v[32:33], v[6:7]
	v_lshlrev_b32_e32 v32, 16, v146
	v_lshlrev_b32_e32 v34, 16, v147
	v_and_b32_e32 v33, 0xffff0000, v146
	v_and_b32_e32 v35, 0xffff0000, v147
	v_cndmask_b32_e32 v41, 0, v69, vcc
	v_cndmask_b32_e32 v40, 0, v68, vcc
	v_cndmask_b32_e32 v43, 0, v71, vcc
	v_cndmask_b32_e32 v42, 0, v70, vcc
	v_pk_fma_f32 v[6:7], v[42:43], v[34:35], v[6:7]
	v_pk_fma_f32 v[4:5], v[40:41], v[32:33], v[4:5]
	v_lshlrev_b32_e32 v32, 16, v151
	v_and_b32_e32 v33, 0xffff0000, v151
	v_lshlrev_b32_e32 v34, 16, v150
	v_and_b32_e32 v35, 0xffff0000, v150
	v_pk_fma_f32 v[6:7], v[72:73], v[32:33], v[6:7]
	v_pk_fma_f32 v[34:35], v[82:83], v[34:35], v[4:5]
	v_cvt_pk_bf16_f32 v5, v6, v7
	ds_write2_b32 v120, v6, v7 offset0:2 offset1:3
	ds_write2_b32 v120, v34, v35 offset1:1
	v_lshlrev_b32_e32 v6, 16, v106
	v_lshlrev_b32_e32 v32, 16, v107
	v_and_b32_e32 v7, 0xffff0000, v106
	v_and_b32_e32 v33, 0xffff0000, v107
	v_pk_fma_f32 v[22:23], v[26:27], v[32:33], v[22:23]
	v_pk_fma_f32 v[6:7], v[24:25], v[6:7], v[20:21]
	v_lshlrev_b32_e32 v20, 16, v117
	v_lshlrev_b32_e32 v24, 16, v116
	v_and_b32_e32 v21, 0xffff0000, v117
	v_and_b32_e32 v25, 0xffff0000, v116
	v_cndmask_b32_e64 v27, 0, v31, s[40:41]
	v_cndmask_b32_e64 v26, 0, v30, s[40:41]
	v_pk_fma_f32 v[6:7], v[28:29], v[24:25], v[6:7]
	v_pk_fma_f32 v[20:21], v[26:27], v[20:21], v[22:23]
	v_lshlrev_b32_e32 v22, 16, v148
	v_lshlrev_b32_e32 v24, 16, v149
	v_and_b32_e32 v23, 0xffff0000, v148
	v_and_b32_e32 v25, 0xffff0000, v149
	v_cndmask_b32_e32 v27, 0, v37, vcc
	v_cndmask_b32_e32 v26, 0, v36, vcc
	v_cndmask_b32_e32 v29, 0, v39, vcc
	v_cndmask_b32_e32 v28, 0, v38, vcc
	v_pk_fma_f32 v[20:21], v[28:29], v[24:25], v[20:21]
	v_pk_fma_f32 v[6:7], v[26:27], v[22:23], v[6:7]
	v_lshlrev_b32_e32 v22, 16, v153
	v_and_b32_e32 v23, 0xffff0000, v153
	v_lshlrev_b32_e32 v24, 16, v152
	v_and_b32_e32 v25, 0xffff0000, v152
	v_pk_fma_f32 v[20:21], v[74:75], v[22:23], v[20:21]
	v_pk_fma_f32 v[24:25], v[84:85], v[24:25], v[6:7]
	v_cvt_pk_bf16_f32 v7, v20, v21
	ds_write2_b32 v120, v20, v21 offset0:6 offset1:7
	ds_write2_b32 v120, v24, v25 offset0:4 offset1:5
	v_add_u32_e32 v20, 32, v78
	v_ashrrev_i32_e32 v21, 31, v20
	v_lshl_add_u64 v[84:85], v[86:87], 0, s[80:81]
	s_mov_b64 s[80:81], 0x1880
	v_lshl_add_u64 v[106:107], v[86:87], 0, s[80:81]
	v_lshlrev_b64 v[104:105], 1, v[20:21]
	v_mov_b32_dpp v80, v242 row_ror:3 row_mask:0xf bank_mask:0xf
	v_mov_b32_dpp v81, v243 row_ror:3 row_mask:0xf bank_mask:0xf
	v_mov_b32_dpp v82, v244 row_ror:3 row_mask:0xf bank_mask:0xf
	v_mov_b32_dpp v83, v245 row_ror:3 row_mask:0xf bank_mask:0xf
	v_mov_b32_dpp v80, v246 row_shr:3 row_mask:0xf bank_mask:0xf
	v_mov_b32_dpp v81, v247 row_shr:3 row_mask:0xf bank_mask:0xf
	v_mov_b32_dpp v82, v248 row_shr:3 row_mask:0xf bank_mask:0xf
	v_mov_b32_dpp v83, v249 row_shr:3 row_mask:0xf bank_mask:0xf
	v_cvt_pk_bf16_f32 v4, v34, v35
	v_mov_b32_dpp v32, v242 row_ror:2 row_mask:0xf bank_mask:0xf
	v_mov_b32_dpp v33, v243 row_ror:2 row_mask:0xf bank_mask:0xf
	v_mov_b32_dpp v34, v244 row_ror:2 row_mask:0xf bank_mask:0xf
	v_mov_b32_dpp v35, v245 row_ror:2 row_mask:0xf bank_mask:0xf
	v_mov_b32_dpp v32, v246 row_shr:2 row_mask:0xf bank_mask:0xf
	v_mov_b32_dpp v33, v247 row_shr:2 row_mask:0xf bank_mask:0xf
	v_mov_b32_dpp v34, v248 row_shr:2 row_mask:0xf bank_mask:0xf
	v_mov_b32_dpp v35, v249 row_shr:2 row_mask:0xf bank_mask:0xf
	v_mov_b32_dpp v28, v242 row_ror:1 row_mask:0xf bank_mask:0xf
	v_mov_b32_dpp v29, v243 row_ror:1 row_mask:0xf bank_mask:0xf
	v_mov_b32_dpp v30, v244 row_ror:1 row_mask:0xf bank_mask:0xf
	v_mov_b32_dpp v31, v245 row_ror:1 row_mask:0xf bank_mask:0xf
	v_mov_b32_dpp v28, v246 row_shr:1 row_mask:0xf bank_mask:0xf
	v_mov_b32_dpp v29, v247 row_shr:1 row_mask:0xf bank_mask:0xf
	v_mov_b32_dpp v30, v248 row_shr:1 row_mask:0xf bank_mask:0xf
	v_mov_b32_dpp v31, v249 row_shr:1 row_mask:0xf bank_mask:0xf
	v_cvt_pk_bf16_f32 v6, v24, v25
	v_mov_b64_e32 v[24:25], v[246:247]
	v_mov_b64_e32 v[26:27], v[248:249]
	global_load_dwordx4 v[40:43], v[76:77], off offset:144
	global_load_dwordx4 v[72:75], v[76:77], off offset:128
	global_load_dwordx4 v[68:71], v[86:87], off offset:144
	s_nop 0
	global_load_dwordx4 v[76:79], v[86:87], off offset:128
	global_load_dwordx4 v[36:39], v[86:87], off offset:2192
	global_load_dwordx4 v[20:23], v[86:87], off offset:2176
	global_load_dwordx4 v[92:95], v[96:97], off offset:128
	s_nop 0
	global_load_dwordx4 v[84:87], v[84:85], off offset:16
	s_nop 0
	global_load_dwordx4 v[96:99], v[96:97], off offset:2176
	s_nop 0
	global_load_dwordx4 v[146:149], v[106:107], off offset:16
	s_waitcnt vmcnt(0) lgkmcnt(0)
; __device__ __forceinline__ void ld8bf(const bf16_t* p, float (&o)[8]) { unpack8(*(const u32x4*)p, o); }
; __device__ __forceinline__ bf16x8 pack_frag(const float (&v)[8]) { return __builtin_bit_cast(bf16x8, pack8(v)); }
; __device__ __forceinline__ void w_lru_m1(const Args& a, int l, unsigned char* ws, const bf16_t* proj, bf16_t* y, LAS unsigned char* wl, int b, int ck_, int h, int lane) {
;     ...
;         for (int tb = 0; tb < 4; ++tb) { const int tok = 16 * tb + lo, t = 64 * ck_ + tok; float s[8];
; #pragma unroll
;             for (int j = 0; j < 8; ++j) s[j] = bs[j];
; #pragma unroll
;             for (int k = 0; k < 4; ++k) { const int tt = t - 3 + k; float x[8];
;                 ld8bf(proj + (size_t)(b * SEQ + (tt >= 0 ? tt : 0)) * NIN + C_LX + ch0, x);
; #pragma unroll
;                 for (int j = 0; j < 8; ++j) s[j] += (tt >= 0 ? w[k][j] : 0.f) * x[j]; }
;             Xf[tb][kk] = pack_frag(s);
; #pragma unroll
;             for (int j = 0; j < 8; ++j) xcf[tok * 65 + 32 * kk + 8 * fq + j] = s[j]; }
	v_lshlrev_b32_e32 v106, 16, v80
	v_lshlrev_b32_e32 v114, 16, v81
	v_and_b32_e32 v107, 0xffff0000, v80
	v_and_b32_e32 v115, 0xffff0000, v81
	v_cndmask_b32_e64 v81, 0, v77, s[50:51]
	v_cndmask_b32_e64 v80, 0, v76, s[50:51]
	v_cndmask_b32_e64 v117, 0, v79, s[50:51]
	v_cndmask_b32_e64 v116, 0, v78, s[50:51]
	v_pk_fma_f32 v[114:115], v[116:117], v[114:115], v[74:75]
	v_pk_fma_f32 v[80:81], v[80:81], v[106:107], v[72:73]
	v_lshlrev_b32_e32 v106, 16, v33
	v_lshlrev_b32_e32 v116, 16, v32
	v_and_b32_e32 v107, 0xffff0000, v33
	v_and_b32_e32 v117, 0xffff0000, v32
	v_cndmask_b32_e64 v33, 0, v23, s[48:49]
	v_cndmask_b32_e64 v32, 0, v22, s[48:49]
	v_cndmask_b32_e64 v119, 0, v21, s[48:49]
	v_cndmask_b32_e64 v118, 0, v20, s[48:49]
	v_pk_fma_f32 v[80:81], v[118:119], v[116:117], v[80:81]
	v_pk_fma_f32 v[32:33], v[32:33], v[106:107], v[114:115]
	v_lshlrev_b32_e32 v106, 16, v28
	v_lshlrev_b32_e32 v114, 16, v29
	v_and_b32_e32 v107, 0xffff0000, v28
	v_and_b32_e32 v115, 0xffff0000, v29
	v_cndmask_b32_e64 v29, 0, v93, s[44:45]
	v_cndmask_b32_e64 v28, 0, v92, s[44:45]
	v_cndmask_b32_e64 v117, 0, v95, s[44:45]
	v_cndmask_b32_e64 v116, 0, v94, s[44:45]
	v_pk_fma_f32 v[32:33], v[116:117], v[114:115], v[32:33]
	v_pk_fma_f32 v[28:29], v[28:29], v[106:107], v[80:81]
	v_lshlrev_b32_e32 v80, 16, v25
	v_lshlrev_b32_e32 v116, 16, v24
	v_and_b32_e32 v81, 0xffff0000, v25
	v_and_b32_e32 v117, 0xffff0000, v24
	v_cndmask_b32_e64 v107, 0, v99, s[42:43]
	v_cndmask_b32_e64 v106, 0, v98, s[42:43]
	v_cndmask_b32_e64 v115, 0, v97, s[42:43]
	v_cndmask_b32_e64 v114, 0, v96, s[42:43]
	v_pk_fma_f32 v[24:25], v[114:115], v[116:117], v[28:29]
	v_pk_fma_f32 v[28:29], v[106:107], v[80:81], v[32:33]
	v_cvt_pk_bf16_f32 v32, v24, v25
	v_cvt_pk_bf16_f32 v33, v28, v29
	ds_write2_b32 v121, v28, v29 offset0:34 offset1:35
	ds_write2_b32 v121, v24, v25 offset0:32 offset1:33
	v_lshlrev_b32_e32 v24, 16, v82
	v_lshlrev_b32_e32 v28, 16, v83
	v_and_b32_e32 v25, 0xffff0000, v82
	v_and_b32_e32 v29, 0xffff0000, v83
	v_cndmask_b32_e64 v81, 0, v69, s[50:51]
	v_cndmask_b32_e64 v80, 0, v68, s[50:51]
	v_cndmask_b32_e64 v83, 0, v71, s[50:51]
	v_cndmask_b32_e64 v82, 0, v70, s[50:51]
	v_pk_fma_f32 v[28:29], v[82:83], v[28:29], v[42:43]
	v_pk_fma_f32 v[24:25], v[80:81], v[24:25], v[40:41]
	v_lshlrev_b32_e32 v80, 16, v35
	v_lshlrev_b32_e32 v82, 16, v34
	v_and_b32_e32 v81, 0xffff0000, v35
	v_and_b32_e32 v83, 0xffff0000, v34
	v_cndmask_b32_e64 v35, 0, v39, s[48:49]
	v_cndmask_b32_e64 v34, 0, v38, s[48:49]
	v_cndmask_b32_e64 v97, 0, v37, s[48:49]
	v_cndmask_b32_e64 v96, 0, v36, s[48:49]
	v_pk_fma_f32 v[24:25], v[96:97], v[82:83], v[24:25]
	v_pk_fma_f32 v[28:29], v[34:35], v[80:81], v[28:29]
	v_lshlrev_b32_e32 v34, 16, v30
	v_lshlrev_b32_e32 v80, 16, v31
	v_and_b32_e32 v35, 0xffff0000, v30
	v_and_b32_e32 v81, 0xffff0000, v31
	v_cndmask_b32_e64 v31, 0, v85, s[44:45]
	v_cndmask_b32_e64 v30, 0, v84, s[44:45]
	v_cndmask_b32_e64 v83, 0, v87, s[44:45]
	v_cndmask_b32_e64 v82, 0, v86, s[44:45]
	v_pk_fma_f32 v[28:29], v[82:83], v[80:81], v[28:29]
	v_pk_fma_f32 v[24:25], v[30:31], v[34:35], v[24:25]
	v_lshlrev_b32_e32 v30, 16, v27
	v_lshlrev_b32_e32 v34, 16, v26
	v_and_b32_e32 v31, 0xffff0000, v27
	v_and_b32_e32 v35, 0xffff0000, v26
	v_cndmask_b32_e64 v117, 0, v149, s[42:43]
	v_cndmask_b32_e64 v116, 0, v148, s[42:43]
	v_cndmask_b32_e64 v119, 0, v147, s[42:43]
	v_cndmask_b32_e64 v118, 0, v146, s[42:43]
	v_pk_fma_f32 v[24:25], v[118:119], v[34:35], v[24:25]
	v_pk_fma_f32 v[26:27], v[116:117], v[30:31], v[28:29]
	v_cvt_pk_bf16_f32 v34, v24, v25
	ds_write2_b32 v121, v26, v27 offset0:38 offset1:39
	ds_write2_b32 v121, v24, v25 offset0:36 offset1:37
	v_cvt_pk_bf16_f32 v35, v26, v27
	v_mov_b32_dpp v24, v246 row_ror:3 row_mask:0xf bank_mask:0xf
	v_mov_b32_dpp v25, v247 row_ror:3 row_mask:0xf bank_mask:0xf
	v_mov_b32_dpp v26, v248 row_ror:3 row_mask:0xf bank_mask:0xf
	v_mov_b32_dpp v27, v249 row_ror:3 row_mask:0xf bank_mask:0xf
	v_mov_b32_dpp v24, v250 row_shr:3 row_mask:0xf bank_mask:0xf
	v_mov_b32_dpp v25, v251 row_shr:3 row_mask:0xf bank_mask:0xf
	v_mov_b32_dpp v26, v252 row_shr:3 row_mask:0xf bank_mask:0xf
	v_mov_b32_dpp v27, v253 row_shr:3 row_mask:0xf bank_mask:0xf
	v_mov_b32_dpp v28, v246 row_ror:2 row_mask:0xf bank_mask:0xf
	v_mov_b32_dpp v29, v247 row_ror:2 row_mask:0xf bank_mask:0xf
	v_mov_b32_dpp v30, v248 row_ror:2 row_mask:0xf bank_mask:0xf
	v_mov_b32_dpp v31, v249 row_ror:2 row_mask:0xf bank_mask:0xf
	v_mov_b32_dpp v28, v250 row_shr:2 row_mask:0xf bank_mask:0xf
	v_mov_b32_dpp v29, v251 row_shr:2 row_mask:0xf bank_mask:0xf
	v_mov_b32_dpp v30, v252 row_shr:2 row_mask:0xf bank_mask:0xf
	v_mov_b32_dpp v31, v253 row_shr:2 row_mask:0xf bank_mask:0xf
	v_mov_b32_dpp v80, v246 row_ror:1 row_mask:0xf bank_mask:0xf
	v_mov_b32_dpp v81, v247 row_ror:1 row_mask:0xf bank_mask:0xf
	v_mov_b32_dpp v82, v248 row_ror:1 row_mask:0xf bank_mask:0xf
	v_mov_b32_dpp v83, v249 row_ror:1 row_mask:0xf bank_mask:0xf
	v_mov_b32_dpp v80, v250 row_shr:1 row_mask:0xf bank_mask:0xf
	v_mov_b32_dpp v81, v251 row_shr:1 row_mask:0xf bank_mask:0xf
	v_mov_b32_dpp v82, v252 row_shr:1 row_mask:0xf bank_mask:0xf
	v_mov_b32_dpp v83, v253 row_shr:1 row_mask:0xf bank_mask:0xf
	v_mov_b64_e32 v[96:97], v[250:251]
	v_mov_b64_e32 v[98:99], v[252:253]
	v_cndmask_b32_e64 v147, 0, v79, s[62:63]
	v_cndmask_b32_e64 v146, 0, v78, s[62:63]
	v_cndmask_b32_e64 v149, 0, v21, s[60:61]
	v_cndmask_b32_e64 v148, 0, v20, s[60:61]
	s_add_i32 s48, s20, s27
	s_lshl_b32 s20, s91, 7
	s_add_u32 s44, s10, s20
	s_addc_u32 s45, s11, 0
	s_waitcnt vmcnt(0) lgkmcnt(0)
; __device__ __forceinline__ void ld8bf(const bf16_t* p, float (&o)[8]) { unpack8(*(const u32x4*)p, o); }
; __device__ __forceinline__ bf16x8 pack_frag(const float (&v)[8]) { return __builtin_bit_cast(bf16x8, pack8(v)); }
; __device__ __forceinline__ void w_lru_m1(const Args& a, int l, unsigned char* ws, const bf16_t* proj, bf16_t* y, LAS unsigned char* wl, int b, int ck_, int h, int lane) {
;     ...
;         for (int tb = 0; tb < 4; ++tb) { const int tok = 16 * tb + lo, t = 64 * ck_ + tok; float s[8];
; #pragma unroll
;             for (int j = 0; j < 8; ++j) s[j] = bs[j];
; #pragma unroll
;             for (int k = 0; k < 4; ++k) { const int tt = t - 3 + k; float x[8];
;                 ld8bf(proj + (size_t)(b * SEQ + (tt >= 0 ? tt : 0)) * NIN + C_LX + ch0, x);
; #pragma unroll
;                 for (int j = 0; j < 8; ++j) s[j] += (tt >= 0 ? w[k][j] : 0.f) * x[j]; }
;             Xf[tb][kk] = pack_frag(s);
; #pragma unroll
;             for (int j = 0; j < 8; ++j) xcf[tok * 65 + 32 * kk + 8 * fq + j] = s[j]; }
	v_lshlrev_b32_e32 v134, 16, v24
	v_lshlrev_b32_e32 v142, 16, v25
	v_and_b32_e32 v135, 0xffff0000, v24
	v_and_b32_e32 v143, 0xffff0000, v25
	v_cndmask_b32_e64 v25, 0, v77, s[62:63]
	v_cndmask_b32_e64 v24, 0, v76, s[62:63]
	v_pk_fma_f32 v[142:143], v[146:147], v[142:143], v[74:75]
	v_pk_fma_f32 v[24:25], v[24:25], v[134:135], v[72:73]
	v_lshlrev_b32_e32 v134, 16, v29
	v_lshlrev_b32_e32 v146, 16, v28
	v_and_b32_e32 v135, 0xffff0000, v29
	v_and_b32_e32 v147, 0xffff0000, v28
	v_cndmask_b32_e64 v29, 0, v23, s[60:61]
	v_cndmask_b32_e64 v28, 0, v22, s[60:61]
	v_pk_fma_f32 v[24:25], v[148:149], v[146:147], v[24:25]
	v_pk_fma_f32 v[28:29], v[28:29], v[134:135], v[142:143]
	v_lshlrev_b32_e32 v134, 16, v80
	v_lshlrev_b32_e32 v142, 16, v81
	v_and_b32_e32 v135, 0xffff0000, v80
	v_and_b32_e32 v143, 0xffff0000, v81
	v_cndmask_b32_e64 v81, 0, v93, s[58:59]
	v_cndmask_b32_e64 v80, 0, v92, s[58:59]
	v_cndmask_b32_e64 v147, 0, v95, s[58:59]
	v_cndmask_b32_e64 v146, 0, v94, s[58:59]
	v_pk_fma_f32 v[28:29], v[146:147], v[142:143], v[28:29]
	v_pk_fma_f32 v[24:25], v[80:81], v[134:135], v[24:25]
	v_lshlrev_b32_e32 v80, 16, v97
	v_lshlrev_b32_e32 v134, 16, v96
	v_and_b32_e32 v81, 0xffff0000, v97
	v_and_b32_e32 v135, 0xffff0000, v96
	v_pk_fma_f32 v[24:25], v[114:115], v[134:135], v[24:25]
	v_pk_fma_f32 v[80:81], v[106:107], v[80:81], v[28:29]
	v_cvt_pk_bf16_f32 v28, v24, v25
	v_cvt_pk_bf16_f32 v29, v80, v81
	ds_write2_b32 v125, v80, v81 offset0:34 offset1:35
	ds_write2_b32 v125, v24, v25 offset0:32 offset1:33
	v_lshlrev_b32_e32 v24, 16, v26
	v_lshlrev_b32_e32 v80, 16, v27
	v_and_b32_e32 v25, 0xffff0000, v26
	v_and_b32_e32 v81, 0xffff0000, v27
	v_cndmask_b32_e64 v27, 0, v69, s[62:63]
	v_cndmask_b32_e64 v26, 0, v68, s[62:63]
	v_cndmask_b32_e64 v97, 0, v71, s[62:63]
	v_cndmask_b32_e64 v96, 0, v70, s[62:63]
	v_pk_fma_f32 v[80:81], v[96:97], v[80:81], v[42:43]
	v_pk_fma_f32 v[24:25], v[26:27], v[24:25], v[40:41]
	v_lshlrev_b32_e32 v26, 16, v31
	v_lshlrev_b32_e32 v96, 16, v30
	v_and_b32_e32 v27, 0xffff0000, v31
	v_and_b32_e32 v97, 0xffff0000, v30
	v_cndmask_b32_e64 v31, 0, v39, s[60:61]
	v_cndmask_b32_e64 v30, 0, v38, s[60:61]
	v_cndmask_b32_e64 v135, 0, v37, s[60:61]
	v_cndmask_b32_e64 v134, 0, v36, s[60:61]
	v_pk_fma_f32 v[24:25], v[134:135], v[96:97], v[24:25]
	v_pk_fma_f32 v[26:27], v[30:31], v[26:27], v[80:81]
	v_lshlrev_b32_e32 v30, 16, v82
	v_lshlrev_b32_e32 v80, 16, v83
	v_and_b32_e32 v31, 0xffff0000, v82
	v_and_b32_e32 v81, 0xffff0000, v83
	v_cndmask_b32_e64 v83, 0, v85, s[58:59]
	v_cndmask_b32_e64 v82, 0, v84, s[58:59]
	v_cndmask_b32_e64 v97, 0, v87, s[58:59]
	v_cndmask_b32_e64 v96, 0, v86, s[58:59]
	v_pk_fma_f32 v[26:27], v[96:97], v[80:81], v[26:27]
	v_pk_fma_f32 v[24:25], v[82:83], v[30:31], v[24:25]
	v_lshlrev_b32_e32 v30, 16, v99
	v_lshlrev_b32_e32 v80, 16, v98
	v_and_b32_e32 v31, 0xffff0000, v99
	v_and_b32_e32 v81, 0xffff0000, v98
	v_pk_fma_f32 v[24:25], v[118:119], v[80:81], v[24:25]
	v_pk_fma_f32 v[26:27], v[116:117], v[30:31], v[26:27]
	v_cvt_pk_bf16_f32 v30, v24, v25
	ds_write2_b32 v125, v26, v27 offset0:38 offset1:39
	ds_write2_b32 v125, v24, v25 offset0:36 offset1:37
	v_cvt_pk_bf16_f32 v31, v26, v27
	v_mov_b32_dpp v24, v250 row_ror:3 row_mask:0xf bank_mask:0xf
	v_mov_b32_dpp v25, v251 row_ror:3 row_mask:0xf bank_mask:0xf
	v_mov_b32_dpp v26, v252 row_ror:3 row_mask:0xf bank_mask:0xf
	v_mov_b32_dpp v27, v253 row_ror:3 row_mask:0xf bank_mask:0xf
	v_mov_b32_dpp v24, v190 row_shr:3 row_mask:0xf bank_mask:0xf
	v_mov_b32_dpp v25, v191 row_shr:3 row_mask:0xf bank_mask:0xf
	v_mov_b32_dpp v26, v192 row_shr:3 row_mask:0xf bank_mask:0xf
	v_mov_b32_dpp v27, v193 row_shr:3 row_mask:0xf bank_mask:0xf
	v_mov_b32_dpp v80, v250 row_ror:2 row_mask:0xf bank_mask:0xf
	v_mov_b32_dpp v81, v251 row_ror:2 row_mask:0xf bank_mask:0xf
	v_mov_b32_dpp v82, v252 row_ror:2 row_mask:0xf bank_mask:0xf
	v_mov_b32_dpp v83, v253 row_ror:2 row_mask:0xf bank_mask:0xf
	v_mov_b32_dpp v80, v190 row_shr:2 row_mask:0xf bank_mask:0xf
	v_mov_b32_dpp v81, v191 row_shr:2 row_mask:0xf bank_mask:0xf
	v_mov_b32_dpp v82, v192 row_shr:2 row_mask:0xf bank_mask:0xf
	v_mov_b32_dpp v83, v193 row_shr:2 row_mask:0xf bank_mask:0xf
	v_mov_b32_dpp v96, v250 row_ror:1 row_mask:0xf bank_mask:0xf
	v_mov_b32_dpp v97, v251 row_ror:1 row_mask:0xf bank_mask:0xf
	v_mov_b32_dpp v98, v252 row_ror:1 row_mask:0xf bank_mask:0xf
	v_mov_b32_dpp v99, v253 row_ror:1 row_mask:0xf bank_mask:0xf
	v_mov_b32_dpp v96, v190 row_shr:1 row_mask:0xf bank_mask:0xf
	v_mov_b32_dpp v97, v191 row_shr:1 row_mask:0xf bank_mask:0xf
	v_mov_b32_dpp v98, v192 row_shr:1 row_mask:0xf bank_mask:0xf
	v_mov_b32_dpp v99, v193 row_shr:1 row_mask:0xf bank_mask:0xf
	v_mov_b64_e32 v[130:131], v[190:191]
	v_mov_b64_e32 v[132:133], v[192:193]
	v_cndmask_b32_e64 v147, 0, v79, s[56:57]
	v_cndmask_b32_e64 v146, 0, v78, s[56:57]
	v_cndmask_b32_e64 v149, 0, v21, s[54:55]
	v_cndmask_b32_e64 v148, 0, v20, s[54:55]
	v_cndmask_b32_e64 v79, 0, v79, s[46:47]
	v_cndmask_b32_e64 v78, 0, v78, s[46:47]
	v_cndmask_b32_e64 v21, 0, v21, s[40:41]
	v_cndmask_b32_e64 v20, 0, v20, s[40:41]
	s_waitcnt vmcnt(0) lgkmcnt(0)
; __device__ __forceinline__ void ld8bf(const bf16_t* p, float (&o)[8]) { unpack8(*(const u32x4*)p, o); }
; __device__ __forceinline__ bf16x8 pack_frag(const float (&v)[8]) { return __builtin_bit_cast(bf16x8, pack8(v)); }
; __device__ __forceinline__ void w_lru_m1(const Args& a, int l, unsigned char* ws, const bf16_t* proj, bf16_t* y, LAS unsigned char* wl, int b, int ck_, int h, int lane) {
;     ...
;         for (int tb = 0; tb < 4; ++tb) { const int tok = 16 * tb + lo, t = 64 * ck_ + tok; float s[8];
; #pragma unroll
;             for (int j = 0; j < 8; ++j) s[j] = bs[j];
; #pragma unroll
;             for (int k = 0; k < 4; ++k) { const int tt = t - 3 + k; float x[8];
;                 ld8bf(proj + (size_t)(b * SEQ + (tt >= 0 ? tt : 0)) * NIN + C_LX + ch0, x);
; #pragma unroll
;                 for (int j = 0; j < 8; ++j) s[j] += (tt >= 0 ? w[k][j] : 0.f) * x[j]; }
;             Xf[tb][kk] = pack_frag(s);
; #pragma unroll
;             for (int j = 0; j < 8; ++j) xcf[tok * 65 + 32 * kk + 8 * fq + j] = s[j]; }
	v_lshlrev_b32_e32 v134, 16, v24
	v_lshlrev_b32_e32 v142, 16, v25
	v_and_b32_e32 v135, 0xffff0000, v24
	v_and_b32_e32 v143, 0xffff0000, v25
	v_cndmask_b32_e64 v25, 0, v77, s[56:57]
	v_cndmask_b32_e64 v24, 0, v76, s[56:57]
	v_pk_fma_f32 v[142:143], v[146:147], v[142:143], v[74:75]
	v_pk_fma_f32 v[24:25], v[24:25], v[134:135], v[72:73]
	v_lshlrev_b32_e32 v134, 16, v81
	v_lshlrev_b32_e32 v146, 16, v80
	v_and_b32_e32 v135, 0xffff0000, v81
	v_and_b32_e32 v147, 0xffff0000, v80
	v_cndmask_b32_e64 v81, 0, v23, s[54:55]
	v_cndmask_b32_e64 v80, 0, v22, s[54:55]
	v_pk_fma_f32 v[24:25], v[148:149], v[146:147], v[24:25]
	v_pk_fma_f32 v[80:81], v[80:81], v[134:135], v[142:143]
	v_lshlrev_b32_e32 v134, 16, v96
	v_lshlrev_b32_e32 v142, 16, v97
	v_and_b32_e32 v135, 0xffff0000, v96
	v_and_b32_e32 v143, 0xffff0000, v97
	v_cndmask_b32_e64 v97, 0, v93, s[52:53]
	v_cndmask_b32_e64 v96, 0, v92, s[52:53]
	v_cndmask_b32_e64 v147, 0, v95, s[52:53]
	v_cndmask_b32_e64 v146, 0, v94, s[52:53]
	v_pk_fma_f32 v[80:81], v[146:147], v[142:143], v[80:81]
	v_pk_fma_f32 v[24:25], v[96:97], v[134:135], v[24:25]
	v_lshlrev_b32_e32 v96, 16, v131
	v_lshlrev_b32_e32 v134, 16, v130
	v_and_b32_e32 v97, 0xffff0000, v131
	v_and_b32_e32 v135, 0xffff0000, v130
	v_pk_fma_f32 v[130:131], v[114:115], v[134:135], v[24:25]
	v_pk_fma_f32 v[80:81], v[106:107], v[96:97], v[80:81]
	v_cvt_pk_bf16_f32 v24, v130, v131
	v_cvt_pk_bf16_f32 v25, v80, v81
	ds_write2_b32 v124, v80, v81 offset0:34 offset1:35
	ds_write2_b32 v124, v130, v131 offset0:32 offset1:33
	v_lshlrev_b32_e32 v80, 16, v26
	v_lshlrev_b32_e32 v96, 16, v27
	v_and_b32_e32 v81, 0xffff0000, v26
	v_and_b32_e32 v97, 0xffff0000, v27
	v_cndmask_b32_e64 v27, 0, v69, s[56:57]
	v_cndmask_b32_e64 v26, 0, v68, s[56:57]
	v_cndmask_b32_e64 v131, 0, v71, s[56:57]
	v_cndmask_b32_e64 v130, 0, v70, s[56:57]
	v_pk_fma_f32 v[96:97], v[130:131], v[96:97], v[42:43]
	v_pk_fma_f32 v[26:27], v[26:27], v[80:81], v[40:41]
	v_lshlrev_b32_e32 v80, 16, v83
	v_lshlrev_b32_e32 v130, 16, v82
	v_and_b32_e32 v81, 0xffff0000, v83
	v_and_b32_e32 v131, 0xffff0000, v82
	v_cndmask_b32_e64 v83, 0, v39, s[54:55]
	v_cndmask_b32_e64 v82, 0, v38, s[54:55]
	v_cndmask_b32_e64 v135, 0, v37, s[54:55]
	v_cndmask_b32_e64 v134, 0, v36, s[54:55]
	v_pk_fma_f32 v[26:27], v[134:135], v[130:131], v[26:27]
	v_pk_fma_f32 v[80:81], v[82:83], v[80:81], v[96:97]
	v_lshlrev_b32_e32 v82, 16, v98
	v_lshlrev_b32_e32 v96, 16, v99
	v_and_b32_e32 v83, 0xffff0000, v98
	v_and_b32_e32 v97, 0xffff0000, v99
	v_cndmask_b32_e64 v99, 0, v85, s[52:53]
	v_cndmask_b32_e64 v98, 0, v84, s[52:53]
	v_cndmask_b32_e64 v131, 0, v87, s[52:53]
	v_cndmask_b32_e64 v130, 0, v86, s[52:53]
	v_pk_fma_f32 v[80:81], v[130:131], v[96:97], v[80:81]
	v_pk_fma_f32 v[26:27], v[98:99], v[82:83], v[26:27]
	v_lshlrev_b32_e32 v82, 16, v133
	v_and_b32_e32 v83, 0xffff0000, v133
	v_lshlrev_b32_e32 v96, 16, v132
	v_and_b32_e32 v97, 0xffff0000, v132
	v_pk_fma_f32 v[80:81], v[116:117], v[82:83], v[80:81]
	v_pk_fma_f32 v[96:97], v[118:119], v[96:97], v[26:27]
	v_cvt_pk_bf16_f32 v27, v80, v81
	ds_write2_b32 v124, v80, v81 offset0:38 offset1:39
	ds_write2_b32 v124, v96, v97 offset0:36 offset1:37
	v_mov_b32_dpp v130, v190 row_ror:3 row_mask:0xf bank_mask:0xf
	v_mov_b32_dpp v131, v191 row_ror:3 row_mask:0xf bank_mask:0xf
	v_mov_b32_dpp v132, v192 row_ror:3 row_mask:0xf bank_mask:0xf
	v_mov_b32_dpp v133, v193 row_ror:3 row_mask:0xf bank_mask:0xf
	v_mov_b32_dpp v130, v194 row_shr:3 row_mask:0xf bank_mask:0xf
	v_mov_b32_dpp v131, v195 row_shr:3 row_mask:0xf bank_mask:0xf
	v_mov_b32_dpp v132, v196 row_shr:3 row_mask:0xf bank_mask:0xf
	v_mov_b32_dpp v133, v197 row_shr:3 row_mask:0xf bank_mask:0xf
	v_mov_b32_dpp v124, v190 row_ror:2 row_mask:0xf bank_mask:0xf
	v_mov_b32_dpp v125, v191 row_ror:2 row_mask:0xf bank_mask:0xf
	v_mov_b32_dpp v126, v192 row_ror:2 row_mask:0xf bank_mask:0xf
	v_mov_b32_dpp v127, v193 row_ror:2 row_mask:0xf bank_mask:0xf
	v_mov_b32_dpp v124, v194 row_shr:2 row_mask:0xf bank_mask:0xf
	v_mov_b32_dpp v125, v195 row_shr:2 row_mask:0xf bank_mask:0xf
	v_mov_b32_dpp v126, v196 row_shr:2 row_mask:0xf bank_mask:0xf
	v_mov_b32_dpp v127, v197 row_shr:2 row_mask:0xf bank_mask:0xf
	v_cvt_pk_bf16_f32 v26, v96, v97
	v_mov_b32_dpp v96, v190 row_ror:1 row_mask:0xf bank_mask:0xf
	v_mov_b32_dpp v97, v191 row_ror:1 row_mask:0xf bank_mask:0xf
	v_mov_b32_dpp v98, v192 row_ror:1 row_mask:0xf bank_mask:0xf
	v_mov_b32_dpp v99, v193 row_ror:1 row_mask:0xf bank_mask:0xf
	v_mov_b32_dpp v96, v194 row_shr:1 row_mask:0xf bank_mask:0xf
	v_mov_b32_dpp v97, v195 row_shr:1 row_mask:0xf bank_mask:0xf
	v_mov_b32_dpp v98, v196 row_shr:1 row_mask:0xf bank_mask:0xf
	v_mov_b32_dpp v99, v197 row_shr:1 row_mask:0xf bank_mask:0xf
	v_mov_b64_e32 v[80:81], v[194:195]
	v_mov_b64_e32 v[82:83], v[196:197]
	v_cndmask_b32_e64 v77, 0, v77, s[46:47]
	v_cndmask_b32_e64 v76, 0, v76, s[46:47]
	v_cndmask_b32_e64 v23, 0, v23, s[40:41]
	v_cndmask_b32_e64 v22, 0, v22, s[40:41]
	v_cndmask_b32_e64 v69, 0, v69, s[46:47]
	v_cndmask_b32_e64 v68, 0, v68, s[46:47]
	v_cndmask_b32_e64 v71, 0, v71, s[46:47]
	v_cndmask_b32_e64 v70, 0, v70, s[46:47]
	v_cndmask_b32_e64 v39, 0, v39, s[40:41]
	v_cndmask_b32_e64 v38, 0, v38, s[40:41]
	v_cndmask_b32_e64 v37, 0, v37, s[40:41]
	v_cndmask_b32_e64 v36, 0, v36, s[40:41]
	s_add_u32 s46, s71, s20
	s_addc_u32 s47, s64, 0
	s_ashr_i32 s91, s90, 31
	s_lshl_b64 s[42:43], s[90:91], 9
	s_or_b32 s42, s42, s21
	s_waitcnt vmcnt(0) lgkmcnt(0)
; __device__ __forceinline__ float sigmoidf_(float x) { return __builtin_amdgcn_rcpf(1.0f + __expf(-x)); }
; __device__ __forceinline__ bf16x8 pack_frag(const float (&v)[8]) { return __builtin_bit_cast(bf16x8, pack8(v)); }
; __device__ __forceinline__ void w_lru_m1(const Args& a, int l, unsigned char* ws, const bf16_t* proj, bf16_t* y, LAS unsigned char* wl, int b, int ck_, int h, int lane) {
;     ...
;                 for (int j = 0; j < 8; ++j) s[j] += (tt >= 0 ? w[k][j] : 0.f) * x[j]; }
;             Xf[tb][kk] = pack_frag(s);
; #pragma unroll
;             for (int j = 0; j < 8; ++j) xcf[tok * 65 + 32 * kk + 8 * fq + j] = s[j]; }
;     ...
;     for (int jb = 0; jb < 4; ++jb) {
;         bf16x8 WaF[2], WxF[2]; f32x4 pba, pbx, plam;
; #pragma unroll
;         for (int kk = 0; kk < 2; ++kk) { WaF[kk] = nWa[kk]; WxF[kk] = nWx[kk]; }
;         pba = nba; pbx = nbx; plam = nlam;
;         if (jb < 3) {
; #pragma unroll
;             for (int kk = 0; kk < 2; ++kk) { nWa[kk] = *(const bf16x8*)(waT + (16 * (jb + 1) + lo) * 64 + 32 * kk + 8 * fq); nWx[kk] = *(const bf16x8*)(wxT + (16 * (jb + 1) + lo) * 64 + 32 * kk + 8 * fq); }
;             nba = *(const f32x4*)(ba + 16 * (jb + 1) + 4 * fq); nbx = *(const f32x4*)(bx + 16 * (jb + 1) + 4 * fq); nlam = *(const f32x4*)(lam + 16 * (jb + 1) + 4 * fq);
;         }
;         const int j0 = 16 * jb + 4 * fq;
;         float bav[4], bxv[4], sp[4], hc[4], Pc[4];
; #pragma unroll
;         for (int r = 0; r < 4; ++r) { bav[r] = pba[r]; bxv[r] = pbx[r]; sp[r] = log1pf(__expf(-plam[r])); hc[r] = 0.f; Pc[r] = 1.f; }
; #pragma unroll
;         for (int tb = 0; tb < 4; ++tb) { const int tok = 16 * tb + lo;
;             f32x4 ga = {0.f, 0.f, 0.f, 0.f}, gx = {0.f, 0.f, 0.f, 0.f};
; #pragma unroll
;             for (int kk = 0; kk < 2; ++kk) { ga = __builtin_amdgcn_mfma_f32_16x16x32_bf16(WaF[kk], Xf[tb][kk], ga, 0, 0, 0); gx = __builtin_amdgcn_mfma_f32_16x16x32_bf16(WxF[kk], Xf[tb][kk], gx, 0, 0, 0); }
;             float hv[4], pv[4];
; #pragma unroll
;             for (int r = 0; r < 4; ++r) {
;                 const float rg = sigmoidf_(ga[r] + bav[r]), ig = sigmoidf_(gx[r] + bxv[r]);
;                 const float la = -8.0f * rg * sp[r]; float A = __expf(la);
;                 float U = __builtin_amdgcn_sqrtf(1.0f - A * A) * (ig * xcf[tok * 65 + j0 + r]);
	v_lshlrev_b32_e32 v102, 16, v130
	v_lshlrev_b32_e32 v104, 16, v131
	v_and_b32_e32 v103, 0xffff0000, v130
	v_and_b32_e32 v105, 0xffff0000, v131
	v_pk_fma_f32 v[74:75], v[78:79], v[104:105], v[74:75]
	v_pk_fma_f32 v[72:73], v[76:77], v[102:103], v[72:73]
	v_lshlrev_b32_e32 v76, 16, v125
	v_lshlrev_b32_e32 v78, 16, v124
	v_and_b32_e32 v77, 0xffff0000, v125
	v_and_b32_e32 v79, 0xffff0000, v124
	v_pk_fma_f32 v[20:21], v[20:21], v[78:79], v[72:73]
	v_pk_fma_f32 v[22:23], v[22:23], v[76:77], v[74:75]
	v_lshlrev_b32_e32 v72, 16, v96
	v_lshlrev_b32_e32 v74, 16, v97
	v_and_b32_e32 v73, 0xffff0000, v96
	v_and_b32_e32 v75, 0xffff0000, v97
	v_cndmask_b32_e32 v77, 0, v93, vcc
	v_cndmask_b32_e32 v76, 0, v92, vcc
	v_cndmask_b32_e32 v79, 0, v95, vcc
	v_cndmask_b32_e32 v78, 0, v94, vcc
	v_pk_fma_f32 v[22:23], v[78:79], v[74:75], v[22:23]
	v_pk_fma_f32 v[20:21], v[76:77], v[72:73], v[20:21]
	v_lshlrev_b32_e32 v72, 16, v81
	v_and_b32_e32 v73, 0xffff0000, v81
	v_lshlrev_b32_e32 v74, 16, v80
	v_and_b32_e32 v75, 0xffff0000, v80
	v_pk_fma_f32 v[22:23], v[106:107], v[72:73], v[22:23]
	v_pk_fma_f32 v[74:75], v[114:115], v[74:75], v[20:21]
	v_cvt_pk_bf16_f32 v21, v22, v23
	ds_write2_b32 v120, v22, v23 offset0:34 offset1:35
	ds_write2_b32 v120, v74, v75 offset0:32 offset1:33
	v_lshlrev_b32_e32 v22, 16, v132
	v_lshlrev_b32_e32 v72, 16, v133
	v_and_b32_e32 v23, 0xffff0000, v132
	v_and_b32_e32 v73, 0xffff0000, v133
	v_pk_fma_f32 v[42:43], v[70:71], v[72:73], v[42:43]
	v_pk_fma_f32 v[22:23], v[68:69], v[22:23], v[40:41]
	v_lshlrev_b32_e32 v40, 16, v127
	v_lshlrev_b32_e32 v68, 16, v126
	v_and_b32_e32 v41, 0xffff0000, v127
	v_and_b32_e32 v69, 0xffff0000, v126
	v_pk_fma_f32 v[22:23], v[36:37], v[68:69], v[22:23]
	v_pk_fma_f32 v[36:37], v[38:39], v[40:41], v[42:43]
	v_lshlrev_b32_e32 v38, 16, v98
	v_lshlrev_b32_e32 v40, 16, v99
	v_and_b32_e32 v39, 0xffff0000, v98
	v_and_b32_e32 v41, 0xffff0000, v99
	v_cndmask_b32_e32 v43, 0, v85, vcc
	v_cndmask_b32_e32 v42, 0, v84, vcc
	v_cndmask_b32_e32 v69, 0, v87, vcc
	v_cndmask_b32_e32 v68, 0, v86, vcc
	v_pk_fma_f32 v[36:37], v[68:69], v[40:41], v[36:37]
	v_pk_fma_f32 v[22:23], v[42:43], v[38:39], v[22:23]
	v_lshlrev_b32_e32 v38, 16, v83
	v_and_b32_e32 v39, 0xffff0000, v83
	v_lshlrev_b32_e32 v40, 16, v82
	v_and_b32_e32 v41, 0xffff0000, v82
	v_pk_fma_f32 v[36:37], v[116:117], v[38:39], v[36:37]
	v_pk_fma_f32 v[40:41], v[118:119], v[40:41], v[22:23]
	v_cvt_pk_bf16_f32 v23, v36, v37
	ds_write2_b32 v120, v36, v37 offset0:38 offset1:39
	ds_write2_b32 v120, v40, v41 offset0:36 offset1:37
	v_lshlrev_b32_e32 v36, 2, v122
	v_lshl_add_u64 v[118:119], s[92:93], 0, v[100:101]
	v_lshl_add_u64 v[120:121], s[34:35], 0, v[100:101]
	v_and_b32_e32 v143, 0xc0, v36
	v_lshl_add_u64 v[36:37], v[118:119], 0, v[2:3]
	v_lshl_add_u64 v[38:39], v[120:121], 0, v[2:3]
	s_nop 7
	s_waitcnt lgkmcnt(0)
	v_cvt_pk_bf16_f32 v20, v74, v75
	v_cvt_pk_bf16_f32 v22, v40, v41
	s_nop 7
	global_load_dwordx4 v[68:71], v[36:37], off offset:2048
	global_load_dwordx4 v[72:75], v[38:39], off offset:2048
	global_load_dwordx4 v[76:79], v[36:37], off offset:2112
	global_load_dwordx4 v[80:83], v[38:39], off offset:2112
	global_load_dwordx4 v[40:43], v[108:109], off offset:64
	s_nop 0
	global_load_dwordx4 v[36:39], v[110:111], off offset:64
	global_load_dwordx4 v[84:87], v[112:113], off offset:64
	s_nop 7
	v_mov_b32_e32 v104, 1.0
	s_nop 7
	v_mov_b32_e32 v105, 1.0
	s_nop 7
	v_cmp_eq_u32_e32 vcc, 0, v136
	s_nop 0
	s_nop 7
	s_nop 1
	s_nop 7
	s_nop 1
	s_nop 7
	v_mov_b32_e32 v145, v88
	s_nop 7
	s_nop 0
	s_nop 7
	s_nop 0
	s_nop 7
	s_nop 0
	s_nop 7
	s_nop 0
	s_nop 7
	s_nop 0
	s_nop 7
	s_nop 0
	s_nop 7
	s_nop 1
	s_nop 7
	s_nop 1
	s_nop 7
	s_nop 1
	s_nop 7
	v_mov_b32_e32 v147, v89
	s_nop 7
	s_nop 0
	s_nop 7
	s_nop 0
	s_nop 7
	v_mov_b32_e32 v103, 1.0
	s_nop 7
	s_nop 0
	s_nop 7
	s_nop 1
	s_nop 7
	s_nop 1
	s_nop 7
	s_nop 1
	s_nop 7
	v_mov_b32_e32 v2, v90
	s_nop 7
	s_nop 0
	s_nop 7
	s_nop 0
	s_nop 7
	s_nop 0
	s_nop 7
	s_nop 0
	s_nop 7
	v_mov_b32_e32 v100, 1.0
	s_nop 7
	v_mov_b32_e32 v101, 1.0
	s_nop 7
	v_mfma_f32_16x16x32_bf16 v[92:95], v[56:59], v[16:19], 0
	v_mov_b32_e32 v98, 1.0
	s_nop 7
	v_mfma_f32_16x16x32_bf16 v[92:95], v[64:67], v[32:35], v[92:95]
	v_mov_b32_e32 v99, 1.0
	s_nop 7
	s_nop 1
	s_nop 7
	v_mov_b32_e32 v146, v91
	v_and_b32_e32 v88, -16, v122
	v_add_u32_e32 v142, s6, v88
	v_lshlrev_b64 v[88:89], 1, v[0:1]
	v_lshl_add_u64 v[114:115], s[44:45], 0, v[88:89]
	v_lshl_add_u64 v[116:117], s[46:47], 0, v[88:89]
	v_mfma_f32_16x16x32_bf16 v[88:91], v[52:55], v[16:19], 0
	v_mad_u32_u24 v122, v136, s76, v142
	ds_read2_b32 v[124:125], v122 offset1:1
	ds_read2_b32 v[128:129], v122 offset0:2 offset1:3
	v_mfma_f32_16x16x32_bf16 v[88:91], v[60:63], v[32:35], v[88:91]
	v_mov_b32_e32 v102, 1.0
	v_add_u32_e32 v148, v142, v123
	v_add_u32_e32 v150, v142, v141
	s_nop 4
	v_add_f32_e32 v88, v48, v88
	v_add_f32_e32 v89, v49, v89
	v_mul_f32_e32 v88, 0xbfb8aa3b, v88
	v_mul_f32_e32 v89, 0xbfb8aa3b, v89
	v_exp_f32_e32 v88, v88
	v_exp_f32_e32 v89, v89
	v_add_f32_e32 v90, v50, v90
	v_mul_f32_e32 v90, 0xbfb8aa3b, v90
	v_add_f32_e32 v88, 1.0, v88
	v_add_f32_e32 v89, 1.0, v89
	v_rcp_f32_e32 v96, v88
	v_rcp_f32_e32 v97, v89
	v_add_f32_e32 v88, v44, v92
	v_add_f32_e32 v89, v45, v93
	v_mul_f32_e32 v92, 0xc1000000, v96
	v_mul_f32_e32 v93, 0xc1000000, v97
	v_mul_f32_e32 v88, 0xbfb8aa3b, v88
	v_mul_f32_e32 v92, v145, v92
	v_mul_f32_e32 v89, 0xbfb8aa3b, v89
	v_mul_f32_e32 v93, v147, v93
	v_exp_f32_e32 v88, v88
	v_mul_f32_e32 v92, 0x3fb8aa3b, v92
	v_exp_f32_e32 v89, v89
	v_mul_f32_e32 v93, 0x3fb8aa3b, v93
	v_exp_f32_e32 v92, v92
	v_exp_f32_e32 v93, v93
	v_add_f32_e32 v88, 1.0, v88
	v_add_f32_e32 v89, 1.0, v89
	v_rcp_f32_e32 v88, v88
	v_fma_f32 v96, -v92, v92, 1.0
	v_rcp_f32_e32 v89, v89
	v_fma_f32 v97, -v93, v93, 1.0
	v_sqrt_f32_e32 v96, v96
	v_sqrt_f32_e32 v97, v97
	s_waitcnt lgkmcnt(0)
; __device__ __forceinline__ unsigned pk2(float lo, float hi) { const f32x2_t v = {lo, hi}; const bf16x2_t b = __builtin_convertvector(v, bf16x2_t); return __builtin_bit_cast(unsigned, b); }
; __device__ __forceinline__ float sigmoidf_(float x) { return __builtin_amdgcn_rcpf(1.0f + __expf(-x)); }
; __device__ __forceinline__ float bcast15(float v, int lane) { return bperm_f((lane & 48) | 15, v); }
; __device__ __forceinline__ void w_lru_m1(const Args& a, int l, unsigned char* ws, const bf16_t* proj, bf16_t* y, LAS unsigned char* wl, int b, int ck_, int h, int lane) {
;     ...
;         for (int tb = 0; tb < 4; ++tb) { const int tok = 16 * tb + lo;
;             f32x4 ga = {0.f, 0.f, 0.f, 0.f}, gx = {0.f, 0.f, 0.f, 0.f};
; #pragma unroll
;             for (int kk = 0; kk < 2; ++kk) { ga = __builtin_amdgcn_mfma_f32_16x16x32_bf16(WaF[kk], Xf[tb][kk], ga, 0, 0, 0); gx = __builtin_amdgcn_mfma_f32_16x16x32_bf16(WxF[kk], Xf[tb][kk], gx, 0, 0, 0); }
;             float hv[4], pv[4];
; #pragma unroll
;             for (int r = 0; r < 4; ++r) {
;                 const float rg = sigmoidf_(ga[r] + bav[r]), ig = sigmoidf_(gx[r] + bxv[r]);
;                 const float la = -8.0f * rg * sp[r]; float A = __expf(la);
;                 float U = __builtin_amdgcn_sqrtf(1.0f - A * A) * (ig * xcf[tok * 65 + j0 + r]);
;                 { const float As = dpp_shr1<1>(A), Us = dpp_shr0<1>(U); U = A * Us + U; A = A * As; }
;                 { const float As = dpp_shr1<2>(A), Us = dpp_shr0<2>(U); U = A * Us + U; A = A * As; }
;                 { const float As = dpp_shr1<4>(A), Us = dpp_shr0<4>(U); U = A * Us + U; A = A * As; }
;                 { const float As = dpp_shr1<8>(A), Us = dpp_shr0<8>(U); U = A * Us + U; A = A * As; }
;                 const float hh = U + A * hc[r], PP = A * Pc[r];
;                 hc[r] = bcast15(hh, lane); Pc[r] = bcast15(PP, lane); hv[r] = hh; pv[r] = PP; }
;             *(unsigned long long*)(y + (size_t)(row0 + tok) * DM + 64 * h + j0) = (unsigned long long)pk2(hv[0], hv[1]) | ((unsigned long long)pk2(hv[2], hv[3]) << 32);
;             *(unsigned long long*)((bf16_t*)(ws + WS_P) + (size_t)(row0 + tok) * 512 + 64 * h + j0) = (unsigned long long)pk2(pv[0], pv[1]) | ((unsigned long long)pk2(pv[2], pv[3]) << 32);
	v_pk_mul_f32 v[88:89], v[124:125], v[88:89]
	v_mov_b32_dpp v98, v92 row_shr:1 row_mask:0xf bank_mask:0xf
	v_mov_b32_dpp v99, v93 row_shr:1 row_mask:0xf bank_mask:0xf
	v_pk_mul_f32 v[88:89], v[88:89], v[96:97]
	v_pk_mul_f32 v[98:99], v[92:93], v[98:99]
	v_exp_f32_e32 v90, v90
	v_mov_b32_dpp v96, v88 row_shr:1 row_mask:0xf bank_mask:0xf bound_ctrl:1
	v_mov_b32_dpp v97, v89 row_shr:1 row_mask:0xf bank_mask:0xf bound_ctrl:1
	v_pk_fma_f32 v[88:89], v[92:93], v[96:97], v[88:89]
	v_mov_b32_dpp v100, v98 row_shr:2 row_mask:0xf bank_mask:0xf
	v_mov_b32_dpp v101, v99 row_shr:2 row_mask:0xf bank_mask:0xf
	v_mov_b32_dpp v92, v88 row_shr:2 row_mask:0xf bank_mask:0xf bound_ctrl:1
	v_mov_b32_dpp v93, v89 row_shr:2 row_mask:0xf bank_mask:0xf bound_ctrl:1
	v_pk_fma_f32 v[88:89], v[98:99], v[92:93], v[88:89]
	v_pk_mul_f32 v[100:101], v[98:99], v[100:101]
	v_add_f32_e32 v90, 1.0, v90
	v_mov_b32_dpp v92, v88 row_shr:4 row_mask:0xf bank_mask:0xf bound_ctrl:1
	v_mov_b32_dpp v93, v89 row_shr:4 row_mask:0xf bank_mask:0xf bound_ctrl:1
	v_mov_b32_dpp v102, v100 row_shr:4 row_mask:0xf bank_mask:0xf
	v_mov_b32_dpp v103, v101 row_shr:4 row_mask:0xf bank_mask:0xf
	v_pk_fma_f32 v[88:89], v[100:101], v[92:93], v[88:89]
	v_pk_mul_f32 v[102:103], v[100:101], v[102:103]
	v_add_f32_e32 v91, v51, v91
	v_mov_b32_dpp v92, v88 row_shr:8 row_mask:0xf bank_mask:0xf bound_ctrl:1
	v_mov_b32_dpp v93, v89 row_shr:8 row_mask:0xf bank_mask:0xf bound_ctrl:1
	v_pk_fma_f32 v[88:89], v[102:103], v[92:93], v[88:89]
	v_rcp_f32_e32 v92, v90
	v_mul_f32_e32 v91, 0xbfb8aa3b, v91
	v_exp_f32_e32 v91, v91
	v_add_f32_e32 v90, v46, v94
	v_mul_f32_e32 v92, 0xc1000000, v92
	v_mul_f32_e32 v92, v2, v92
	v_mul_f32_e32 v92, 0x3fb8aa3b, v92
	v_exp_f32_e32 v92, v92
	v_add_f32_e32 v91, 1.0, v91
	v_mul_f32_e32 v90, 0xbfb8aa3b, v90
	v_exp_f32_e32 v90, v90
	v_fma_f32 v93, -v92, v92, 1.0
	v_sqrt_f32_e32 v94, v93
	v_rcp_f32_e32 v93, v91
	v_add_f32_e32 v91, v47, v95
	v_mul_f32_e32 v91, 0xbfb8aa3b, v91
	v_exp_f32_e32 v91, v91
	v_mul_f32_e32 v93, 0xc1000000, v93
	v_mul_f32_e32 v93, v146, v93
	v_mul_f32_e32 v93, 0x3fb8aa3b, v93
	v_exp_f32_e32 v93, v93
	v_add_f32_e32 v90, 1.0, v90
	v_add_f32_e32 v91, 1.0, v91
	v_rcp_f32_e32 v90, v90
	v_rcp_f32_e32 v91, v91
	v_fma_f32 v95, -v93, v93, 1.0
	v_sqrt_f32_e32 v95, v95
	v_mov_b32_e32 v96, 1.0
	v_pk_mul_f32 v[90:91], v[90:91], v[128:129]
	v_mov_b32_e32 v97, 1.0
	v_pk_mul_f32 v[90:91], v[94:95], v[90:91]
	v_mov_b32_dpp v96, v92 row_shr:1 row_mask:0xf bank_mask:0xf
	v_mov_b32_dpp v97, v93 row_shr:1 row_mask:0xf bank_mask:0xf
	v_mov_b32_dpp v94, v90 row_shr:1 row_mask:0xf bank_mask:0xf bound_ctrl:1
	v_mov_b32_dpp v95, v91 row_shr:1 row_mask:0xf bank_mask:0xf bound_ctrl:1
	v_pk_mul_f32 v[96:97], v[92:93], v[96:97]
	v_mov_b32_e32 v100, 1.0
	v_mov_b32_e32 v101, 1.0
	v_pk_fma_f32 v[90:91], v[92:93], v[94:95], v[90:91]
	v_mov_b32_dpp v104, v102 row_shr:8 row_mask:0xf bank_mask:0xf
	v_mov_b32_dpp v105, v103 row_shr:8 row_mask:0xf bank_mask:0xf
	v_mov_b32_dpp v100, v96 row_shr:2 row_mask:0xf bank_mask:0xf
	v_mov_b32_dpp v101, v97 row_shr:2 row_mask:0xf bank_mask:0xf
	v_mov_b32_dpp v92, v90 row_shr:2 row_mask:0xf bank_mask:0xf bound_ctrl:1
	v_mov_b32_dpp v93, v91 row_shr:2 row_mask:0xf bank_mask:0xf bound_ctrl:1
	v_pk_mul_f32 v[106:107], v[102:103], v[104:105]
	v_pk_mul_f32 v[100:101], v[96:97], v[100:101]
	v_mov_b32_e32 v102, 1.0
	v_mov_b32_e32 v103, 1.0
	v_pk_fma_f32 v[90:91], v[96:97], v[92:93], v[90:91]
	v_mov_b32_dpp v102, v100 row_shr:4 row_mask:0xf bank_mask:0xf
	v_mov_b32_dpp v103, v101 row_shr:4 row_mask:0xf bank_mask:0xf
	v_mov_b32_dpp v92, v90 row_shr:4 row_mask:0xf bank_mask:0xf bound_ctrl:1
	v_mov_b32_dpp v93, v91 row_shr:4 row_mask:0xf bank_mask:0xf bound_ctrl:1
	v_pk_mul_f32 v[102:103], v[100:101], v[102:103]
	v_mov_b32_e32 v124, 1.0
	v_mov_b32_e32 v125, 1.0
	v_pk_fma_f32 v[90:91], v[100:101], v[92:93], v[90:91]
	v_mov_b32_dpp v124, v102 row_shr:8 row_mask:0xf bank_mask:0xf
	v_mov_b32_dpp v125, v103 row_shr:8 row_mask:0xf bank_mask:0xf
	v_mov_b32_dpp v92, v90 row_shr:8 row_mask:0xf bank_mask:0xf bound_ctrl:1
	v_mov_b32_dpp v93, v91 row_shr:8 row_mask:0xf bank_mask:0xf bound_ctrl:1
	v_pk_mul_f32 v[126:127], v[102:103], v[124:125]
	v_pk_fma_f32 v[90:91], v[102:103], v[92:93], v[90:91]
	v_pk_fma_f32 v[88:89], v[106:107], 0, v[88:89] op_sel_hi:[1,0,1]
	v_pk_fma_f32 v[90:91], v[126:127], 0, v[90:91] op_sel_hi:[1,0,1]
	ds_bpermute_b32 v98, v143, v88 offset:60
	ds_bpermute_b32 v99, v143, v89 offset:60
	ds_bpermute_b32 v96, v143, v90 offset:60
	v_cvt_pk_bf16_f32 v88, v88, v89
	v_cvt_pk_bf16_f32 v89, v90, v91
	v_or_b32_e32 v90, s48, v136
	ds_bpermute_b32 v97, v143, v91 offset:60
	v_ashrrev_i32_e32 v91, 31, v90
	v_lshlrev_b64 v[92:93], 11, v[90:91]
	v_lshl_add_u64 v[100:101], v[114:115], 0, v[92:93]
	v_lshlrev_b64 v[90:91], 10, v[90:91]
	global_store_dwordx2 v[100:101], v[88:89], off
	v_cvt_pk_bf16_f32 v88, v106, v107
	v_cvt_pk_bf16_f32 v89, v126, v127
	v_lshl_add_u64 v[102:103], v[116:117], 0, v[90:91]
	global_store_dwordx2 v[102:103], v[88:89], off
	v_mfma_f32_16x16x32_bf16 v[88:91], v[52:55], v[12:15], 0
	ds_bpermute_b32 v124, v143, v126 offset:60
	ds_bpermute_b32 v125, v143, v127 offset:60
	ds_bpermute_b32 v104, v143, v106 offset:60
	v_mfma_f32_16x16x32_bf16 v[126:129], v[56:59], v[12:15], 0
	ds_bpermute_b32 v105, v143, v107 offset:60
	v_mfma_f32_16x16x32_bf16 v[92:95], v[60:63], v[28:31], v[88:91]
	v_mfma_f32_16x16x32_bf16 v[88:91], v[64:67], v[28:31], v[126:129]
	s_nop 6
	v_add_f32_e32 v92, v48, v92
	v_mul_f32_e32 v92, 0xbfb8aa3b, v92
	v_exp_f32_e32 v92, v92
	v_add_f32_e32 v88, v44, v88
	v_mul_f32_e32 v88, 0xbfb8aa3b, v88
	v_exp_f32_e32 v88, v88
	v_add_f32_e32 v92, 1.0, v92
; __device__ __forceinline__ float sigmoidf_(float x) { return __builtin_amdgcn_rcpf(1.0f + __expf(-x)); }
; __device__ __forceinline__ float bcast15(float v, int lane) { return bperm_f((lane & 48) | 15, v); }
; __device__ __forceinline__ void w_lru_m1(const Args& a, int l, unsigned char* ws, const bf16_t* proj, bf16_t* y, LAS unsigned char* wl, int b, int ck_, int h, int lane) {
;     ...
;         for (int tb = 0; tb < 4; ++tb) { const int tok = 16 * tb + lo;
;             f32x4 ga = {0.f, 0.f, 0.f, 0.f}, gx = {0.f, 0.f, 0.f, 0.f};
; #pragma unroll
;             for (int kk = 0; kk < 2; ++kk) { ga = __builtin_amdgcn_mfma_f32_16x16x32_bf16(WaF[kk], Xf[tb][kk], ga, 0, 0, 0); gx = __builtin_amdgcn_mfma_f32_16x16x32_bf16(WxF[kk], Xf[tb][kk], gx, 0, 0, 0); }
;             float hv[4], pv[4];
; #pragma unroll
;             for (int r = 0; r < 4; ++r) {
;                 const float rg = sigmoidf_(ga[r] + bav[r]), ig = sigmoidf_(gx[r] + bxv[r]);
;                 const float la = -8.0f * rg * sp[r]; float A = __expf(la);
;                 float U = __builtin_amdgcn_sqrtf(1.0f - A * A) * (ig * xcf[tok * 65 + j0 + r]);
;                 { const float As = dpp_shr1<1>(A), Us = dpp_shr0<1>(U); U = A * Us + U; A = A * As; }
;                 { const float As = dpp_shr1<2>(A), Us = dpp_shr0<2>(U); U = A * Us + U; A = A * As; }
;                 { const float As = dpp_shr1<4>(A), Us = dpp_shr0<4>(U); U = A * Us + U; A = A * As; }
;                 { const float As = dpp_shr1<8>(A), Us = dpp_shr0<8>(U); U = A * Us + U; A = A * As; }
;                 const float hh = U + A * hc[r], PP = A * Pc[r];
;                 hc[r] = bcast15(hh, lane); Pc[r] = bcast15(PP, lane); hv[r] = hh; pv[r] = PP; }
	v_rcp_f32_e32 v92, v92
	v_add_f32_e32 v89, v45, v89
	v_add_f32_e32 v88, 1.0, v88
	v_rcp_f32_e32 v106, v88
	v_mul_f32_e32 v88, 0xc1000000, v92
	v_add_f32_e32 v92, v49, v93
	v_mul_f32_e32 v92, 0xbfb8aa3b, v92
	v_exp_f32_e32 v92, v92
	v_mul_f32_e32 v89, 0xbfb8aa3b, v89
	v_exp_f32_e32 v89, v89
	v_mul_f32_e32 v88, v145, v88
	v_add_f32_e32 v92, 1.0, v92
	v_rcp_f32_e32 v92, v92
	v_add_f32_e32 v89, 1.0, v89
	v_rcp_f32_e32 v107, v89
	v_mul_f32_e32 v88, 0x3fb8aa3b, v88
	v_mul_f32_e32 v89, 0xc1000000, v92
	v_mul_f32_e32 v89, v147, v89
	v_mul_f32_e32 v89, 0x3fb8aa3b, v89
	v_exp_f32_e32 v122, v88
	v_exp_f32_e32 v123, v89
	v_add_f32_e32 v94, v50, v94
	v_add_f32_e32 v95, v51, v95
	v_fma_f32 v88, -v122, v122, 1.0
	v_fma_f32 v89, -v123, v123, 1.0
	v_sqrt_f32_e32 v126, v88
	v_mov_b32_e32 v88, 1.0
	v_sqrt_f32_e32 v127, v89
	v_mov_b32_e32 v89, 1.0
	v_mov_b32_dpp v88, v122 row_shr:1 row_mask:0xf bank_mask:0xf
	v_mul_f32_e32 v94, 0xbfb8aa3b, v94
	v_mov_b32_dpp v89, v123 row_shr:1 row_mask:0xf bank_mask:0xf
	v_pk_mul_f32 v[128:129], v[122:123], v[88:89]
	v_mov_b32_e32 v88, 1.0
	v_mov_b32_e32 v89, 1.0
	v_mul_f32_e32 v95, 0xbfb8aa3b, v95
	v_mov_b32_dpp v88, v128 row_shr:2 row_mask:0xf bank_mask:0xf
	v_mov_b32_dpp v89, v129 row_shr:2 row_mask:0xf bank_mask:0xf
	v_pk_mul_f32 v[130:131], v[128:129], v[88:89]
	v_mov_b32_e32 v88, 1.0
	v_mov_b32_e32 v89, 1.0
	v_exp_f32_e32 v94, v94
	v_mov_b32_dpp v88, v130 row_shr:4 row_mask:0xf bank_mask:0xf
	v_mov_b32_dpp v89, v131 row_shr:4 row_mask:0xf bank_mask:0xf
	v_pk_mul_f32 v[132:133], v[130:131], v[88:89]
	v_mov_b32_e32 v88, 1.0
	v_mov_b32_e32 v89, 1.0
	v_exp_f32_e32 v95, v95
	v_mov_b32_dpp v88, v132 row_shr:8 row_mask:0xf bank_mask:0xf
	v_mov_b32_dpp v89, v133 row_shr:8 row_mask:0xf bank_mask:0xf
	v_pk_mul_f32 v[134:135], v[132:133], v[88:89]
	v_add_f32_e32 v90, v46, v90
	s_waitcnt lgkmcnt(0)
	v_pk_mul_f32 v[92:93], v[134:135], v[104:105]
	ds_read2_b32 v[104:105], v148 offset1:1
	v_add_f32_e32 v91, v47, v91
	v_mul_f32_e32 v90, 0xbfb8aa3b, v90
	v_mul_f32_e32 v91, 0xbfb8aa3b, v91
	v_add_f32_e32 v94, 1.0, v94
	s_waitcnt lgkmcnt(0)
	v_pk_mul_f32 v[104:105], v[104:105], v[106:107]
	v_exp_f32_e32 v90, v90
	v_pk_mul_f32 v[104:105], v[104:105], v[126:127]
	v_add_f32_e32 v95, 1.0, v95
	v_exp_f32_e32 v91, v91
	v_mov_b32_dpp v106, v104 row_shr:1 row_mask:0xf bank_mask:0xf bound_ctrl:1
	v_mov_b32_dpp v107, v105 row_shr:1 row_mask:0xf bank_mask:0xf bound_ctrl:1
	v_pk_fma_f32 v[104:105], v[122:123], v[106:107], v[104:105]
	v_rcp_f32_e32 v94, v94
	v_rcp_f32_e32 v95, v95
	v_mov_b32_dpp v106, v104 row_shr:2 row_mask:0xf bank_mask:0xf bound_ctrl:1
	v_mov_b32_dpp v107, v105 row_shr:2 row_mask:0xf bank_mask:0xf bound_ctrl:1
	v_pk_fma_f32 v[104:105], v[128:129], v[106:107], v[104:105]
	v_add_f32_e32 v90, 1.0, v90
	v_add_f32_e32 v91, 1.0, v91
	v_mov_b32_dpp v106, v104 row_shr:4 row_mask:0xf bank_mask:0xf bound_ctrl:1
	v_mov_b32_dpp v107, v105 row_shr:4 row_mask:0xf bank_mask:0xf bound_ctrl:1
	v_pk_fma_f32 v[104:105], v[130:131], v[106:107], v[104:105]
	ds_bpermute_b32 v88, v143, v92 offset:60
	ds_bpermute_b32 v89, v143, v93 offset:60
	v_mov_b32_dpp v106, v104 row_shr:8 row_mask:0xf bank_mask:0xf bound_ctrl:1
	v_mov_b32_dpp v107, v105 row_shr:8 row_mask:0xf bank_mask:0xf bound_ctrl:1
	v_pk_fma_f32 v[104:105], v[132:133], v[106:107], v[104:105]
	v_rcp_f32_e32 v106, v90
	v_mul_f32_e32 v90, 0xc1000000, v94
	v_rcp_f32_e32 v107, v91
	v_mul_f32_e32 v91, 0xc1000000, v95
	v_mul_f32_e32 v90, v2, v90
	v_mul_f32_e32 v91, v146, v91
	v_mul_f32_e32 v90, 0x3fb8aa3b, v90
	v_mul_f32_e32 v91, 0x3fb8aa3b, v91
	v_exp_f32_e32 v94, v90
	v_exp_f32_e32 v95, v91
	v_pk_fma_f32 v[104:105], v[134:135], v[98:99], v[104:105]
	ds_read2_b32 v[134:135], v148 offset0:2 offset1:3
	v_fma_f32 v90, -v94, v94, 1.0
	v_fma_f32 v91, -v95, v95, 1.0
	v_sqrt_f32_e32 v122, v90
	v_sqrt_f32_e32 v123, v91
	s_waitcnt lgkmcnt(0)
	v_pk_mul_f32 v[106:107], v[106:107], v[134:135]
	v_mov_b32_e32 v90, 1.0
	v_mov_b32_e32 v91, 1.0
	v_pk_mul_f32 v[106:107], v[122:123], v[106:107]
	v_mov_b32_dpp v90, v94 row_shr:1 row_mask:0xf bank_mask:0xf
	v_mov_b32_dpp v91, v95 row_shr:1 row_mask:0xf bank_mask:0xf
	v_mov_b32_dpp v122, v106 row_shr:1 row_mask:0xf bank_mask:0xf bound_ctrl:1
	v_mov_b32_dpp v123, v107 row_shr:1 row_mask:0xf bank_mask:0xf bound_ctrl:1
	v_pk_mul_f32 v[126:127], v[94:95], v[90:91]
	v_mov_b32_e32 v90, 1.0
	v_mov_b32_e32 v91, 1.0
	v_pk_fma_f32 v[94:95], v[94:95], v[122:123], v[106:107]
	v_mov_b32_dpp v90, v126 row_shr:2 row_mask:0xf bank_mask:0xf
	v_mov_b32_dpp v91, v127 row_shr:2 row_mask:0xf bank_mask:0xf
	v_mov_b32_dpp v106, v94 row_shr:2 row_mask:0xf bank_mask:0xf bound_ctrl:1
	v_mov_b32_dpp v107, v95 row_shr:2 row_mask:0xf bank_mask:0xf bound_ctrl:1
	v_pk_mul_f32 v[128:129], v[126:127], v[90:91]
	v_mov_b32_e32 v90, 1.0
	v_mov_b32_e32 v91, 1.0
	v_pk_fma_f32 v[94:95], v[126:127], v[106:107], v[94:95]
	v_mov_b32_dpp v90, v128 row_shr:4 row_mask:0xf bank_mask:0xf
	v_mov_b32_dpp v91, v129 row_shr:4 row_mask:0xf bank_mask:0xf
	v_mov_b32_dpp v106, v94 row_shr:4 row_mask:0xf bank_mask:0xf bound_ctrl:1
	v_mov_b32_dpp v107, v95 row_shr:4 row_mask:0xf bank_mask:0xf bound_ctrl:1
	v_pk_mul_f32 v[130:131], v[128:129], v[90:91]
	v_mov_b32_e32 v90, 1.0
	v_mov_b32_e32 v91, 1.0
	v_pk_fma_f32 v[94:95], v[128:129], v[106:107], v[94:95]
	v_mov_b32_dpp v90, v130 row_shr:8 row_mask:0xf bank_mask:0xf
	v_mov_b32_dpp v91, v131 row_shr:8 row_mask:0xf bank_mask:0xf
	v_mov_b32_dpp v106, v94 row_shr:8 row_mask:0xf bank_mask:0xf bound_ctrl:1
	v_mov_b32_dpp v107, v95 row_shr:8 row_mask:0xf bank_mask:0xf bound_ctrl:1
	v_pk_mul_f32 v[132:133], v[130:131], v[90:91]
	v_pk_fma_f32 v[94:95], v[130:131], v[106:107], v[94:95]
; __device__ __forceinline__ unsigned pk2(float lo, float hi) { const f32x2_t v = {lo, hi}; const bf16x2_t b = __builtin_convertvector(v, bf16x2_t); return __builtin_bit_cast(unsigned, b); }
; __device__ __forceinline__ float sigmoidf_(float x) { return __builtin_amdgcn_rcpf(1.0f + __expf(-x)); }
; __device__ __forceinline__ float bcast15(float v, int lane) { return bperm_f((lane & 48) | 15, v); }
; __device__ __forceinline__ void w_lru_m1(const Args& a, int l, unsigned char* ws, const bf16_t* proj, bf16_t* y, LAS unsigned char* wl, int b, int ck_, int h, int lane) {
;     ...
;         for (int tb = 0; tb < 4; ++tb) { const int tok = 16 * tb + lo;
;             f32x4 ga = {0.f, 0.f, 0.f, 0.f}, gx = {0.f, 0.f, 0.f, 0.f};
; #pragma unroll
;             for (int kk = 0; kk < 2; ++kk) { ga = __builtin_amdgcn_mfma_f32_16x16x32_bf16(WaF[kk], Xf[tb][kk], ga, 0, 0, 0); gx = __builtin_amdgcn_mfma_f32_16x16x32_bf16(WxF[kk], Xf[tb][kk], gx, 0, 0, 0); }
;             float hv[4], pv[4];
; #pragma unroll
;             for (int r = 0; r < 4; ++r) {
;                 const float rg = sigmoidf_(ga[r] + bav[r]), ig = sigmoidf_(gx[r] + bxv[r]);
;                 const float la = -8.0f * rg * sp[r]; float A = __expf(la);
;                 float U = __builtin_amdgcn_sqrtf(1.0f - A * A) * (ig * xcf[tok * 65 + j0 + r]);
;                 { const float As = dpp_shr1<1>(A), Us = dpp_shr0<1>(U); U = A * Us + U; A = A * As; }
;                 { const float As = dpp_shr1<2>(A), Us = dpp_shr0<2>(U); U = A * Us + U; A = A * As; }
;                 { const float As = dpp_shr1<4>(A), Us = dpp_shr0<4>(U); U = A * Us + U; A = A * As; }
;                 { const float As = dpp_shr1<8>(A), Us = dpp_shr0<8>(U); U = A * Us + U; A = A * As; }
;                 const float hh = U + A * hc[r], PP = A * Pc[r];
;                 hc[r] = bcast15(hh, lane); Pc[r] = bcast15(PP, lane); hv[r] = hh; pv[r] = PP; }
;             *(unsigned long long*)(y + (size_t)(row0 + tok) * DM + 64 * h + j0) = (unsigned long long)pk2(hv[0], hv[1]) | ((unsigned long long)pk2(hv[2], hv[3]) << 32);
;             *(unsigned long long*)((bf16_t*)(ws + WS_P) + (size_t)(row0 + tok) * 512 + 64 * h + j0) = (unsigned long long)pk2(pv[0], pv[1]) | ((unsigned long long)pk2(pv[2], pv[3]) << 32);
;         }
	ds_bpermute_b32 v98, v143, v104 offset:60
	v_pk_fma_f32 v[94:95], v[132:133], v[96:97], v[94:95]
	ds_bpermute_b32 v96, v143, v94 offset:60
	v_cvt_pk_bf16_f32 v107, v94, v95
	v_or_b32_e32 v94, s48, v140
	ds_bpermute_b32 v97, v143, v95 offset:60
	v_ashrrev_i32_e32 v95, 31, v94
	ds_bpermute_b32 v99, v143, v105 offset:60
	v_cvt_pk_bf16_f32 v106, v104, v105
	v_lshlrev_b64 v[104:105], 11, v[94:95]
	v_pk_mul_f32 v[124:125], v[132:133], v[124:125]
	v_lshl_add_u64 v[104:105], v[114:115], 0, v[104:105]
	v_lshlrev_b64 v[94:95], 10, v[94:95]
	global_store_dwordx2 v[104:105], v[106:107], off
	v_cvt_pk_bf16_f32 v92, v92, v93
	v_cvt_pk_bf16_f32 v93, v124, v125
	v_lshl_add_u64 v[106:107], v[116:117], 0, v[94:95]
	global_store_dwordx2 v[106:107], v[92:93], off
	v_mfma_f32_16x16x32_bf16 v[92:95], v[52:55], v[8:11], 0
	ds_bpermute_b32 v90, v143, v124 offset:60
	ds_bpermute_b32 v91, v143, v125 offset:60
	v_mfma_f32_16x16x32_bf16 v[126:129], v[60:63], v[24:27], v[92:95]
	v_mfma_f32_16x16x32_bf16 v[122:125], v[56:59], v[8:11], 0
	v_mfma_f32_16x16x32_bf16 v[122:125], v[64:67], v[24:27], v[122:125]
	s_nop 5
	v_add_f32_e32 v92, v48, v126
	v_mul_f32_e32 v92, 0xbfb8aa3b, v92
	v_exp_f32_e32 v92, v92
	v_mfma_f32_16x16x32_bf16 v[52:55], v[52:55], v[4:7], 0
	v_add_f32_e32 v92, 1.0, v92
	v_rcp_f32_e32 v93, v92
	v_add_f32_e32 v92, v44, v122
	v_mov_b32_e32 v122, 1.0
	v_mul_f32_e32 v92, 0xbfb8aa3b, v92
	v_mul_f32_e32 v93, 0xc1000000, v93
	v_mul_f32_e32 v93, v145, v93
	v_mul_f32_e32 v93, 0x3fb8aa3b, v93
	v_exp_f32_e32 v94, v93
	v_exp_f32_e32 v92, v92
	v_fma_f32 v93, -v94, v94, 1.0
	v_sqrt_f32_e32 v126, v93
	v_add_f32_e32 v93, v49, v127
	v_mul_f32_e32 v93, 0xbfb8aa3b, v93
	v_exp_f32_e32 v93, v93
	v_mov_b32_dpp v122, v94 row_shr:1 row_mask:0xf bank_mask:0xf
	v_add_f32_e32 v92, 1.0, v92
	v_rcp_f32_e32 v92, v92
	v_add_f32_e32 v93, 1.0, v93
	v_rcp_f32_e32 v95, v93
	v_add_f32_e32 v93, v45, v123
	v_mul_f32_e32 v93, 0xbfb8aa3b, v93
	v_exp_f32_e32 v93, v93
	v_mul_f32_e32 v95, 0xc1000000, v95
	v_mul_f32_e32 v95, v147, v95
	v_mul_f32_e32 v95, 0x3fb8aa3b, v95
	v_exp_f32_e32 v95, v95
	v_add_f32_e32 v93, 1.0, v93
	v_rcp_f32_e32 v93, v93
	v_fma_f32 v123, -v95, v95, 1.0
	v_sqrt_f32_e32 v127, v123
	v_mov_b32_e32 v123, 1.0
	s_nop 1
	v_mov_b32_dpp v123, v95 row_shr:1 row_mask:0xf bank_mask:0xf
	v_pk_mul_f32 v[130:131], v[94:95], v[122:123]
	v_mov_b32_e32 v122, 1.0
	v_mov_b32_e32 v123, 1.0
	s_nop 0
	v_mov_b32_dpp v122, v130 row_shr:2 row_mask:0xf bank_mask:0xf
	v_mov_b32_dpp v123, v131 row_shr:2 row_mask:0xf bank_mask:0xf
	v_pk_mul_f32 v[132:133], v[130:131], v[122:123]
	v_mov_b32_e32 v122, 1.0
	v_mov_b32_e32 v123, 1.0
	s_nop 0
	v_mov_b32_dpp v122, v132 row_shr:4 row_mask:0xf bank_mask:0xf
	v_mov_b32_dpp v123, v133 row_shr:4 row_mask:0xf bank_mask:0xf
	v_pk_mul_f32 v[134:135], v[132:133], v[122:123]
	v_mov_b32_e32 v122, 1.0
	v_mov_b32_e32 v123, 1.0
	s_nop 0
	v_mov_b32_dpp v122, v134 row_shr:8 row_mask:0xf bank_mask:0xf
	v_mov_b32_dpp v123, v135 row_shr:8 row_mask:0xf bank_mask:0xf
	v_pk_mul_f32 v[140:141], v[134:135], v[122:123]
	s_nop 0
	v_pk_mul_f32 v[148:149], v[140:141], v[88:89]
	ds_read2_b32 v[88:89], v150 offset1:1
	ds_bpermute_b32 v122, v143, v148 offset:60
	ds_bpermute_b32 v123, v143, v149 offset:60
	s_waitcnt lgkmcnt(0)
	v_pk_mul_f32 v[88:89], v[88:89], v[92:93]
	s_nop 0
	v_pk_mul_f32 v[88:89], v[88:89], v[126:127]
	s_nop 1
	v_mov_b32_dpp v92, v88 row_shr:1 row_mask:0xf bank_mask:0xf bound_ctrl:1
	v_mov_b32_dpp v93, v89 row_shr:1 row_mask:0xf bank_mask:0xf bound_ctrl:1
	v_pk_fma_f32 v[88:89], v[94:95], v[92:93], v[88:89]
	s_nop 1
	v_mov_b32_dpp v92, v88 row_shr:2 row_mask:0xf bank_mask:0xf bound_ctrl:1
	v_mov_b32_dpp v93, v89 row_shr:2 row_mask:0xf bank_mask:0xf bound_ctrl:1
	v_pk_fma_f32 v[88:89], v[130:131], v[92:93], v[88:89]
	s_nop 1
	v_mov_b32_dpp v92, v88 row_shr:4 row_mask:0xf bank_mask:0xf bound_ctrl:1
	v_mov_b32_dpp v93, v89 row_shr:4 row_mask:0xf bank_mask:0xf bound_ctrl:1
	v_pk_fma_f32 v[88:89], v[132:133], v[92:93], v[88:89]
	s_nop 1
	v_mov_b32_dpp v92, v88 row_shr:8 row_mask:0xf bank_mask:0xf bound_ctrl:1
	v_mov_b32_dpp v93, v89 row_shr:8 row_mask:0xf bank_mask:0xf bound_ctrl:1
	v_pk_fma_f32 v[88:89], v[134:135], v[92:93], v[88:89]
	v_mov_b32_e32 v92, 1.0
	v_pk_fma_f32 v[98:99], v[140:141], v[98:99], v[88:89]
	v_add_f32_e32 v88, v50, v128
	v_mul_f32_e32 v88, 0xbfb8aa3b, v88
	v_exp_f32_e32 v88, v88
	ds_read2_b32 v[140:141], v150 offset0:2 offset1:3
	ds_bpermute_b32 v94, v143, v98 offset:60
	ds_bpermute_b32 v95, v143, v99 offset:60
	v_add_f32_e32 v88, 1.0, v88
	v_rcp_f32_e32 v89, v88
	v_add_f32_e32 v88, v46, v124
	v_mul_f32_e32 v88, 0xbfb8aa3b, v88
	v_exp_f32_e32 v88, v88
	v_mul_f32_e32 v89, 0xc1000000, v89
	v_mul_f32_e32 v89, v2, v89
	v_mul_f32_e32 v89, 0x3fb8aa3b, v89
	v_exp_f32_e32 v124, v89
	v_add_f32_e32 v88, 1.0, v88
	v_rcp_f32_e32 v88, v88
	v_cvt_pk_bf16_f32 v98, v98, v99
	v_fma_f32 v89, -v124, v124, 1.0
	v_sqrt_f32_e32 v126, v89
	v_add_f32_e32 v89, v51, v129
	v_mul_f32_e32 v89, 0xbfb8aa3b, v89
	v_exp_f32_e32 v89, v89
	v_mov_b32_dpp v92, v124 row_shr:1 row_mask:0xf bank_mask:0xf
	v_add_f32_e32 v89, 1.0, v89
	v_rcp_f32_e32 v93, v89
	v_add_f32_e32 v89, v47, v125
	v_mul_f32_e32 v89, 0xbfb8aa3b, v89
	v_exp_f32_e32 v89, v89
	v_mul_f32_e32 v93, 0xc1000000, v93
	v_mul_f32_e32 v93, v146, v93
	v_mul_f32_e32 v93, 0x3fb8aa3b, v93
	v_exp_f32_e32 v125, v93
	v_add_f32_e32 v89, 1.0, v89
	v_rcp_f32_e32 v89, v89
	v_fma_f32 v93, -v125, v125, 1.0
	v_sqrt_f32_e32 v127, v93
	s_waitcnt lgkmcnt(0)
; __device__ __forceinline__ unsigned pk2(float lo, float hi) { const f32x2_t v = {lo, hi}; const bf16x2_t b = __builtin_convertvector(v, bf16x2_t); return __builtin_bit_cast(unsigned, b); }
; __device__ __forceinline__ float sigmoidf_(float x) { return __builtin_amdgcn_rcpf(1.0f + __expf(-x)); }
; __device__ __forceinline__ float bcast15(float v, int lane) { return bperm_f((lane & 48) | 15, v); }
; __device__ __forceinline__ void w_lru_m1(const Args& a, int l, unsigned char* ws, const bf16_t* proj, bf16_t* y, LAS unsigned char* wl, int b, int ck_, int h, int lane) {
;     ...
;         for (int tb = 0; tb < 4; ++tb) { const int tok = 16 * tb + lo;
;             f32x4 ga = {0.f, 0.f, 0.f, 0.f}, gx = {0.f, 0.f, 0.f, 0.f};
; #pragma unroll
;             for (int kk = 0; kk < 2; ++kk) { ga = __builtin_amdgcn_mfma_f32_16x16x32_bf16(WaF[kk], Xf[tb][kk], ga, 0, 0, 0); gx = __builtin_amdgcn_mfma_f32_16x16x32_bf16(WxF[kk], Xf[tb][kk], gx, 0, 0, 0); }
;             float hv[4], pv[4];
; #pragma unroll
;             for (int r = 0; r < 4; ++r) {
;                 const float rg = sigmoidf_(ga[r] + bav[r]), ig = sigmoidf_(gx[r] + bxv[r]);
;                 const float la = -8.0f * rg * sp[r]; float A = __expf(la);
;                 float U = __builtin_amdgcn_sqrtf(1.0f - A * A) * (ig * xcf[tok * 65 + j0 + r]);
;                 { const float As = dpp_shr1<1>(A), Us = dpp_shr0<1>(U); U = A * Us + U; A = A * As; }
;                 { const float As = dpp_shr1<2>(A), Us = dpp_shr0<2>(U); U = A * Us + U; A = A * As; }
;                 { const float As = dpp_shr1<4>(A), Us = dpp_shr0<4>(U); U = A * Us + U; A = A * As; }
;                 { const float As = dpp_shr1<8>(A), Us = dpp_shr0<8>(U); U = A * Us + U; A = A * As; }
;                 const float hh = U + A * hc[r], PP = A * Pc[r];
;                 hc[r] = bcast15(hh, lane); Pc[r] = bcast15(PP, lane); hv[r] = hh; pv[r] = PP; }
;             *(unsigned long long*)(y + (size_t)(row0 + tok) * DM + 64 * h + j0) = (unsigned long long)pk2(hv[0], hv[1]) | ((unsigned long long)pk2(hv[2], hv[3]) << 32);
;             *(unsigned long long*)((bf16_t*)(ws + WS_P) + (size_t)(row0 + tok) * 512 + 64 * h + j0) = (unsigned long long)pk2(pv[0], pv[1]) | ((unsigned long long)pk2(pv[2], pv[3]) << 32);
;         }
	v_pk_mul_f32 v[88:89], v[88:89], v[140:141]
	v_mov_b32_e32 v93, 1.0
	v_pk_mul_f32 v[88:89], v[126:127], v[88:89]
	s_nop 0
	v_mov_b32_dpp v93, v125 row_shr:1 row_mask:0xf bank_mask:0xf
	v_mov_b32_dpp v126, v88 row_shr:1 row_mask:0xf bank_mask:0xf bound_ctrl:1
	v_mov_b32_dpp v127, v89 row_shr:1 row_mask:0xf bank_mask:0xf bound_ctrl:1
	v_pk_mul_f32 v[128:129], v[124:125], v[92:93]
	v_mov_b32_e32 v92, 1.0
	v_mov_b32_e32 v93, 1.0
	v_pk_fma_f32 v[88:89], v[124:125], v[126:127], v[88:89]
	v_mov_b32_dpp v92, v128 row_shr:2 row_mask:0xf bank_mask:0xf
	v_mov_b32_dpp v93, v129 row_shr:2 row_mask:0xf bank_mask:0xf
	v_mov_b32_dpp v124, v88 row_shr:2 row_mask:0xf bank_mask:0xf bound_ctrl:1
	v_mov_b32_dpp v125, v89 row_shr:2 row_mask:0xf bank_mask:0xf bound_ctrl:1
	v_pk_mul_f32 v[130:131], v[128:129], v[92:93]
	v_mov_b32_e32 v92, 1.0
	v_mov_b32_e32 v93, 1.0
	v_pk_fma_f32 v[88:89], v[128:129], v[124:125], v[88:89]
	v_mov_b32_dpp v92, v130 row_shr:4 row_mask:0xf bank_mask:0xf
	v_mov_b32_dpp v93, v131 row_shr:4 row_mask:0xf bank_mask:0xf
	v_mov_b32_dpp v124, v88 row_shr:4 row_mask:0xf bank_mask:0xf bound_ctrl:1
	v_mov_b32_dpp v125, v89 row_shr:4 row_mask:0xf bank_mask:0xf bound_ctrl:1
	v_pk_mul_f32 v[132:133], v[130:131], v[92:93]
	v_mov_b32_e32 v92, 1.0
	v_mov_b32_e32 v93, 1.0
	v_pk_fma_f32 v[88:89], v[130:131], v[124:125], v[88:89]
	v_mov_b32_dpp v92, v132 row_shr:8 row_mask:0xf bank_mask:0xf
	v_mov_b32_dpp v93, v133 row_shr:8 row_mask:0xf bank_mask:0xf
	v_mov_b32_dpp v124, v88 row_shr:8 row_mask:0xf bank_mask:0xf bound_ctrl:1
	v_mov_b32_dpp v125, v89 row_shr:8 row_mask:0xf bank_mask:0xf bound_ctrl:1
	v_pk_mul_f32 v[134:135], v[132:133], v[92:93]
	v_pk_fma_f32 v[88:89], v[132:133], v[124:125], v[88:89]
	v_or_b32_e32 v124, s48, v139
	v_pk_fma_f32 v[96:97], v[134:135], v[96:97], v[88:89]
	v_ashrrev_i32_e32 v125, 31, v124
	v_pk_mul_f32 v[90:91], v[134:135], v[90:91]
	ds_bpermute_b32 v88, v143, v96 offset:60
	ds_bpermute_b32 v89, v143, v97 offset:60
	v_cvt_pk_bf16_f32 v99, v96, v97
	v_lshlrev_b64 v[96:97], 11, v[124:125]
	ds_bpermute_b32 v92, v143, v90 offset:60
	ds_bpermute_b32 v93, v143, v91 offset:60
	v_lshl_add_u64 v[96:97], v[114:115], 0, v[96:97]
	v_cvt_pk_bf16_f32 v127, v90, v91
	v_lshlrev_b64 v[90:91], 10, v[124:125]
	global_store_dwordx2 v[96:97], v[98:99], off
	v_cvt_pk_bf16_f32 v126, v148, v149
	v_lshl_add_u64 v[98:99], v[116:117], 0, v[90:91]
	global_store_dwordx2 v[98:99], v[126:127], off
	v_mfma_f32_16x16x32_bf16 v[124:127], v[56:59], v[4:7], 0
	v_mfma_f32_16x16x32_bf16 v[56:59], v[60:63], v[20:23], v[52:55]
	v_mfma_f32_16x16x32_bf16 v[52:55], v[64:67], v[20:23], v[124:127]
	s_nop 5
	v_add_u32_e32 v124, v142, v138
	v_add_f32_e32 v48, v48, v56
	v_add_f32_e32 v49, v49, v57
	v_mul_f32_e32 v48, 0xbfb8aa3b, v48
	v_mul_f32_e32 v49, 0xbfb8aa3b, v49
	v_exp_f32_e32 v48, v48
	v_exp_f32_e32 v49, v49
	v_add_f32_e32 v44, v44, v52
	v_add_f32_e32 v45, v45, v53
	v_mul_f32_e32 v44, 0xbfb8aa3b, v44
	v_mul_f32_e32 v45, 0xbfb8aa3b, v45
	v_add_f32_e32 v48, 1.0, v48
	v_exp_f32_e32 v44, v44
	v_add_f32_e32 v49, 1.0, v49
	v_exp_f32_e32 v45, v45
	v_rcp_f32_e32 v56, v48
	v_rcp_f32_e32 v52, v49
	v_add_f32_e32 v44, 1.0, v44
	v_add_f32_e32 v45, 1.0, v45
	v_rcp_f32_e32 v48, v44
	v_mul_f32_e32 v44, 0xc1000000, v56
	v_rcp_f32_e32 v49, v45
	v_mul_f32_e32 v45, 0xc1000000, v52
	v_mul_f32_e32 v44, v145, v44
	v_mul_f32_e32 v45, v147, v45
	v_mul_f32_e32 v44, 0x3fb8aa3b, v44
	v_mul_f32_e32 v45, 0x3fb8aa3b, v45
	v_exp_f32_e32 v56, v44
	v_exp_f32_e32 v57, v45
	v_add_f32_e32 v50, v50, v58
	v_mul_f32_e32 v50, 0xbfb8aa3b, v50
	v_fma_f32 v44, -v56, v56, 1.0
	v_fma_f32 v45, -v57, v57, 1.0
	v_sqrt_f32_e32 v60, v44
	v_mov_b32_e32 v44, 1.0
	v_sqrt_f32_e32 v61, v45
	v_mov_b32_e32 v45, 1.0
	v_exp_f32_e32 v50, v50
	v_mov_b32_dpp v44, v56 row_shr:1 row_mask:0xf bank_mask:0xf
	v_mov_b32_dpp v45, v57 row_shr:1 row_mask:0xf bank_mask:0xf
	v_pk_mul_f32 v[62:63], v[56:57], v[44:45]
	v_mov_b32_e32 v44, 1.0
	v_mov_b32_e32 v45, 1.0
	v_add_f32_e32 v46, v46, v54
	v_mov_b32_dpp v44, v62 row_shr:2 row_mask:0xf bank_mask:0xf
	v_mov_b32_dpp v45, v63 row_shr:2 row_mask:0xf bank_mask:0xf
	v_mul_f32_e32 v46, 0xbfb8aa3b, v46
	v_pk_mul_f32 v[64:65], v[62:63], v[44:45]
	v_mov_b32_e32 v44, 1.0
	v_mov_b32_e32 v45, 1.0
	v_add_f32_e32 v50, 1.0, v50
	v_exp_f32_e32 v46, v46
	v_mov_b32_dpp v44, v64 row_shr:4 row_mask:0xf bank_mask:0xf
	v_mov_b32_dpp v45, v65 row_shr:4 row_mask:0xf bank_mask:0xf
	v_rcp_f32_e32 v50, v50
	v_pk_mul_f32 v[66:67], v[64:65], v[44:45]
	v_mov_b32_e32 v44, 1.0
	v_mov_b32_e32 v45, 1.0
	v_add_f32_e32 v46, 1.0, v46
	v_mov_b32_dpp v44, v66 row_shr:8 row_mask:0xf bank_mask:0xf
	v_mov_b32_dpp v45, v67 row_shr:8 row_mask:0xf bank_mask:0xf
	v_pk_mul_f32 v[90:91], v[66:67], v[44:45]
	v_rcp_f32_e32 v54, v46
	v_pk_mul_f32 v[52:53], v[90:91], v[122:123]
	ds_read2_b32 v[122:123], v124 offset1:1
	v_mul_f32_e32 v46, 0xc1000000, v50
	v_mul_f32_e32 v2, v2, v46
	v_mul_f32_e32 v2, 0x3fb8aa3b, v2
	v_exp_f32_e32 v50, v2
	s_waitcnt lgkmcnt(0)
; __device__ __forceinline__ unsigned pk2(float lo, float hi) { const f32x2_t v = {lo, hi}; const bf16x2_t b = __builtin_convertvector(v, bf16x2_t); return __builtin_bit_cast(unsigned, b); }
; __device__ __forceinline__ float sigmoidf_(float x) { return __builtin_amdgcn_rcpf(1.0f + __expf(-x)); }
; __device__ __forceinline__ void w_lru_m1(const Args& a, int l, unsigned char* ws, const bf16_t* proj, bf16_t* y, LAS unsigned char* wl, int b, int ck_, int h, int lane) {
;     ...
;         for (int tb = 0; tb < 4; ++tb) { const int tok = 16 * tb + lo;
;             f32x4 ga = {0.f, 0.f, 0.f, 0.f}, gx = {0.f, 0.f, 0.f, 0.f};
; #pragma unroll
;             for (int kk = 0; kk < 2; ++kk) { ga = __builtin_amdgcn_mfma_f32_16x16x32_bf16(WaF[kk], Xf[tb][kk], ga, 0, 0, 0); gx = __builtin_amdgcn_mfma_f32_16x16x32_bf16(WxF[kk], Xf[tb][kk], gx, 0, 0, 0); }
;             float hv[4], pv[4];
; #pragma unroll
;             for (int r = 0; r < 4; ++r) {
;                 const float rg = sigmoidf_(ga[r] + bav[r]), ig = sigmoidf_(gx[r] + bxv[r]);
;                 const float la = -8.0f * rg * sp[r]; float A = __expf(la);
;                 float U = __builtin_amdgcn_sqrtf(1.0f - A * A) * (ig * xcf[tok * 65 + j0 + r]);
;                 { const float As = dpp_shr1<1>(A), Us = dpp_shr0<1>(U); U = A * Us + U; A = A * As; }
;                 { const float As = dpp_shr1<2>(A), Us = dpp_shr0<2>(U); U = A * Us + U; A = A * As; }
;                 { const float As = dpp_shr1<4>(A), Us = dpp_shr0<4>(U); U = A * Us + U; A = A * As; }
;                 { const float As = dpp_shr1<8>(A), Us = dpp_shr0<8>(U); U = A * Us + U; A = A * As; }
;                 const float hh = U + A * hc[r], PP = A * Pc[r];
;                 hc[r] = bcast15(hh, lane); Pc[r] = bcast15(PP, lane); hv[r] = hh; pv[r] = PP; }
;             *(unsigned long long*)(y + (size_t)(row0 + tok) * DM + 64 * h + j0) = (unsigned long long)pk2(hv[0], hv[1]) | ((unsigned long long)pk2(hv[2], hv[3]) << 32);
;             *(unsigned long long*)((bf16_t*)(ws + WS_P) + (size_t)(row0 + tok) * 512 + 64 * h + j0) = (unsigned long long)pk2(pv[0], pv[1]) | ((unsigned long long)pk2(pv[2], pv[3]) << 32);
;         }
;         if (lo == 0) { const size_t so = (size_t)(b * NCH + ck_) * 512 + 64 * h + j0;
; #pragma unroll
;             for (int r = 0; r < 4; ++r) { ((float*)(ws + WS_LRUA))[so + r] = Pc[r]; ((float*)(ws + WS_LRUH))[so + r] = hc[r]; } }
	v_pk_mul_f32 v[48:49], v[122:123], v[48:49]
	v_add_f32_e32 v47, v47, v55
	v_pk_mul_f32 v[48:49], v[48:49], v[60:61]
	v_fma_f32 v2, -v50, v50, 1.0
	v_mul_f32_e32 v47, 0xbfb8aa3b, v47
	v_mov_b32_dpp v60, v48 row_shr:1 row_mask:0xf bank_mask:0xf bound_ctrl:1
	v_mov_b32_dpp v61, v49 row_shr:1 row_mask:0xf bank_mask:0xf bound_ctrl:1
	v_pk_fma_f32 v[48:49], v[56:57], v[60:61], v[48:49]
	v_sqrt_f32_e32 v60, v2
	v_add_f32_e32 v2, v51, v59
	v_mul_f32_e32 v2, 0xbfb8aa3b, v2
	v_exp_f32_e32 v2, v2
	v_exp_f32_e32 v47, v47
	v_mov_b32_e32 v46, 1.0
	v_mov_b32_dpp v56, v48 row_shr:2 row_mask:0xf bank_mask:0xf bound_ctrl:1
	v_add_f32_e32 v2, 1.0, v2
	v_rcp_f32_e32 v2, v2
	v_add_f32_e32 v47, 1.0, v47
	v_rcp_f32_e32 v55, v47
	v_mov_b32_e32 v47, 1.0
	v_mul_f32_e32 v2, 0xc1000000, v2
	v_mul_f32_e32 v2, v146, v2
	v_mul_f32_e32 v2, 0x3fb8aa3b, v2
	v_exp_f32_e32 v51, v2
	v_mov_b32_dpp v57, v49 row_shr:2 row_mask:0xf bank_mask:0xf bound_ctrl:1
	v_mov_b32_dpp v46, v50 row_shr:1 row_mask:0xf bank_mask:0xf
	v_pk_fma_f32 v[48:49], v[62:63], v[56:57], v[48:49]
	v_mov_b32_dpp v47, v51 row_shr:1 row_mask:0xf bank_mask:0xf
	v_pk_mul_f32 v[62:63], v[50:51], v[46:47]
	v_mov_b32_e32 v46, 1.0
	v_mov_b32_e32 v47, 1.0
	v_mov_b32_dpp v56, v48 row_shr:4 row_mask:0xf bank_mask:0xf bound_ctrl:1
	v_mov_b32_dpp v57, v49 row_shr:4 row_mask:0xf bank_mask:0xf bound_ctrl:1
	v_mov_b32_dpp v46, v62 row_shr:2 row_mask:0xf bank_mask:0xf
	v_mov_b32_dpp v47, v63 row_shr:2 row_mask:0xf bank_mask:0xf
	v_pk_fma_f32 v[48:49], v[64:65], v[56:57], v[48:49]
	v_pk_mul_f32 v[64:65], v[62:63], v[46:47]
	v_mov_b32_e32 v46, 1.0
	v_mov_b32_e32 v47, 1.0
	v_mov_b32_dpp v56, v48 row_shr:8 row_mask:0xf bank_mask:0xf bound_ctrl:1
	v_mov_b32_dpp v57, v49 row_shr:8 row_mask:0xf bank_mask:0xf bound_ctrl:1
	v_mov_b32_dpp v46, v64 row_shr:4 row_mask:0xf bank_mask:0xf
	v_mov_b32_dpp v47, v65 row_shr:4 row_mask:0xf bank_mask:0xf
	v_pk_fma_f32 v[48:49], v[66:67], v[56:57], v[48:49]
	v_pk_mul_f32 v[66:67], v[64:65], v[46:47]
	v_mov_b32_e32 v46, 1.0
	v_mov_b32_e32 v47, 1.0
	v_pk_fma_f32 v[56:57], v[90:91], v[94:95], v[48:49]
	v_mov_b32_dpp v46, v66 row_shr:8 row_mask:0xf bank_mask:0xf
	v_mov_b32_dpp v47, v67 row_shr:8 row_mask:0xf bank_mask:0xf
	v_pk_mul_f32 v[90:91], v[66:67], v[46:47]
	v_fma_f32 v2, -v51, v51, 1.0
	v_pk_mul_f32 v[58:59], v[90:91], v[92:93]
	ds_read2_b32 v[92:93], v124 offset0:2 offset1:3
	v_sqrt_f32_e32 v61, v2
	ds_bpermute_b32 v44, v143, v52 offset:60
	ds_bpermute_b32 v48, v143, v56 offset:60
	ds_bpermute_b32 v49, v143, v57 offset:60
	s_waitcnt lgkmcnt(0)
	v_pk_mul_f32 v[54:55], v[54:55], v[92:93]
	ds_bpermute_b32 v45, v143, v53 offset:60
	v_pk_mul_f32 v[54:55], v[60:61], v[54:55]
	ds_bpermute_b32 v46, v143, v58 offset:60
	ds_bpermute_b32 v47, v143, v59 offset:60
	v_mov_b32_dpp v60, v54 row_shr:1 row_mask:0xf bank_mask:0xf bound_ctrl:1
	v_mov_b32_dpp v61, v55 row_shr:1 row_mask:0xf bank_mask:0xf bound_ctrl:1
	v_pk_fma_f32 v[50:51], v[50:51], v[60:61], v[54:55]
	v_cvt_pk_bf16_f32 v56, v56, v57
	v_cvt_pk_bf16_f32 v52, v52, v53
	v_mov_b32_dpp v54, v50 row_shr:2 row_mask:0xf bank_mask:0xf bound_ctrl:1
	v_mov_b32_dpp v55, v51 row_shr:2 row_mask:0xf bank_mask:0xf bound_ctrl:1
	v_pk_fma_f32 v[50:51], v[62:63], v[54:55], v[50:51]
	v_cvt_pk_bf16_f32 v53, v58, v59
	s_nop 0
	v_mov_b32_dpp v54, v50 row_shr:4 row_mask:0xf bank_mask:0xf bound_ctrl:1
	v_mov_b32_dpp v55, v51 row_shr:4 row_mask:0xf bank_mask:0xf bound_ctrl:1
	v_pk_fma_f32 v[50:51], v[64:65], v[54:55], v[50:51]
	s_nop 1
	v_mov_b32_dpp v54, v50 row_shr:8 row_mask:0xf bank_mask:0xf bound_ctrl:1
	v_mov_b32_dpp v55, v51 row_shr:8 row_mask:0xf bank_mask:0xf bound_ctrl:1
	v_pk_fma_f32 v[50:51], v[66:67], v[54:55], v[50:51]
	s_nop 0
	v_pk_fma_f32 v[54:55], v[90:91], v[88:89], v[50:51]
	ds_bpermute_b32 v50, v143, v54 offset:60
	ds_bpermute_b32 v51, v143, v55 offset:60
	v_cvt_pk_bf16_f32 v57, v54, v55
	v_or_b32_e32 v54, s48, v137
	v_ashrrev_i32_e32 v55, 31, v54
	v_lshlrev_b64 v[60:61], 11, v[54:55]
	v_lshlrev_b64 v[54:55], 10, v[54:55]
	v_lshl_add_u64 v[114:115], v[114:115], 0, v[60:61]
	v_lshl_add_u64 v[116:117], v[116:117], 0, v[54:55]
	global_store_dwordx2 v[114:115], v[56:57], off
	global_store_dwordx2 v[116:117], v[52:53], off
	s_and_saveexec_b64 s[34:35], vcc
	s_cbranch_execz .LBB0_523
	v_lshl_add_u64 v[52:53], s[42:43], 0, v[0:1]
	v_lshlrev_b64 v[52:53], 2, v[52:53]
	v_lshl_add_u64 v[54:55], s[84:85], 0, v[52:53]
	v_lshl_add_u64 v[52:53], s[86:87], 0, v[52:53]
	s_waitcnt lgkmcnt(0)
	global_store_dwordx4 v[54:55], v[44:47], off
	global_store_dwordx4 v[52:53], v[48:51], off
; __device__ __forceinline__ void w_lru_m1(const Args& a, int l, unsigned char* ws, const bf16_t* proj, bf16_t* y, LAS unsigned char* wl, int b, int ck_, int h, int lane) {
;     ...
;     for (int jb = 0; jb < 4; ++jb) {
;         bf16x8 WaF[2], WxF[2]; f32x4 pba, pbx, plam;
; #pragma unroll
;         for (int kk = 0; kk < 2; ++kk) { WaF[kk] = nWa[kk]; WxF[kk] = nWx[kk]; }
;         pba = nba; pbx = nbx; plam = nlam;
;         if (jb < 3) {
; #pragma unroll
;             for (int kk = 0; kk < 2; ++kk) { nWa[kk] = *(const bf16x8*)(waT + (16 * (jb + 1) + lo) * 64 + 32 * kk + 8 * fq); nWx[kk] = *(const bf16x8*)(wxT + (16 * (jb + 1) + lo) * 64 + 32 * kk + 8 * fq); }
;             nba = *(const f32x4*)(ba + 16 * (jb + 1) + 4 * fq); nbx = *(const f32x4*)(bx + 16 * (jb + 1) + 4 * fq); nlam = *(const f32x4*)(lam + 16 * (jb + 1) + 4 * fq);
;         }
;         const int j0 = 16 * jb + 4 * fq;
;         float bav[4], bxv[4], sp[4], hc[4], Pc[4];
; #pragma unroll
;         for (int r = 0; r < 4; ++r) { bav[r] = pba[r]; bxv[r] = pbx[r]; sp[r] = log1pf(__expf(-plam[r])); hc[r] = 0.f; Pc[r] = 1.f; }
; #pragma unroll
;         for (int tb = 0; tb < 4; ++tb) { const int tok = 16 * tb + lo;
;             f32x4 ga = {0.f, 0.f, 0.f, 0.f}, gx = {0.f, 0.f, 0.f, 0.f};
; #pragma unroll
;             for (int kk = 0; kk < 2; ++kk) { ga = __builtin_amdgcn_mfma_f32_16x16x32_bf16(WaF[kk], Xf[tb][kk], ga, 0, 0, 0); gx = __builtin_amdgcn_mfma_f32_16x16x32_bf16(WxF[kk], Xf[tb][kk], gx, 0, 0, 0); }
;             float hv[4], pv[4];
; #pragma unroll
;             for (int r = 0; r < 4; ++r) {
;                 const float rg = sigmoidf_(ga[r] + bav[r]), ig = sigmoidf_(gx[r] + bxv[r]);
;                 const float la = -8.0f * rg * sp[r]; float A = __expf(la);
;                 float U = __builtin_amdgcn_sqrtf(1.0f - A * A) * (ig * xcf[tok * 65 + j0 + r]);
;                 { const float As = dpp_shr1<1>(A), Us = dpp_shr0<1>(U); U = A * Us + U; A = A * As; }
;                 { const float As = dpp_shr1<2>(A), Us = dpp_shr0<2>(U); U = A * Us + U; A = A * As; }
;                 { const float As = dpp_shr1<4>(A), Us = dpp_shr0<4>(U); U = A * Us + U; A = A * As; }
;                 { const float As = dpp_shr1<8>(A), Us = dpp_shr0<8>(U); U = A * Us + U; A = A * As; }
;                 const float hh = U + A * hc[r], PP = A * Pc[r];
.LBB0_523:
	s_or_b64 exec, exec, s[34:35]
	v_lshlrev_b32_e32 v146, 6, v136
	v_lshl_or_b32 v2, v146, 1, v209
	s_waitcnt lgkmcnt(0)
	v_lshl_add_u64 v[44:45], v[118:119], 0, v[2:3]
	v_lshl_add_u64 v[46:47], v[120:121], 0, v[2:3]
	s_waitcnt vmcnt(10)
	s_nop 7
	v_mul_u32_u24_e32 v92, 0x104, v136
	v_add_u32_e32 v145, v142, v92
	global_load_dwordx4 v[64:67], v[44:45], off
	global_load_dwordx4 v[60:63], v[46:47], off
	global_load_dwordx4 v[56:59], v[44:45], off offset:64
	global_load_dwordx4 v[52:55], v[46:47], off offset:64
	global_load_dwordx4 v[48:51], v[108:109], off offset:128
	s_nop 0
	global_load_dwordx4 v[44:47], v[110:111], off offset:128
	global_load_dwordx4 v[88:91], v[112:113], off offset:128
	s_nop 7
	v_mov_b32_e32 v132, 1.0
	s_nop 7
	v_mov_b32_e32 v133, 1.0
	s_nop 7
	v_or_b32_e32 v1, 60, v143
	ds_read2_b32 v[136:137], v145 offset0:18 offset1:19
	s_nop 7
	s_nop 1
	s_nop 7
	s_nop 1
	s_nop 7
	v_mov_b32_e32 v147, v84
	s_nop 7
	s_nop 0
	s_nop 7
	s_nop 0
	s_nop 7
	s_nop 0
	s_nop 7
	s_nop 0
	s_nop 7
	s_nop 1
	s_nop 7
	s_nop 1
	s_nop 7
	s_nop 1
	s_nop 7
	v_mov_b32_e32 v149, v85
	s_nop 7
	s_nop 0
	s_nop 7
	s_nop 0
	s_nop 7
	v_mov_b32_e32 v130, 1.0
	s_nop 7
	v_mov_b32_e32 v131, 1.0
	s_nop 7
	s_nop 1
	s_nop 7
	s_nop 1
	s_nop 7
	s_nop 1
	s_nop 7
	v_mov_b32_e32 v2, v86
	s_nop 7
	s_nop 0
	s_nop 7
	s_nop 0
	s_nop 7
	s_nop 0
	s_nop 7
	s_nop 0
	s_nop 7
	v_mov_b32_e32 v128, 1.0
	s_nop 7
	v_mov_b32_e32 v129, 1.0
	s_nop 7
	v_mfma_f32_16x16x32_bf16 v[122:125], v[72:75], v[16:19], 0
	s_nop 0
	s_nop 7
	v_mfma_f32_16x16x32_bf16 v[124:127], v[80:83], v[32:35], v[122:125]
	s_nop 0
	s_nop 7
	s_nop 1
	s_nop 7
	v_mov_b32_e32 v148, v87
	v_mfma_f32_16x16x32_bf16 v[84:87], v[68:71], v[16:19], 0
	v_mfma_f32_16x16x32_bf16 v[84:87], v[76:79], v[32:35], v[84:87]
	s_nop 7
	v_add_f32_e32 v84, v40, v84
	v_mul_f32_e32 v84, 0xbfb8aa3b, v84
	v_exp_f32_e32 v84, v84
	v_add_f32_e32 v85, v41, v85
	v_mul_f32_e32 v85, 0xbfb8aa3b, v85
	v_exp_f32_e32 v85, v85
	v_add_f32_e32 v84, 1.0, v84
	v_rcp_f32_e32 v93, v84
	v_add_f32_e32 v84, v36, v124
	v_add_f32_e32 v85, 1.0, v85
	v_mul_f32_e32 v84, 0xbfb8aa3b, v84
	v_mul_f32_e32 v93, 0xc1000000, v93
	v_mul_f32_e32 v93, v147, v93
	v_mul_f32_e32 v93, 0x3fb8aa3b, v93
	v_exp_f32_e32 v94, v93
	v_exp_f32_e32 v84, v84
	v_mov_b32_e32 v124, 1.0
	v_add_f32_e32 v86, v42, v86
	v_fma_f32 v93, -v94, v94, 1.0
	v_sqrt_f32_e32 v122, v93
	v_rcp_f32_e32 v93, v85
	v_add_f32_e32 v85, v37, v125
	v_mul_f32_e32 v85, 0xbfb8aa3b, v85
	v_exp_f32_e32 v85, v85
	v_mul_f32_e32 v93, 0xc1000000, v93
	v_mul_f32_e32 v93, v149, v93
	v_mul_f32_e32 v93, 0x3fb8aa3b, v93
	v_exp_f32_e32 v95, v93
	v_add_f32_e32 v84, 1.0, v84
	v_add_f32_e32 v85, 1.0, v85
	v_rcp_f32_e32 v84, v84
	v_fma_f32 v93, -v95, v95, 1.0
	v_sqrt_f32_e32 v123, v93
	ds_read2_b32 v[92:93], v145 offset0:16 offset1:17
	v_rcp_f32_e32 v85, v85
	v_mov_b32_e32 v125, 1.0
	v_mov_b32_dpp v124, v94 row_shr:1 row_mask:0xf bank_mask:0xf
	v_mul_f32_e32 v86, 0xbfb8aa3b, v86
	s_waitcnt lgkmcnt(0)
	v_pk_mul_f32 v[84:85], v[92:93], v[84:85]
	v_mov_b32_dpp v125, v95 row_shr:1 row_mask:0xf bank_mask:0xf
	v_pk_mul_f32 v[84:85], v[84:85], v[122:123]
	v_pk_mul_f32 v[124:125], v[94:95], v[124:125]
	v_exp_f32_e32 v86, v86
	v_mov_b32_dpp v92, v84 row_shr:1 row_mask:0xf bank_mask:0xf bound_ctrl:1
	v_mov_b32_dpp v93, v85 row_shr:1 row_mask:0xf bank_mask:0xf bound_ctrl:1
	v_pk_fma_f32 v[84:85], v[94:95], v[92:93], v[84:85]
	v_mov_b32_dpp v128, v124 row_shr:2 row_mask:0xf bank_mask:0xf
	v_mov_b32_dpp v129, v125 row_shr:2 row_mask:0xf bank_mask:0xf
	v_mov_b32_dpp v92, v84 row_shr:2 row_mask:0xf bank_mask:0xf bound_ctrl:1
	v_mov_b32_dpp v93, v85 row_shr:2 row_mask:0xf bank_mask:0xf bound_ctrl:1
	v_pk_fma_f32 v[84:85], v[124:125], v[92:93], v[84:85]
	v_pk_mul_f32 v[128:129], v[124:125], v[128:129]
	v_add_f32_e32 v86, 1.0, v86
	v_mov_b32_dpp v92, v84 row_shr:4 row_mask:0xf bank_mask:0xf bound_ctrl:1
	v_mov_b32_dpp v93, v85 row_shr:4 row_mask:0xf bank_mask:0xf bound_ctrl:1
	v_mov_b32_dpp v130, v128 row_shr:4 row_mask:0xf bank_mask:0xf
	v_mov_b32_dpp v131, v129 row_shr:4 row_mask:0xf bank_mask:0xf
	v_pk_fma_f32 v[84:85], v[128:129], v[92:93], v[84:85]
	v_pk_mul_f32 v[130:131], v[128:129], v[130:131]
	v_add_f32_e32 v87, v43, v87
	v_mov_b32_dpp v92, v84 row_shr:8 row_mask:0xf bank_mask:0xf bound_ctrl:1
	v_mov_b32_dpp v93, v85 row_shr:8 row_mask:0xf bank_mask:0xf bound_ctrl:1
	v_pk_fma_f32 v[84:85], v[130:131], v[92:93], v[84:85]
	v_rcp_f32_e32 v92, v86
	v_mul_f32_e32 v87, 0xbfb8aa3b, v87
	v_exp_f32_e32 v87, v87
	v_add_f32_e32 v86, v38, v126
	v_mul_f32_e32 v92, 0xc1000000, v92
	v_mul_f32_e32 v92, v2, v92
	v_mul_f32_e32 v92, 0x3fb8aa3b, v92
	v_exp_f32_e32 v92, v92
	v_add_f32_e32 v87, 1.0, v87
	v_mul_f32_e32 v86, 0xbfb8aa3b, v86
	v_exp_f32_e32 v86, v86
	v_fma_f32 v93, -v92, v92, 1.0
	v_sqrt_f32_e32 v94, v93
	v_rcp_f32_e32 v93, v87
	v_add_f32_e32 v87, v39, v127
	v_mul_f32_e32 v87, 0xbfb8aa3b, v87
	v_exp_f32_e32 v87, v87
	v_mul_f32_e32 v93, 0xc1000000, v93
	v_mul_f32_e32 v93, v148, v93
	v_mul_f32_e32 v93, 0x3fb8aa3b, v93
	v_exp_f32_e32 v93, v93
	v_add_f32_e32 v86, 1.0, v86
	v_add_f32_e32 v87, 1.0, v87
	v_rcp_f32_e32 v86, v86
	v_rcp_f32_e32 v87, v87
	v_fma_f32 v95, -v93, v93, 1.0
	v_sqrt_f32_e32 v95, v95
	v_mov_b32_e32 v122, 1.0
	v_pk_mul_f32 v[86:87], v[86:87], v[136:137]
	v_mov_b32_e32 v123, 1.0
	v_pk_mul_f32 v[86:87], v[94:95], v[86:87]
	v_mov_b32_dpp v122, v92 row_shr:1 row_mask:0xf bank_mask:0xf
	v_mov_b32_dpp v123, v93 row_shr:1 row_mask:0xf bank_mask:0xf
	v_mov_b32_dpp v94, v86 row_shr:1 row_mask:0xf bank_mask:0xf bound_ctrl:1
	v_mov_b32_dpp v95, v87 row_shr:1 row_mask:0xf bank_mask:0xf bound_ctrl:1
	v_pk_mul_f32 v[122:123], v[92:93], v[122:123]
; __device__ __forceinline__ unsigned pk2(float lo, float hi) { const f32x2_t v = {lo, hi}; const bf16x2_t b = __builtin_convertvector(v, bf16x2_t); return __builtin_bit_cast(unsigned, b); }
; __device__ __forceinline__ float sigmoidf_(float x) { return __builtin_amdgcn_rcpf(1.0f + __expf(-x)); }
; __device__ __forceinline__ float bcast15(float v, int lane) { return bperm_f((lane & 48) | 15, v); }
; __device__ __forceinline__ void w_lru_m1(const Args& a, int l, unsigned char* ws, const bf16_t* proj, bf16_t* y, LAS unsigned char* wl, int b, int ck_, int h, int lane) {
;     ...
;         for (int tb = 0; tb < 4; ++tb) { const int tok = 16 * tb + lo;
;             f32x4 ga = {0.f, 0.f, 0.f, 0.f}, gx = {0.f, 0.f, 0.f, 0.f};
; #pragma unroll
;             for (int kk = 0; kk < 2; ++kk) { ga = __builtin_amdgcn_mfma_f32_16x16x32_bf16(WaF[kk], Xf[tb][kk], ga, 0, 0, 0); gx = __builtin_amdgcn_mfma_f32_16x16x32_bf16(WxF[kk], Xf[tb][kk], gx, 0, 0, 0); }
;             float hv[4], pv[4];
; #pragma unroll
;             for (int r = 0; r < 4; ++r) {
;                 const float rg = sigmoidf_(ga[r] + bav[r]), ig = sigmoidf_(gx[r] + bxv[r]);
;                 const float la = -8.0f * rg * sp[r]; float A = __expf(la);
;                 float U = __builtin_amdgcn_sqrtf(1.0f - A * A) * (ig * xcf[tok * 65 + j0 + r]);
;                 { const float As = dpp_shr1<1>(A), Us = dpp_shr0<1>(U); U = A * Us + U; A = A * As; }
;                 { const float As = dpp_shr1<2>(A), Us = dpp_shr0<2>(U); U = A * Us + U; A = A * As; }
;                 { const float As = dpp_shr1<4>(A), Us = dpp_shr0<4>(U); U = A * Us + U; A = A * As; }
;                 { const float As = dpp_shr1<8>(A), Us = dpp_shr0<8>(U); U = A * Us + U; A = A * As; }
;                 const float hh = U + A * hc[r], PP = A * Pc[r];
;                 hc[r] = bcast15(hh, lane); Pc[r] = bcast15(PP, lane); hv[r] = hh; pv[r] = PP; }
;             *(unsigned long long*)(y + (size_t)(row0 + tok) * DM + 64 * h + j0) = (unsigned long long)pk2(hv[0], hv[1]) | ((unsigned long long)pk2(hv[2], hv[3]) << 32);
;             *(unsigned long long*)((bf16_t*)(ws + WS_P) + (size_t)(row0 + tok) * 512 + 64 * h + j0) = (unsigned long long)pk2(pv[0], pv[1]) | ((unsigned long long)pk2(pv[2], pv[3]) << 32);
;         }
	v_mov_b32_e32 v126, 1.0
	v_mov_b32_e32 v127, 1.0
	v_pk_fma_f32 v[86:87], v[92:93], v[94:95], v[86:87]
	v_mov_b32_dpp v126, v122 row_shr:2 row_mask:0xf bank_mask:0xf
	v_mov_b32_dpp v127, v123 row_shr:2 row_mask:0xf bank_mask:0xf
	v_mov_b32_dpp v92, v86 row_shr:2 row_mask:0xf bank_mask:0xf bound_ctrl:1
	v_mov_b32_dpp v93, v87 row_shr:2 row_mask:0xf bank_mask:0xf bound_ctrl:1
	v_pk_mul_f32 v[126:127], v[122:123], v[126:127]
	v_mov_b32_e32 v128, 1.0
	v_mov_b32_e32 v129, 1.0
	v_pk_fma_f32 v[86:87], v[122:123], v[92:93], v[86:87]
	v_mov_b32_dpp v132, v130 row_shr:8 row_mask:0xf bank_mask:0xf
	v_mov_b32_dpp v133, v131 row_shr:8 row_mask:0xf bank_mask:0xf
	v_mov_b32_dpp v128, v126 row_shr:4 row_mask:0xf bank_mask:0xf
	v_mov_b32_dpp v129, v127 row_shr:4 row_mask:0xf bank_mask:0xf
	v_mov_b32_dpp v92, v86 row_shr:4 row_mask:0xf bank_mask:0xf bound_ctrl:1
	v_mov_b32_dpp v93, v87 row_shr:4 row_mask:0xf bank_mask:0xf bound_ctrl:1
	v_pk_mul_f32 v[134:135], v[130:131], v[132:133]
	v_pk_mul_f32 v[128:129], v[126:127], v[128:129]
	v_mov_b32_e32 v130, 1.0
	v_mov_b32_e32 v131, 1.0
	v_pk_fma_f32 v[86:87], v[126:127], v[92:93], v[86:87]
	v_mov_b32_dpp v130, v128 row_shr:8 row_mask:0xf bank_mask:0xf
	v_mov_b32_dpp v131, v129 row_shr:8 row_mask:0xf bank_mask:0xf
	v_mov_b32_dpp v92, v86 row_shr:8 row_mask:0xf bank_mask:0xf bound_ctrl:1
	v_mov_b32_dpp v93, v87 row_shr:8 row_mask:0xf bank_mask:0xf bound_ctrl:1
	v_pk_mul_f32 v[130:131], v[128:129], v[130:131]
	v_pk_fma_f32 v[86:87], v[128:129], v[92:93], v[86:87]
	v_pk_fma_f32 v[84:85], v[134:135], 0, v[84:85] op_sel_hi:[1,0,1]
	v_pk_fma_f32 v[86:87], v[130:131], 0, v[86:87] op_sel_hi:[1,0,1]
	ds_bpermute_b32 v124, v1, v84
	ds_bpermute_b32 v125, v1, v85
	v_cvt_pk_bf16_f32 v84, v84, v85
	v_cvt_pk_bf16_f32 v85, v86, v87
	global_store_dwordx2 v[100:101], v[84:85], off offset:32
	v_cvt_pk_bf16_f32 v84, v134, v135
	v_cvt_pk_bf16_f32 v85, v130, v131
	ds_bpermute_b32 v122, v1, v86
	ds_bpermute_b32 v123, v1, v87
	global_store_dwordx2 v[102:103], v[84:85], off offset:32
	v_mfma_f32_16x16x32_bf16 v[84:87], v[68:71], v[12:15], 0
	ds_bpermute_b32 v132, v1, v130
	ds_bpermute_b32 v133, v1, v131
	ds_bpermute_b32 v150, v1, v134
	v_mfma_f32_16x16x32_bf16 v[126:129], v[72:75], v[12:15], 0
	ds_bpermute_b32 v151, v1, v135
	v_mfma_f32_16x16x32_bf16 v[92:95], v[76:79], v[28:31], v[84:87]
	v_mfma_f32_16x16x32_bf16 v[84:87], v[80:83], v[28:31], v[126:129]
	s_nop 6
	v_add_f32_e32 v92, v40, v92
	v_mul_f32_e32 v92, 0xbfb8aa3b, v92
	v_exp_f32_e32 v92, v92
	v_add_f32_e32 v84, v36, v84
	v_mul_f32_e32 v84, 0xbfb8aa3b, v84
	v_exp_f32_e32 v84, v84
	v_add_f32_e32 v92, 1.0, v92
	v_rcp_f32_e32 v92, v92
	v_add_f32_e32 v85, v37, v85
	v_add_f32_e32 v84, 1.0, v84
	v_rcp_f32_e32 v126, v84
	v_mul_f32_e32 v84, 0xc1000000, v92
	v_add_f32_e32 v92, v41, v93
	v_mul_f32_e32 v92, 0xbfb8aa3b, v92
	v_exp_f32_e32 v92, v92
	v_mul_f32_e32 v85, 0xbfb8aa3b, v85
	v_exp_f32_e32 v85, v85
	v_mul_f32_e32 v84, v147, v84
	v_add_f32_e32 v92, 1.0, v92
	v_rcp_f32_e32 v92, v92
	v_add_f32_e32 v85, 1.0, v85
	v_rcp_f32_e32 v127, v85
	v_mul_f32_e32 v84, 0x3fb8aa3b, v84
	v_mul_f32_e32 v85, 0xc1000000, v92
	v_mul_f32_e32 v85, v149, v85
	v_mul_f32_e32 v85, 0x3fb8aa3b, v85
	v_exp_f32_e32 v128, v84
	v_exp_f32_e32 v129, v85
	v_add_f32_e32 v94, v42, v94
	v_add_f32_e32 v95, v43, v95
	v_fma_f32 v84, -v128, v128, 1.0
	v_fma_f32 v85, -v129, v129, 1.0
	v_sqrt_f32_e32 v130, v84
	v_mov_b32_e32 v84, 1.0
	v_sqrt_f32_e32 v131, v85
	v_mov_b32_e32 v85, 1.0
	v_mov_b32_dpp v84, v128 row_shr:1 row_mask:0xf bank_mask:0xf
	v_mul_f32_e32 v94, 0xbfb8aa3b, v94
	v_mov_b32_dpp v85, v129 row_shr:1 row_mask:0xf bank_mask:0xf
	v_pk_mul_f32 v[134:135], v[128:129], v[84:85]
	v_mov_b32_e32 v84, 1.0
	v_mov_b32_e32 v85, 1.0
	v_mul_f32_e32 v95, 0xbfb8aa3b, v95
	v_mov_b32_dpp v84, v134 row_shr:2 row_mask:0xf bank_mask:0xf
	v_mov_b32_dpp v85, v135 row_shr:2 row_mask:0xf bank_mask:0xf
	v_pk_mul_f32 v[136:137], v[134:135], v[84:85]
	v_mov_b32_e32 v84, 1.0
	v_mov_b32_e32 v85, 1.0
	v_exp_f32_e32 v94, v94
	v_mov_b32_dpp v84, v136 row_shr:4 row_mask:0xf bank_mask:0xf
	v_mov_b32_dpp v85, v137 row_shr:4 row_mask:0xf bank_mask:0xf
	v_pk_mul_f32 v[138:139], v[136:137], v[84:85]
	v_mov_b32_e32 v84, 1.0
	v_mov_b32_e32 v85, 1.0
	v_exp_f32_e32 v95, v95
	v_mov_b32_dpp v84, v138 row_shr:8 row_mask:0xf bank_mask:0xf
	v_mov_b32_dpp v85, v139 row_shr:8 row_mask:0xf bank_mask:0xf
	v_pk_mul_f32 v[140:141], v[138:139], v[84:85]
	v_add_u32_e32 v85, 0x1080, v145
	ds_read2_b32 v[142:143], v85 offset1:1
	v_add_f32_e32 v86, v38, v86
	v_add_f32_e32 v87, v39, v87
	v_mul_f32_e32 v86, 0xbfb8aa3b, v86
	v_mul_f32_e32 v87, 0xbfb8aa3b, v87
	s_waitcnt lgkmcnt(0)
	v_pk_mul_f32 v[126:127], v[142:143], v[126:127]
	v_add_f32_e32 v94, 1.0, v94
	v_pk_mul_f32 v[126:127], v[126:127], v[130:131]
	v_exp_f32_e32 v86, v86
	v_add_f32_e32 v95, 1.0, v95
	v_mov_b32_dpp v130, v126 row_shr:1 row_mask:0xf bank_mask:0xf bound_ctrl:1
	v_mov_b32_dpp v131, v127 row_shr:1 row_mask:0xf bank_mask:0xf bound_ctrl:1
	v_pk_fma_f32 v[126:127], v[128:129], v[130:131], v[126:127]
	v_exp_f32_e32 v87, v87
	v_rcp_f32_e32 v94, v94
	v_mov_b32_dpp v128, v126 row_shr:2 row_mask:0xf bank_mask:0xf bound_ctrl:1
	v_mov_b32_dpp v129, v127 row_shr:2 row_mask:0xf bank_mask:0xf bound_ctrl:1
	v_pk_fma_f32 v[126:127], v[134:135], v[128:129], v[126:127]
	v_rcp_f32_e32 v95, v95
	v_add_f32_e32 v86, 1.0, v86
	v_mov_b32_dpp v128, v126 row_shr:4 row_mask:0xf bank_mask:0xf bound_ctrl:1
	v_mov_b32_dpp v129, v127 row_shr:4 row_mask:0xf bank_mask:0xf bound_ctrl:1
	v_pk_fma_f32 v[126:127], v[136:137], v[128:129], v[126:127]
	v_add_f32_e32 v87, 1.0, v87
	v_pk_mul_f32 v[92:93], v[140:141], v[150:151]
	v_mov_b32_dpp v128, v126 row_shr:8 row_mask:0xf bank_mask:0xf bound_ctrl:1
	v_mov_b32_dpp v129, v127 row_shr:8 row_mask:0xf bank_mask:0xf bound_ctrl:1
	v_pk_fma_f32 v[126:127], v[138:139], v[128:129], v[126:127]
	v_rcp_f32_e32 v128, v86
	v_mul_f32_e32 v86, 0xc1000000, v94
	v_rcp_f32_e32 v129, v87
	v_mul_f32_e32 v87, 0xc1000000, v95
	v_mul_f32_e32 v86, v2, v86
	v_mul_f32_e32 v87, v148, v87
	v_mul_f32_e32 v86, 0x3fb8aa3b, v86
	v_mul_f32_e32 v87, 0x3fb8aa3b, v87
	v_exp_f32_e32 v94, v86
	v_exp_f32_e32 v95, v87
	v_pk_fma_f32 v[126:127], v[140:141], v[124:125], v[126:127]
	ds_bpermute_b32 v84, v1, v92
	v_fma_f32 v86, -v94, v94, 1.0
	v_fma_f32 v87, -v95, v95, 1.0
	v_sqrt_f32_e32 v130, v86
	v_mov_b32_e32 v86, 1.0
	v_sqrt_f32_e32 v131, v87
	v_mov_b32_e32 v87, 1.0
	v_mov_b32_dpp v86, v94 row_shr:1 row_mask:0xf bank_mask:0xf
	ds_bpermute_b32 v124, v1, v126
	v_mov_b32_dpp v87, v95 row_shr:1 row_mask:0xf bank_mask:0xf
	v_pk_mul_f32 v[134:135], v[94:95], v[86:87]
	v_mov_b32_e32 v86, 1.0
	v_mov_b32_e32 v87, 1.0
	ds_bpermute_b32 v125, v1, v127
	v_mov_b32_dpp v86, v134 row_shr:2 row_mask:0xf bank_mask:0xf
	v_mov_b32_dpp v87, v135 row_shr:2 row_mask:0xf bank_mask:0xf
	v_pk_mul_f32 v[136:137], v[134:135], v[86:87]
	v_mov_b32_e32 v86, 1.0
	v_mov_b32_e32 v87, 1.0
	ds_bpermute_b32 v85, v1, v93
	v_mov_b32_dpp v86, v136 row_shr:4 row_mask:0xf bank_mask:0xf
	v_mov_b32_dpp v87, v137 row_shr:4 row_mask:0xf bank_mask:0xf
	v_pk_mul_f32 v[138:139], v[136:137], v[86:87]
	v_mov_b32_e32 v86, 1.0
	v_mov_b32_e32 v87, 1.0
	v_cvt_pk_bf16_f32 v126, v126, v127
	v_mov_b32_dpp v86, v138 row_shr:8 row_mask:0xf bank_mask:0xf
	v_mov_b32_dpp v87, v139 row_shr:8 row_mask:0xf bank_mask:0xf
	v_pk_mul_f32 v[140:141], v[138:139], v[86:87]
	v_add_u32_e32 v87, 0x1088, v145
	ds_read2_b32 v[142:143], v87 offset1:1
	v_pk_mul_f32 v[132:133], v[140:141], v[132:133]
	v_cvt_pk_bf16_f32 v92, v92, v93
	v_cvt_pk_bf16_f32 v93, v132, v133
	ds_bpermute_b32 v86, v1, v132
	s_waitcnt lgkmcnt(0)
	v_pk_mul_f32 v[128:129], v[128:129], v[142:143]
	ds_bpermute_b32 v87, v1, v133
	v_pk_mul_f32 v[128:129], v[130:131], v[128:129]
	s_nop 1
	v_mov_b32_dpp v130, v128 row_shr:1 row_mask:0xf bank_mask:0xf bound_ctrl:1
	v_mov_b32_dpp v131, v129 row_shr:1 row_mask:0xf bank_mask:0xf bound_ctrl:1
	v_pk_fma_f32 v[94:95], v[94:95], v[130:131], v[128:129]
	s_nop 1
	v_mov_b32_dpp v128, v94 row_shr:2 row_mask:0xf bank_mask:0xf bound_ctrl:1
	v_mov_b32_dpp v129, v95 row_shr:2 row_mask:0xf bank_mask:0xf bound_ctrl:1
	v_pk_fma_f32 v[94:95], v[134:135], v[128:129], v[94:95]
	s_nop 1
	v_mov_b32_dpp v128, v94 row_shr:4 row_mask:0xf bank_mask:0xf bound_ctrl:1
	v_mov_b32_dpp v129, v95 row_shr:4 row_mask:0xf bank_mask:0xf bound_ctrl:1
	v_pk_fma_f32 v[94:95], v[136:137], v[128:129], v[94:95]
	s_nop 1
	v_mov_b32_dpp v128, v94 row_shr:8 row_mask:0xf bank_mask:0xf bound_ctrl:1
	v_mov_b32_dpp v129, v95 row_shr:8 row_mask:0xf bank_mask:0xf bound_ctrl:1
	v_pk_fma_f32 v[94:95], v[138:139], v[128:129], v[94:95]
	s_nop 0
	v_pk_fma_f32 v[94:95], v[140:141], v[122:123], v[94:95]
	ds_bpermute_b32 v122, v1, v94
	v_cvt_pk_bf16_f32 v127, v94, v95
	ds_bpermute_b32 v123, v1, v95
	global_store_dwordx2 v[104:105], v[126:127], off offset:32
	global_store_dwordx2 v[106:107], v[92:93], off offset:32
	v_mfma_f32_16x16x32_bf16 v[92:95], v[68:71], v[8:11], 0
	v_mfma_f32_16x16x32_bf16 v[130:133], v[76:79], v[24:27], v[92:95]
	v_mfma_f32_16x16x32_bf16 v[126:129], v[72:75], v[8:11], 0
	v_mfma_f32_16x16x32_bf16 v[134:137], v[80:83], v[24:27], v[126:129]
	s_nop 5
	v_add_f32_e32 v92, v40, v130
	v_mul_f32_e32 v92, 0xbfb8aa3b, v92
	v_exp_f32_e32 v92, v92
	v_mov_b32_e32 v126, 1.0
	v_mfma_f32_16x16x32_bf16 v[68:71], v[68:71], v[4:7], 0
	v_add_f32_e32 v92, 1.0, v92
	v_rcp_f32_e32 v93, v92
	v_add_f32_e32 v92, v36, v134
	v_mul_f32_e32 v92, 0xbfb8aa3b, v92
	v_exp_f32_e32 v92, v92
	v_mul_f32_e32 v93, 0xc1000000, v93
	v_mul_f32_e32 v93, v147, v93
	v_mul_f32_e32 v93, 0x3fb8aa3b, v93
	v_exp_f32_e32 v94, v93
	v_add_f32_e32 v92, 1.0, v92
	v_rcp_f32_e32 v92, v92
	v_fma_f32 v93, -v94, v94, 1.0
	v_sqrt_f32_e32 v130, v93
	v_add_f32_e32 v93, v41, v131
	v_mul_f32_e32 v93, 0xbfb8aa3b, v93
	v_exp_f32_e32 v93, v93
	v_mov_b32_dpp v126, v94 row_shr:1 row_mask:0xf bank_mask:0xf
	v_add_f32_e32 v93, 1.0, v93
	v_rcp_f32_e32 v95, v93
	v_add_f32_e32 v93, v37, v135
	v_mul_f32_e32 v93, 0xbfb8aa3b, v93
	v_exp_f32_e32 v93, v93
	v_mul_f32_e32 v95, 0xc1000000, v95
	v_mul_f32_e32 v95, v149, v95
	v_mul_f32_e32 v95, 0x3fb8aa3b, v95
	v_exp_f32_e32 v95, v95
	v_add_f32_e32 v93, 1.0, v93
	v_rcp_f32_e32 v93, v93
	v_fma_f32 v127, -v95, v95, 1.0
	v_sqrt_f32_e32 v131, v127
	v_mov_b32_e32 v127, 1.0
	s_nop 1
	v_mov_b32_dpp v127, v95 row_shr:1 row_mask:0xf bank_mask:0xf
	v_pk_mul_f32 v[134:135], v[94:95], v[126:127]
	v_mov_b32_e32 v126, 1.0
	v_mov_b32_e32 v127, 1.0
	s_nop 0
	v_mov_b32_dpp v126, v134 row_shr:2 row_mask:0xf bank_mask:0xf
	v_mov_b32_dpp v127, v135 row_shr:2 row_mask:0xf bank_mask:0xf
	v_pk_mul_f32 v[138:139], v[134:135], v[126:127]
	v_mov_b32_e32 v126, 1.0
	v_mov_b32_e32 v127, 1.0
	s_nop 0
	v_mov_b32_dpp v126, v138 row_shr:4 row_mask:0xf bank_mask:0xf
	v_mov_b32_dpp v127, v139 row_shr:4 row_mask:0xf bank_mask:0xf
	v_pk_mul_f32 v[140:141], v[138:139], v[126:127]
	v_mov_b32_e32 v126, 1.0
	v_mov_b32_e32 v127, 1.0
	s_nop 0
	v_mov_b32_dpp v126, v140 row_shr:8 row_mask:0xf bank_mask:0xf
	v_mov_b32_dpp v127, v141 row_shr:8 row_mask:0xf bank_mask:0xf
	v_pk_mul_f32 v[142:143], v[140:141], v[126:127]
	s_nop 0
	v_pk_mul_f32 v[128:129], v[142:143], v[84:85]
	v_add_u32_e32 v84, 0x20c0, v145
	ds_read2_b32 v[84:85], v84 offset1:1
	ds_bpermute_b32 v126, v1, v128
	ds_bpermute_b32 v127, v1, v129
	s_waitcnt lgkmcnt(0)
	v_pk_mul_f32 v[84:85], v[84:85], v[92:93]
	s_nop 0
	v_pk_mul_f32 v[84:85], v[84:85], v[130:131]
	s_nop 1
	v_mov_b32_dpp v92, v84 row_shr:1 row_mask:0xf bank_mask:0xf bound_ctrl:1
	v_mov_b32_dpp v93, v85 row_shr:1 row_mask:0xf bank_mask:0xf bound_ctrl:1
	v_pk_fma_f32 v[84:85], v[94:95], v[92:93], v[84:85]
	s_nop 1
	v_mov_b32_dpp v92, v84 row_shr:2 row_mask:0xf bank_mask:0xf bound_ctrl:1
	v_mov_b32_dpp v93, v85 row_shr:2 row_mask:0xf bank_mask:0xf bound_ctrl:1
	v_pk_fma_f32 v[84:85], v[134:135], v[92:93], v[84:85]
	s_nop 1
	v_mov_b32_dpp v92, v84 row_shr:4 row_mask:0xf bank_mask:0xf bound_ctrl:1
	v_mov_b32_dpp v93, v85 row_shr:4 row_mask:0xf bank_mask:0xf bound_ctrl:1
	v_pk_fma_f32 v[84:85], v[138:139], v[92:93], v[84:85]
	s_nop 1
	v_mov_b32_dpp v92, v84 row_shr:8 row_mask:0xf bank_mask:0xf bound_ctrl:1
	v_mov_b32_dpp v93, v85 row_shr:8 row_mask:0xf bank_mask:0xf bound_ctrl:1
	v_pk_fma_f32 v[84:85], v[140:141], v[92:93], v[84:85]
	v_mov_b32_e32 v92, 1.0
	v_pk_fma_f32 v[124:125], v[142:143], v[124:125], v[84:85]
	v_add_f32_e32 v84, v42, v132
	v_mul_f32_e32 v84, 0xbfb8aa3b, v84
	v_exp_f32_e32 v84, v84
	ds_bpermute_b32 v94, v1, v124
	ds_bpermute_b32 v95, v1, v125
	v_cvt_pk_bf16_f32 v124, v124, v125
	v_add_f32_e32 v84, 1.0, v84
	v_rcp_f32_e32 v85, v84
	v_add_f32_e32 v84, v38, v136
	v_mul_f32_e32 v84, 0xbfb8aa3b, v84
	v_exp_f32_e32 v84, v84
	v_mul_f32_e32 v85, 0xc1000000, v85
	v_mul_f32_e32 v85, v2, v85
	v_mul_f32_e32 v85, 0x3fb8aa3b, v85
	v_exp_f32_e32 v130, v85
	v_add_f32_e32 v84, 1.0, v84
	v_rcp_f32_e32 v84, v84
	v_fma_f32 v85, -v130, v130, 1.0
	v_sqrt_f32_e32 v132, v85
	v_add_f32_e32 v85, v43, v133
	v_mul_f32_e32 v85, 0xbfb8aa3b, v85
	v_exp_f32_e32 v85, v85
	v_mov_b32_dpp v92, v130 row_shr:1 row_mask:0xf bank_mask:0xf
	v_add_f32_e32 v85, 1.0, v85
	v_rcp_f32_e32 v93, v85
	v_add_f32_e32 v85, v39, v137
	v_mul_f32_e32 v85, 0xbfb8aa3b, v85
	v_exp_f32_e32 v85, v85
	v_mul_f32_e32 v93, 0xc1000000, v93
	v_mul_f32_e32 v93, v148, v93
	v_mul_f32_e32 v93, 0x3fb8aa3b, v93
	v_exp_f32_e32 v131, v93
	v_add_f32_e32 v85, 1.0, v85
	v_rcp_f32_e32 v85, v85
	v_fma_f32 v93, -v131, v131, 1.0
	v_sqrt_f32_e32 v133, v93
	v_mov_b32_e32 v93, 1.0
	s_nop 1
	v_mov_b32_dpp v93, v131 row_shr:1 row_mask:0xf bank_mask:0xf
	v_pk_mul_f32 v[134:135], v[130:131], v[92:93]
	v_mov_b32_e32 v92, 1.0
	v_mov_b32_e32 v93, 1.0
	s_nop 0
	v_mov_b32_dpp v92, v134 row_shr:2 row_mask:0xf bank_mask:0xf
	v_mov_b32_dpp v93, v135 row_shr:2 row_mask:0xf bank_mask:0xf
	v_pk_mul_f32 v[136:137], v[134:135], v[92:93]
	v_mov_b32_e32 v92, 1.0
	v_mov_b32_e32 v93, 1.0
	s_nop 0
	v_mov_b32_dpp v92, v136 row_shr:4 row_mask:0xf bank_mask:0xf
	v_mov_b32_dpp v93, v137 row_shr:4 row_mask:0xf bank_mask:0xf
	v_pk_mul_f32 v[138:139], v[136:137], v[92:93]
	v_mov_b32_e32 v92, 1.0
	v_mov_b32_e32 v93, 1.0
	s_nop 0
	v_mov_b32_dpp v92, v138 row_shr:8 row_mask:0xf bank_mask:0xf
	v_mov_b32_dpp v93, v139 row_shr:8 row_mask:0xf bank_mask:0xf
	v_pk_mul_f32 v[140:141], v[138:139], v[92:93]
	v_add_u32_e32 v93, 0x20c8, v145
	ds_read2_b32 v[142:143], v93 offset1:1
	v_pk_mul_f32 v[86:87], v[140:141], v[86:87]
	ds_bpermute_b32 v92, v1, v86
	ds_bpermute_b32 v93, v1, v87
	s_waitcnt lgkmcnt(0)
	v_pk_mul_f32 v[84:85], v[84:85], v[142:143]
	s_nop 0
	v_pk_mul_f32 v[84:85], v[132:133], v[84:85]
	s_nop 1
	v_mov_b32_dpp v132, v84 row_shr:1 row_mask:0xf bank_mask:0xf bound_ctrl:1
	v_mov_b32_dpp v133, v85 row_shr:1 row_mask:0xf bank_mask:0xf bound_ctrl:1
	v_pk_fma_f32 v[84:85], v[130:131], v[132:133], v[84:85]
	s_nop 1
	v_mov_b32_dpp v130, v84 row_shr:2 row_mask:0xf bank_mask:0xf bound_ctrl:1
	v_mov_b32_dpp v131, v85 row_shr:2 row_mask:0xf bank_mask:0xf bound_ctrl:1
	v_pk_fma_f32 v[84:85], v[134:135], v[130:131], v[84:85]
	s_nop 1
	v_mov_b32_dpp v130, v84 row_shr:4 row_mask:0xf bank_mask:0xf bound_ctrl:1
	v_mov_b32_dpp v131, v85 row_shr:4 row_mask:0xf bank_mask:0xf bound_ctrl:1
	v_pk_fma_f32 v[84:85], v[136:137], v[130:131], v[84:85]
	s_nop 1
	v_mov_b32_dpp v130, v84 row_shr:8 row_mask:0xf bank_mask:0xf bound_ctrl:1
	v_mov_b32_dpp v131, v85 row_shr:8 row_mask:0xf bank_mask:0xf bound_ctrl:1
	v_pk_fma_f32 v[84:85], v[138:139], v[130:131], v[84:85]
	s_nop 0
	v_pk_fma_f32 v[122:123], v[140:141], v[122:123], v[84:85]
	ds_bpermute_b32 v84, v1, v122
	ds_bpermute_b32 v85, v1, v123
	v_cvt_pk_bf16_f32 v125, v122, v123
	v_cvt_pk_bf16_f32 v122, v128, v129
	v_cvt_pk_bf16_f32 v123, v86, v87
	global_store_dwordx2 v[96:97], v[124:125], off offset:32
	global_store_dwordx2 v[98:99], v[122:123], off offset:32
	v_mfma_f32_16x16x32_bf16 v[122:125], v[72:75], v[4:7], 0
	v_mfma_f32_16x16x32_bf16 v[72:75], v[76:79], v[20:23], v[68:71]
	v_mfma_f32_16x16x32_bf16 v[68:71], v[80:83], v[20:23], v[122:125]
	s_nop 6
	v_add_f32_e32 v40, v40, v72
	v_add_f32_e32 v41, v41, v73
	v_add_f32_e32 v42, v42, v74
	v_mul_f32_e32 v40, 0xbfb8aa3b, v40
	v_mul_f32_e32 v41, 0xbfb8aa3b, v41
	v_mul_f32_e32 v42, 0xbfb8aa3b, v42
	v_exp_f32_e32 v40, v40
	v_exp_f32_e32 v41, v41
	v_exp_f32_e32 v42, v42
	v_add_f32_e32 v36, v36, v68
	v_add_f32_e32 v37, v37, v69
	v_add_f32_e32 v38, v38, v70
	v_mul_f32_e32 v36, 0xbfb8aa3b, v36
	v_mul_f32_e32 v37, 0xbfb8aa3b, v37
	v_mul_f32_e32 v38, 0xbfb8aa3b, v38
	v_add_f32_e32 v40, 1.0, v40
	v_exp_f32_e32 v36, v36
	v_add_f32_e32 v41, 1.0, v41
	v_exp_f32_e32 v37, v37
	v_add_f32_e32 v42, 1.0, v42
	v_exp_f32_e32 v38, v38
	v_rcp_f32_e32 v72, v40
	v_rcp_f32_e32 v68, v41
	v_rcp_f32_e32 v42, v42
	v_add_f32_e32 v36, 1.0, v36
	v_add_f32_e32 v37, 1.0, v37
	v_add_f32_e32 v38, 1.0, v38
	v_rcp_f32_e32 v40, v36
	v_mul_f32_e32 v36, 0xc1000000, v72
	v_rcp_f32_e32 v41, v37
	v_mul_f32_e32 v37, 0xc1000000, v68
	v_rcp_f32_e32 v70, v38
	v_mul_f32_e32 v38, 0xc1000000, v42
	v_mul_f32_e32 v36, v147, v36
	v_mul_f32_e32 v37, v149, v37
	v_mul_f32_e32 v2, v2, v38
	v_mul_f32_e32 v36, 0x3fb8aa3b, v36
	v_mul_f32_e32 v37, 0x3fb8aa3b, v37
	v_mul_f32_e32 v2, 0x3fb8aa3b, v2
	v_exp_f32_e32 v72, v36
	v_exp_f32_e32 v73, v37
	v_exp_f32_e32 v42, v2
	v_add_f32_e32 v39, v39, v71
	v_fma_f32 v36, -v72, v72, 1.0
	v_fma_f32 v37, -v73, v73, 1.0
	v_fma_f32 v2, -v42, v42, 1.0
	v_sqrt_f32_e32 v76, v36
	v_mov_b32_e32 v36, 1.0
	v_sqrt_f32_e32 v77, v37
	v_mov_b32_e32 v37, 1.0
	v_sqrt_f32_e32 v74, v2
	v_add_f32_e32 v2, v43, v75
	v_mov_b32_dpp v36, v72 row_shr:1 row_mask:0xf bank_mask:0xf
	v_mov_b32_dpp v37, v73 row_shr:1 row_mask:0xf bank_mask:0xf
	v_mul_f32_e32 v2, 0xbfb8aa3b, v2
	v_pk_mul_f32 v[78:79], v[72:73], v[36:37]
	v_mov_b32_e32 v36, 1.0
	v_mov_b32_e32 v37, 1.0
	v_exp_f32_e32 v2, v2
	v_mov_b32_dpp v36, v78 row_shr:2 row_mask:0xf bank_mask:0xf
	v_mov_b32_dpp v37, v79 row_shr:2 row_mask:0xf bank_mask:0xf
	v_pk_mul_f32 v[80:81], v[78:79], v[36:37]
	v_mov_b32_e32 v36, 1.0
	v_mov_b32_e32 v37, 1.0
	v_add_f32_e32 v2, 1.0, v2
	v_mov_b32_dpp v36, v80 row_shr:4 row_mask:0xf bank_mask:0xf
	v_mov_b32_dpp v37, v81 row_shr:4 row_mask:0xf bank_mask:0xf
	v_pk_mul_f32 v[82:83], v[80:81], v[36:37]
	v_mov_b32_e32 v36, 1.0
	v_mov_b32_e32 v37, 1.0
	v_rcp_f32_e32 v2, v2
	v_mov_b32_dpp v36, v82 row_shr:8 row_mask:0xf bank_mask:0xf
	v_mov_b32_dpp v37, v83 row_shr:8 row_mask:0xf bank_mask:0xf
	v_pk_mul_f32 v[86:87], v[82:83], v[36:37]
	v_add_u32_e32 v37, 0x3100, v145
	ds_read2_b32 v[122:123], v37 offset1:1
	v_mul_f32_e32 v39, 0xbfb8aa3b, v39
	v_mul_f32_e32 v2, 0xc1000000, v2
	v_exp_f32_e32 v39, v39
	v_mul_f32_e32 v2, v148, v2
	v_mul_f32_e32 v2, 0x3fb8aa3b, v2
	s_waitcnt lgkmcnt(0)
	v_pk_mul_f32 v[40:41], v[122:123], v[40:41]
	v_exp_f32_e32 v43, v2
	v_pk_mul_f32 v[40:41], v[40:41], v[76:77]
	v_add_f32_e32 v39, 1.0, v39
	v_mov_b32_e32 v38, 1.0
	v_mov_b32_dpp v76, v40 row_shr:1 row_mask:0xf bank_mask:0xf bound_ctrl:1
	v_mov_b32_dpp v77, v41 row_shr:1 row_mask:0xf bank_mask:0xf bound_ctrl:1
	v_pk_fma_f32 v[40:41], v[72:73], v[76:77], v[40:41]
	v_rcp_f32_e32 v71, v39
	v_mov_b32_e32 v39, 1.0
	v_mov_b32_dpp v72, v40 row_shr:2 row_mask:0xf bank_mask:0xf bound_ctrl:1
	v_mov_b32_dpp v73, v41 row_shr:2 row_mask:0xf bank_mask:0xf bound_ctrl:1
	v_mov_b32_dpp v38, v42 row_shr:1 row_mask:0xf bank_mask:0xf
	v_mov_b32_dpp v39, v43 row_shr:1 row_mask:0xf bank_mask:0xf
	v_pk_fma_f32 v[40:41], v[78:79], v[72:73], v[40:41]
	v_pk_mul_f32 v[78:79], v[42:43], v[38:39]
	v_mov_b32_e32 v38, 1.0
	v_mov_b32_e32 v39, 1.0
	v_mov_b32_dpp v72, v40 row_shr:4 row_mask:0xf bank_mask:0xf bound_ctrl:1
	v_mov_b32_dpp v73, v41 row_shr:4 row_mask:0xf bank_mask:0xf bound_ctrl:1
	v_mov_b32_dpp v38, v78 row_shr:2 row_mask:0xf bank_mask:0xf
	v_mov_b32_dpp v39, v79 row_shr:2 row_mask:0xf bank_mask:0xf
	v_pk_fma_f32 v[40:41], v[80:81], v[72:73], v[40:41]
	v_pk_mul_f32 v[80:81], v[78:79], v[38:39]
	v_mov_b32_e32 v38, 1.0
	v_mov_b32_e32 v39, 1.0
	v_mov_b32_dpp v72, v40 row_shr:8 row_mask:0xf bank_mask:0xf bound_ctrl:1
	v_mov_b32_dpp v73, v41 row_shr:8 row_mask:0xf bank_mask:0xf bound_ctrl:1
	v_mov_b32_dpp v38, v80 row_shr:4 row_mask:0xf bank_mask:0xf
	v_mov_b32_dpp v39, v81 row_shr:4 row_mask:0xf bank_mask:0xf
	v_pk_fma_f32 v[40:41], v[82:83], v[72:73], v[40:41]
	v_pk_mul_f32 v[82:83], v[80:81], v[38:39]
	v_mov_b32_e32 v38, 1.0
	v_mov_b32_e32 v39, 1.0
	v_fma_f32 v2, -v43, v43, 1.0
	v_mov_b32_dpp v38, v82 row_shr:8 row_mask:0xf bank_mask:0xf
	v_mov_b32_dpp v39, v83 row_shr:8 row_mask:0xf bank_mask:0xf
	v_pk_mul_f32 v[68:69], v[86:87], v[126:127]
	v_pk_fma_f32 v[72:73], v[86:87], v[94:95], v[40:41]
	v_sqrt_f32_e32 v75, v2
	v_pk_mul_f32 v[86:87], v[82:83], v[38:39]
	v_add_u32_e32 v2, 0x3108, v145
	v_pk_mul_f32 v[76:77], v[86:87], v[92:93]
	ds_read2_b32 v[92:93], v2 offset1:1
	ds_bpermute_b32 v36, v1, v68
	ds_bpermute_b32 v40, v1, v72
	ds_bpermute_b32 v41, v1, v73
	ds_bpermute_b32 v37, v1, v69
	s_waitcnt lgkmcnt(0)
	v_pk_mul_f32 v[70:71], v[70:71], v[92:93]
	ds_bpermute_b32 v38, v1, v76
	v_pk_mul_f32 v[70:71], v[74:75], v[70:71]
	ds_bpermute_b32 v39, v1, v77
	v_cvt_pk_bf16_f32 v72, v72, v73
	v_mov_b32_dpp v74, v70 row_shr:1 row_mask:0xf bank_mask:0xf bound_ctrl:1
	v_mov_b32_dpp v75, v71 row_shr:1 row_mask:0xf bank_mask:0xf bound_ctrl:1
	v_pk_fma_f32 v[42:43], v[42:43], v[74:75], v[70:71]
	v_cvt_pk_bf16_f32 v68, v68, v69
	v_cvt_pk_bf16_f32 v69, v76, v77
	v_mov_b32_dpp v70, v42 row_shr:2 row_mask:0xf bank_mask:0xf bound_ctrl:1
	v_mov_b32_dpp v71, v43 row_shr:2 row_mask:0xf bank_mask:0xf bound_ctrl:1
	v_pk_fma_f32 v[42:43], v[78:79], v[70:71], v[42:43]
	s_nop 1
	v_mov_b32_dpp v70, v42 row_shr:4 row_mask:0xf bank_mask:0xf bound_ctrl:1
	v_mov_b32_dpp v71, v43 row_shr:4 row_mask:0xf bank_mask:0xf bound_ctrl:1
	v_pk_fma_f32 v[42:43], v[80:81], v[70:71], v[42:43]
	s_nop 1
	v_mov_b32_dpp v70, v42 row_shr:8 row_mask:0xf bank_mask:0xf bound_ctrl:1
	v_mov_b32_dpp v71, v43 row_shr:8 row_mask:0xf bank_mask:0xf bound_ctrl:1
	v_pk_fma_f32 v[42:43], v[82:83], v[70:71], v[42:43]
	s_nop 0
	v_pk_fma_f32 v[70:71], v[86:87], v[84:85], v[42:43]
	ds_bpermute_b32 v42, v1, v70
	ds_bpermute_b32 v43, v1, v71
	v_cvt_pk_bf16_f32 v73, v70, v71
	global_store_dwordx2 v[114:115], v[72:73], off offset:32
	global_store_dwordx2 v[116:117], v[68:69], off offset:32
	s_and_saveexec_b64 s[34:35], vcc
	s_cbranch_execz .LBB0_525
	v_add_u32_e32 v68, 16, v0
	v_ashrrev_i32_e32 v69, 31, v68
	v_lshl_add_u64 v[68:69], s[42:43], 0, v[68:69]
	v_lshlrev_b64 v[68:69], 2, v[68:69]
	v_lshl_add_u64 v[70:71], s[84:85], 0, v[68:69]
	v_lshl_add_u64 v[68:69], s[86:87], 0, v[68:69]
	s_waitcnt lgkmcnt(0)
	global_store_dwordx4 v[70:71], v[36:39], off
	global_store_dwordx4 v[68:69], v[40:43], off
.LBB0_525:
	s_or_b64 exec, exec, s[34:35]
	v_lshl_or_b32 v2, v146, 1, v210
	v_lshl_add_u64 v[36:37], v[118:119], 0, v[2:3]
	s_waitcnt lgkmcnt(0)
	v_lshl_add_u64 v[38:39], v[120:121], 0, v[2:3]
	s_waitcnt vmcnt(10)
	s_nop 7
	global_load_dwordx4 v[68:71], v[36:37], off
	global_load_dwordx4 v[72:75], v[38:39], off
	global_load_dwordx4 v[76:79], v[36:37], off offset:64
	global_load_dwordx4 v[80:83], v[38:39], off offset:64
	global_load_dwordx4 v[40:43], v[108:109], off offset:192
	s_nop 0
	global_load_dwordx4 v[36:39], v[110:111], off offset:192
	global_load_dwordx4 v[84:87], v[112:113], off offset:192
	ds_read2_b32 v[124:125], v145 offset0:32 offset1:33
	ds_read2_b32 v[128:129], v145 offset0:34 offset1:35
	s_nop 7
	s_nop 0
	s_nop 7
	s_nop 0
	s_nop 7
	s_nop 0
	s_nop 7
	s_nop 1
	s_nop 7
	s_nop 1
	s_nop 7
	s_nop 1
	s_nop 7
	v_mov_b32_e32 v2, v88
	s_nop 7
	s_nop 0
	s_nop 7
	s_nop 0
	s_nop 7
	s_nop 0
	s_nop 7
	s_nop 0
	s_nop 7
	s_nop 0
	s_nop 7
	s_nop 0
	s_nop 7
	s_nop 1
	s_nop 7
	s_nop 1
	s_nop 7
	s_nop 1
	s_nop 7
	v_mov_b32_e32 v134, v89
	s_nop 7
	s_nop 0
	s_nop 7
	s_nop 0
	s_nop 7
	s_nop 0
	s_nop 7
	s_nop 0
	s_nop 7
	s_nop 0
	s_nop 7
	s_nop 0
	s_nop 7
	s_nop 1
	s_nop 7
	s_nop 1
	s_nop 7
	s_nop 1
	s_nop 7
	v_mov_b32_e32 v135, v90
	s_nop 7
	s_nop 0
	s_nop 7
	s_nop 0
	s_nop 7
	s_nop 0
	s_nop 7
	s_nop 0
	s_nop 7
	s_nop 0
	s_nop 7
	s_nop 0
	s_nop 7
	v_mfma_f32_16x16x32_bf16 v[92:95], v[60:63], v[16:19], 0
	s_nop 0
	s_nop 7
	v_mfma_f32_16x16x32_bf16 v[110:113], v[52:55], v[32:35], v[92:95]
	s_nop 0
	s_nop 7
	s_nop 1
	s_nop 7
	v_mov_b32_e32 v136, v91
	v_mfma_f32_16x16x32_bf16 v[88:91], v[64:67], v[16:19], 0
	s_nop 0
	v_add_f32_e32 v92, v44, v110
	v_add_f32_e32 v93, v45, v111
	v_mul_f32_e32 v92, 0xbfb8aa3b, v92
	v_mfma_f32_16x16x32_bf16 v[88:91], v[56:59], v[32:35], v[88:91]
	v_mul_f32_e32 v93, 0xbfb8aa3b, v93
	v_exp_f32_e32 v92, v92
	v_exp_f32_e32 v93, v93
	v_add_f32_e32 v92, 1.0, v92
	v_add_f32_e32 v93, 1.0, v93
	s_nop 2
	v_add_f32_e32 v88, v48, v88
	v_add_f32_e32 v89, v49, v89
	v_mul_f32_e32 v88, 0xbfb8aa3b, v88
	v_mul_f32_e32 v89, 0xbfb8aa3b, v89
	v_exp_f32_e32 v88, v88
	v_exp_f32_e32 v89, v89
	v_rcp_f32_e32 v92, v92
	v_rcp_f32_e32 v93, v93
	v_add_f32_e32 v88, 1.0, v88
	v_add_f32_e32 v89, 1.0, v89
	v_rcp_f32_e32 v88, v88
	v_rcp_f32_e32 v89, v89
	s_waitcnt lgkmcnt(0)
	v_pk_mul_f32 v[92:93], v[124:125], v[92:93]
	v_add_f32_e32 v90, v50, v90
	v_mul_f32_e32 v88, 0xc1000000, v88
	v_mul_f32_e32 v89, 0xc1000000, v89
	v_mul_f32_e32 v88, v2, v88
	v_mul_f32_e32 v89, v134, v89
	v_mul_f32_e32 v88, 0x3fb8aa3b, v88
	v_mul_f32_e32 v89, 0x3fb8aa3b, v89
	v_exp_f32_e32 v108, v88
	v_exp_f32_e32 v109, v89
	v_add_f32_e32 v91, v51, v91
	v_mul_f32_e32 v90, 0xbfb8aa3b, v90
	v_fma_f32 v88, -v108, v108, 1.0
	v_fma_f32 v89, -v109, v109, 1.0
	v_sqrt_f32_e32 v110, v88
	v_sqrt_f32_e32 v111, v89
	v_mov_b32_e32 v88, 1.0
	v_mov_b32_e32 v89, 1.0
	v_mul_f32_e32 v91, 0xbfb8aa3b, v91
	v_pk_mul_f32 v[92:93], v[92:93], v[110:111]
	v_mov_b32_dpp v88, v108 row_shr:1 row_mask:0xf bank_mask:0xf
	v_mov_b32_dpp v89, v109 row_shr:1 row_mask:0xf bank_mask:0xf
	v_mov_b32_dpp v110, v92 row_shr:1 row_mask:0xf bank_mask:0xf bound_ctrl:1
	v_mov_b32_dpp v111, v93 row_shr:1 row_mask:0xf bank_mask:0xf bound_ctrl:1
	v_pk_fma_f32 v[92:93], v[108:109], v[110:111], v[92:93]
	v_pk_mul_f32 v[118:119], v[108:109], v[88:89]
	v_mov_b32_e32 v88, 1.0
	v_mov_b32_e32 v89, 1.0
	v_mov_b32_dpp v108, v92 row_shr:2 row_mask:0xf bank_mask:0xf bound_ctrl:1
	v_mov_b32_dpp v109, v93 row_shr:2 row_mask:0xf bank_mask:0xf bound_ctrl:1
	v_exp_f32_e32 v90, v90
	v_exp_f32_e32 v91, v91
	v_mov_b32_dpp v88, v118 row_shr:2 row_mask:0xf bank_mask:0xf
	v_mov_b32_dpp v89, v119 row_shr:2 row_mask:0xf bank_mask:0xf
	v_pk_fma_f32 v[92:93], v[118:119], v[108:109], v[92:93]
	v_pk_mul_f32 v[120:121], v[118:119], v[88:89]
	v_mov_b32_e32 v88, 1.0
	v_mov_b32_e32 v89, 1.0
	v_mov_b32_dpp v108, v92 row_shr:4 row_mask:0xf bank_mask:0xf bound_ctrl:1
	v_mov_b32_dpp v109, v93 row_shr:4 row_mask:0xf bank_mask:0xf bound_ctrl:1
	v_mov_b32_dpp v88, v120 row_shr:4 row_mask:0xf bank_mask:0xf
	v_mov_b32_dpp v89, v121 row_shr:4 row_mask:0xf bank_mask:0xf
	v_pk_fma_f32 v[92:93], v[120:121], v[108:109], v[92:93]
	v_pk_mul_f32 v[122:123], v[120:121], v[88:89]
	v_add_f32_e32 v90, 1.0, v90
	v_mov_b32_dpp v108, v92 row_shr:8 row_mask:0xf bank_mask:0xf bound_ctrl:1
	v_mov_b32_dpp v109, v93 row_shr:8 row_mask:0xf bank_mask:0xf bound_ctrl:1
	v_add_f32_e32 v91, 1.0, v91
	v_pk_fma_f32 v[92:93], v[122:123], v[108:109], v[92:93]
	v_rcp_f32_e32 v90, v90
	v_add_f32_e32 v108, v46, v112
	v_rcp_f32_e32 v91, v91
	v_add_f32_e32 v109, v47, v113
	v_mul_f32_e32 v108, 0xbfb8aa3b, v108
	v_mul_f32_e32 v109, 0xbfb8aa3b, v109
	v_exp_f32_e32 v108, v108
	v_exp_f32_e32 v109, v109
	v_mul_f32_e32 v90, 0xc1000000, v90
	v_mul_f32_e32 v91, 0xc1000000, v91
	v_mul_f32_e32 v90, v135, v90
	v_mul_f32_e32 v91, v136, v91
	v_add_f32_e32 v108, 1.0, v108
	v_mul_f32_e32 v90, 0x3fb8aa3b, v90
	v_add_f32_e32 v109, 1.0, v109
	v_mul_f32_e32 v91, 0x3fb8aa3b, v91
	v_rcp_f32_e32 v112, v108
	v_exp_f32_e32 v108, v90
	v_rcp_f32_e32 v113, v109
	v_exp_f32_e32 v109, v91
	v_mov_b32_e32 v88, 1.0
	v_fma_f32 v90, -v108, v108, 1.0
	v_sqrt_f32_e32 v118, v90
	v_fma_f32 v91, -v109, v109, 1.0
	v_sqrt_f32_e32 v119, v91
	v_pk_mul_f32 v[112:113], v[112:113], v[128:129]
	v_mov_b32_e32 v89, 1.0
	v_mov_b32_e32 v90, 1.0
	v_mov_b32_e32 v91, 1.0
	v_pk_mul_f32 v[112:113], v[118:119], v[112:113]
	v_mov_b32_dpp v88, v122 row_shr:8 row_mask:0xf bank_mask:0xf
	v_mov_b32_dpp v89, v123 row_shr:8 row_mask:0xf bank_mask:0xf
	v_mov_b32_dpp v90, v108 row_shr:1 row_mask:0xf bank_mask:0xf
	v_mov_b32_dpp v91, v109 row_shr:1 row_mask:0xf bank_mask:0xf
	v_mov_b32_dpp v118, v112 row_shr:1 row_mask:0xf bank_mask:0xf bound_ctrl:1
	v_mov_b32_dpp v119, v113 row_shr:1 row_mask:0xf bank_mask:0xf bound_ctrl:1
	v_pk_mul_f32 v[94:95], v[122:123], v[88:89]
	v_pk_mul_f32 v[122:123], v[108:109], v[90:91]
	v_mov_b32_e32 v90, 1.0
	v_mov_b32_e32 v91, 1.0
	v_pk_fma_f32 v[108:109], v[108:109], v[118:119], v[112:113]
	v_mov_b32_dpp v90, v122 row_shr:2 row_mask:0xf bank_mask:0xf
	v_mov_b32_dpp v91, v123 row_shr:2 row_mask:0xf bank_mask:0xf
	v_mov_b32_dpp v112, v108 row_shr:2 row_mask:0xf bank_mask:0xf bound_ctrl:1
	v_mov_b32_dpp v113, v109 row_shr:2 row_mask:0xf bank_mask:0xf bound_ctrl:1
	v_pk_mul_f32 v[124:125], v[122:123], v[90:91]
	v_mov_b32_e32 v90, 1.0
	v_mov_b32_e32 v91, 1.0
	v_pk_fma_f32 v[108:109], v[122:123], v[112:113], v[108:109]
	v_mov_b32_dpp v90, v124 row_shr:4 row_mask:0xf bank_mask:0xf
	v_mov_b32_dpp v91, v125 row_shr:4 row_mask:0xf bank_mask:0xf
	v_mov_b32_dpp v112, v108 row_shr:4 row_mask:0xf bank_mask:0xf bound_ctrl:1
	v_mov_b32_dpp v113, v109 row_shr:4 row_mask:0xf bank_mask:0xf bound_ctrl:1
	v_pk_mul_f32 v[126:127], v[124:125], v[90:91]
	v_mov_b32_e32 v90, 1.0
	v_mov_b32_e32 v91, 1.0
	v_pk_fma_f32 v[108:109], v[124:125], v[112:113], v[108:109]
	v_mov_b32_dpp v90, v126 row_shr:8 row_mask:0xf bank_mask:0xf
	v_mov_b32_dpp v91, v127 row_shr:8 row_mask:0xf bank_mask:0xf
	v_mov_b32_dpp v112, v108 row_shr:8 row_mask:0xf bank_mask:0xf bound_ctrl:1
	v_mov_b32_dpp v113, v109 row_shr:8 row_mask:0xf bank_mask:0xf bound_ctrl:1
	v_pk_mul_f32 v[120:121], v[126:127], v[90:91]
	v_pk_fma_f32 v[108:109], v[126:127], v[112:113], v[108:109]
	v_pk_fma_f32 v[110:111], v[94:95], 0, v[92:93] op_sel_hi:[1,0,1]
	v_pk_fma_f32 v[112:113], v[120:121], 0, v[108:109] op_sel_hi:[1,0,1]
	ds_bpermute_b32 v92, v1, v110
	ds_bpermute_b32 v93, v1, v111
	v_cvt_pk_bf16_f32 v110, v110, v111
	v_cvt_pk_bf16_f32 v111, v112, v113
	ds_bpermute_b32 v108, v1, v112
	ds_bpermute_b32 v109, v1, v113
	global_store_dwordx2 v[100:101], v[110:111], off offset:64
	v_mfma_f32_16x16x32_bf16 v[110:113], v[64:67], v[12:15], 0
	ds_bpermute_b32 v88, v1, v94
	ds_bpermute_b32 v89, v1, v95
	v_cvt_pk_bf16_f32 v94, v94, v95
	v_mfma_f32_16x16x32_bf16 v[122:125], v[56:59], v[28:31], v[110:113]
	v_cvt_pk_bf16_f32 v95, v120, v121
	global_store_dwordx2 v[102:103], v[94:95], off offset:64
	ds_bpermute_b32 v90, v1, v120
	ds_bpermute_b32 v91, v1, v121
	v_mfma_f32_16x16x32_bf16 v[118:121], v[60:63], v[12:15], 0
	s_nop 2
	v_add_f32_e32 v94, v48, v122
	v_mul_f32_e32 v94, 0xbfb8aa3b, v94
	v_exp_f32_e32 v94, v94
	v_mfma_f32_16x16x32_bf16 v[118:121], v[52:55], v[28:31], v[118:121]
	v_mov_b32_e32 v112, 1.0
	v_add_f32_e32 v94, 1.0, v94
	v_rcp_f32_e32 v95, v94
	s_nop 0
	v_mul_f32_e32 v95, 0xc1000000, v95
	v_mul_f32_e32 v95, v2, v95
	v_mul_f32_e32 v95, 0x3fb8aa3b, v95
	v_exp_f32_e32 v110, v95
	v_add_f32_e32 v94, v44, v118
	v_mul_f32_e32 v94, 0xbfb8aa3b, v94
	v_exp_f32_e32 v94, v94
	v_fma_f32 v95, -v110, v110, 1.0
	v_sqrt_f32_e32 v118, v95
	v_add_f32_e32 v95, v49, v123
	v_mul_f32_e32 v95, 0xbfb8aa3b, v95
	v_exp_f32_e32 v95, v95
	v_mov_b32_dpp v112, v110 row_shr:1 row_mask:0xf bank_mask:0xf
	v_add_f32_e32 v94, 1.0, v94
	v_rcp_f32_e32 v94, v94
	v_add_f32_e32 v95, 1.0, v95
	v_rcp_f32_e32 v111, v95
	v_add_f32_e32 v95, v45, v119
	v_mul_f32_e32 v95, 0xbfb8aa3b, v95
	v_exp_f32_e32 v95, v95
	v_mul_f32_e32 v111, 0xc1000000, v111
	v_mul_f32_e32 v111, v134, v111
	v_mul_f32_e32 v111, 0x3fb8aa3b, v111
	v_exp_f32_e32 v111, v111
	v_add_f32_e32 v95, 1.0, v95
	v_rcp_f32_e32 v95, v95
	v_fma_f32 v113, -v111, v111, 1.0
	v_sqrt_f32_e32 v119, v113
	v_mov_b32_e32 v113, 1.0
	s_nop 1
	v_mov_b32_dpp v113, v111 row_shr:1 row_mask:0xf bank_mask:0xf
	v_pk_mul_f32 v[122:123], v[110:111], v[112:113]
	v_mov_b32_e32 v112, 1.0
	v_mov_b32_e32 v113, 1.0
	s_nop 0
	v_mov_b32_dpp v112, v122 row_shr:2 row_mask:0xf bank_mask:0xf
	v_mov_b32_dpp v113, v123 row_shr:2 row_mask:0xf bank_mask:0xf
	v_pk_mul_f32 v[126:127], v[122:123], v[112:113]
	v_mov_b32_e32 v112, 1.0
	v_mov_b32_e32 v113, 1.0
	s_nop 0
	v_mov_b32_dpp v112, v126 row_shr:4 row_mask:0xf bank_mask:0xf
	v_mov_b32_dpp v113, v127 row_shr:4 row_mask:0xf bank_mask:0xf
	v_pk_mul_f32 v[128:129], v[126:127], v[112:113]
	v_mov_b32_e32 v112, 1.0
	v_mov_b32_e32 v113, 1.0
	s_nop 0
	v_mov_b32_dpp v112, v128 row_shr:8 row_mask:0xf bank_mask:0xf
	v_mov_b32_dpp v113, v129 row_shr:8 row_mask:0xf bank_mask:0xf
	v_pk_mul_f32 v[130:131], v[128:129], v[112:113]
	v_add_u32_e32 v113, 0x10c0, v145
	ds_read2_b32 v[132:133], v113 offset1:1
	s_waitcnt lgkmcnt(0)
	v_pk_mul_f32 v[88:89], v[130:131], v[88:89]
	ds_bpermute_b32 v112, v1, v88
	ds_bpermute_b32 v113, v1, v89
	v_cvt_pk_bf16_f32 v88, v88, v89
	v_pk_mul_f32 v[94:95], v[132:133], v[94:95]
	s_nop 0
	v_pk_mul_f32 v[94:95], v[94:95], v[118:119]
	s_nop 1
	v_mov_b32_dpp v118, v94 row_shr:1 row_mask:0xf bank_mask:0xf bound_ctrl:1
	v_mov_b32_dpp v119, v95 row_shr:1 row_mask:0xf bank_mask:0xf bound_ctrl:1
	v_pk_fma_f32 v[94:95], v[110:111], v[118:119], v[94:95]
	s_nop 1
	v_mov_b32_dpp v110, v94 row_shr:2 row_mask:0xf bank_mask:0xf bound_ctrl:1
	v_mov_b32_dpp v111, v95 row_shr:2 row_mask:0xf bank_mask:0xf bound_ctrl:1
	v_pk_fma_f32 v[94:95], v[122:123], v[110:111], v[94:95]
	v_mov_b32_e32 v122, 1.0
	v_mov_b32_e32 v123, 1.0
	v_mov_b32_dpp v110, v94 row_shr:4 row_mask:0xf bank_mask:0xf bound_ctrl:1
	v_mov_b32_dpp v111, v95 row_shr:4 row_mask:0xf bank_mask:0xf bound_ctrl:1
	v_pk_fma_f32 v[94:95], v[126:127], v[110:111], v[94:95]
	s_nop 1
	v_mov_b32_dpp v110, v94 row_shr:8 row_mask:0xf bank_mask:0xf bound_ctrl:1
	v_mov_b32_dpp v111, v95 row_shr:8 row_mask:0xf bank_mask:0xf bound_ctrl:1
	v_pk_fma_f32 v[94:95], v[128:129], v[110:111], v[94:95]
	s_nop 0
	v_pk_fma_f32 v[92:93], v[130:131], v[92:93], v[94:95]
	v_add_f32_e32 v94, v50, v124
	v_mul_f32_e32 v94, 0xbfb8aa3b, v94
	v_exp_f32_e32 v94, v94
	ds_bpermute_b32 v110, v1, v92
	ds_bpermute_b32 v111, v1, v93
	v_cvt_pk_bf16_f32 v92, v92, v93
	v_add_f32_e32 v94, 1.0, v94
	v_rcp_f32_e32 v95, v94
	v_add_f32_e32 v94, v46, v120
	v_mul_f32_e32 v94, 0xbfb8aa3b, v94
	v_exp_f32_e32 v94, v94
	v_mul_f32_e32 v95, 0xc1000000, v95
	v_mul_f32_e32 v95, v135, v95
	v_mul_f32_e32 v95, 0x3fb8aa3b, v95
	v_exp_f32_e32 v118, v95
	v_add_f32_e32 v94, 1.0, v94
	v_rcp_f32_e32 v94, v94
	v_fma_f32 v95, -v118, v118, 1.0
	v_sqrt_f32_e32 v120, v95
	v_add_f32_e32 v95, v51, v125
	v_mul_f32_e32 v95, 0xbfb8aa3b, v95
	v_exp_f32_e32 v95, v95
	v_mov_b32_dpp v122, v118 row_shr:1 row_mask:0xf bank_mask:0xf
	v_add_f32_e32 v95, 1.0, v95
	v_rcp_f32_e32 v119, v95
	v_add_f32_e32 v95, v47, v121
	v_mul_f32_e32 v95, 0xbfb8aa3b, v95
	v_exp_f32_e32 v95, v95
	v_mul_f32_e32 v119, 0xc1000000, v119
	v_mul_f32_e32 v119, v136, v119
	v_mul_f32_e32 v119, 0x3fb8aa3b, v119
	v_exp_f32_e32 v119, v119
	v_add_f32_e32 v95, 1.0, v95
	v_rcp_f32_e32 v95, v95
	v_mov_b32_dpp v123, v119 row_shr:1 row_mask:0xf bank_mask:0xf
	v_pk_mul_f32 v[124:125], v[118:119], v[122:123]
	v_mov_b32_e32 v122, 1.0
	v_mov_b32_e32 v123, 1.0
	v_fma_f32 v121, -v119, v119, 1.0
	v_mov_b32_dpp v122, v124 row_shr:2 row_mask:0xf bank_mask:0xf
	v_mov_b32_dpp v123, v125 row_shr:2 row_mask:0xf bank_mask:0xf
	v_pk_mul_f32 v[126:127], v[124:125], v[122:123]
	v_mov_b32_e32 v122, 1.0
	v_mov_b32_e32 v123, 1.0
	v_sqrt_f32_e32 v121, v121
	v_mov_b32_dpp v122, v126 row_shr:4 row_mask:0xf bank_mask:0xf
	v_mov_b32_dpp v123, v127 row_shr:4 row_mask:0xf bank_mask:0xf
	v_pk_mul_f32 v[128:129], v[126:127], v[122:123]
	v_mov_b32_e32 v122, 1.0
	v_mov_b32_e32 v123, 1.0
	s_nop 0
	v_mov_b32_dpp v122, v128 row_shr:8 row_mask:0xf bank_mask:0xf
	v_mov_b32_dpp v123, v129 row_shr:8 row_mask:0xf bank_mask:0xf
	v_pk_mul_f32 v[130:131], v[128:129], v[122:123]
	v_add_u32_e32 v123, 0x10c8, v145
	ds_read2_b32 v[132:133], v123 offset1:1
	v_pk_mul_f32 v[90:91], v[130:131], v[90:91]
	ds_bpermute_b32 v122, v1, v90
	v_cvt_pk_bf16_f32 v89, v90, v91
	ds_bpermute_b32 v123, v1, v91
	s_waitcnt lgkmcnt(0)
	v_pk_mul_f32 v[94:95], v[94:95], v[132:133]
	s_nop 0
	v_pk_mul_f32 v[94:95], v[120:121], v[94:95]
	s_nop 1
	v_mov_b32_dpp v120, v94 row_shr:1 row_mask:0xf bank_mask:0xf bound_ctrl:1
	v_mov_b32_dpp v121, v95 row_shr:1 row_mask:0xf bank_mask:0xf bound_ctrl:1
	v_pk_fma_f32 v[94:95], v[118:119], v[120:121], v[94:95]
	s_nop 1
	v_mov_b32_dpp v118, v94 row_shr:2 row_mask:0xf bank_mask:0xf bound_ctrl:1
	v_mov_b32_dpp v119, v95 row_shr:2 row_mask:0xf bank_mask:0xf bound_ctrl:1
	v_pk_fma_f32 v[94:95], v[124:125], v[118:119], v[94:95]
	s_nop 1
	v_mov_b32_dpp v118, v94 row_shr:4 row_mask:0xf bank_mask:0xf bound_ctrl:1
	v_mov_b32_dpp v119, v95 row_shr:4 row_mask:0xf bank_mask:0xf bound_ctrl:1
	v_pk_fma_f32 v[94:95], v[126:127], v[118:119], v[94:95]
	s_nop 1
	v_mov_b32_dpp v118, v94 row_shr:8 row_mask:0xf bank_mask:0xf bound_ctrl:1
	v_mov_b32_dpp v119, v95 row_shr:8 row_mask:0xf bank_mask:0xf bound_ctrl:1
	v_pk_fma_f32 v[94:95], v[128:129], v[118:119], v[94:95]
	v_mfma_f32_16x16x32_bf16 v[118:121], v[60:63], v[8:11], 0
	v_fma_f32 v94, v130, v108, v94
	v_fma_f32 v95, v131, v109, v95
	ds_bpermute_b32 v108, v1, v94
	v_cvt_pk_bf16_f32 v93, v94, v95
	global_store_dwordx2 v[104:105], v[92:93], off offset:64
	global_store_dwordx2 v[106:107], v[88:89], off offset:64
	v_mfma_f32_16x16x32_bf16 v[88:91], v[64:67], v[8:11], 0
	ds_bpermute_b32 v109, v1, v95
	v_mfma_f32_16x16x32_bf16 v[92:95], v[56:59], v[24:27], v[88:91]
	v_mfma_f32_16x16x32_bf16 v[88:91], v[52:55], v[24:27], v[118:121]
	v_mfma_f32_16x16x32_bf16 v[64:67], v[64:67], v[4:7], 0
	s_nop 5
	v_add_f32_e32 v92, v48, v92
	v_mul_f32_e32 v92, 0xbfb8aa3b, v92
	v_exp_f32_e32 v92, v92
	v_add_f32_e32 v88, v44, v88
	v_mul_f32_e32 v88, 0xbfb8aa3b, v88
	v_exp_f32_e32 v88, v88
	v_add_f32_e32 v92, 1.0, v92
	v_rcp_f32_e32 v92, v92
	v_add_f32_e32 v89, v45, v89
	v_add_f32_e32 v88, 1.0, v88
	v_rcp_f32_e32 v118, v88
	v_mul_f32_e32 v88, 0xc1000000, v92
	v_add_f32_e32 v92, v49, v93
	v_mul_f32_e32 v92, 0xbfb8aa3b, v92
	v_exp_f32_e32 v92, v92
	v_mul_f32_e32 v89, 0xbfb8aa3b, v89
	v_exp_f32_e32 v89, v89
	v_mul_f32_e32 v88, v2, v88
	v_add_f32_e32 v92, 1.0, v92
	v_rcp_f32_e32 v92, v92
	v_add_f32_e32 v89, 1.0, v89
	v_rcp_f32_e32 v119, v89
	v_mul_f32_e32 v88, 0x3fb8aa3b, v88
	v_mul_f32_e32 v89, 0xc1000000, v92
	v_mul_f32_e32 v89, v134, v89
	v_mul_f32_e32 v89, 0x3fb8aa3b, v89
	v_exp_f32_e32 v120, v88
	v_exp_f32_e32 v121, v89
	v_mfma_f32_16x16x32_bf16 v[60:63], v[60:63], v[4:7], 0
	v_add_f32_e32 v94, v50, v94
	v_fma_f32 v88, -v120, v120, 1.0
	v_fma_f32 v89, -v121, v121, 1.0
	v_sqrt_f32_e32 v124, v88
	v_mov_b32_e32 v88, 1.0
	v_sqrt_f32_e32 v125, v89
	v_mov_b32_e32 v89, 1.0
	v_mov_b32_dpp v88, v120 row_shr:1 row_mask:0xf bank_mask:0xf
	v_mfma_f32_16x16x32_bf16 v[56:59], v[56:59], v[20:23], v[64:67]
	v_mov_b32_dpp v89, v121 row_shr:1 row_mask:0xf bank_mask:0xf
	v_pk_mul_f32 v[126:127], v[120:121], v[88:89]
	v_mov_b32_e32 v88, 1.0
	v_mov_b32_e32 v89, 1.0
	v_add_f32_e32 v95, v51, v95
	v_mov_b32_dpp v88, v126 row_shr:2 row_mask:0xf bank_mask:0xf
	v_mov_b32_dpp v89, v127 row_shr:2 row_mask:0xf bank_mask:0xf
	v_pk_mul_f32 v[128:129], v[126:127], v[88:89]
	v_mov_b32_e32 v88, 1.0
	v_mov_b32_e32 v89, 1.0
	v_mul_f32_e32 v94, 0xbfb8aa3b, v94
	v_mov_b32_dpp v88, v128 row_shr:4 row_mask:0xf bank_mask:0xf
	v_mov_b32_dpp v89, v129 row_shr:4 row_mask:0xf bank_mask:0xf
	v_pk_mul_f32 v[130:131], v[128:129], v[88:89]
	v_mov_b32_e32 v88, 1.0
	v_mov_b32_e32 v89, 1.0
	v_mul_f32_e32 v95, 0xbfb8aa3b, v95
	v_mov_b32_dpp v88, v130 row_shr:8 row_mask:0xf bank_mask:0xf
	v_mov_b32_dpp v89, v131 row_shr:8 row_mask:0xf bank_mask:0xf
	v_pk_mul_f32 v[132:133], v[130:131], v[88:89]
	v_add_u32_e32 v89, 0x2100, v145
	v_pk_mul_f32 v[92:93], v[132:133], v[112:113]
	ds_read2_b32 v[112:113], v89 offset1:1
	v_mfma_f32_16x16x32_bf16 v[60:63], v[52:55], v[20:23], v[60:63]
	v_add_f32_e32 v48, v48, v56
	v_exp_f32_e32 v94, v94
	v_exp_f32_e32 v95, v95
	s_waitcnt lgkmcnt(0)
	v_pk_mul_f32 v[112:113], v[112:113], v[118:119]
	v_mul_f32_e32 v48, 0xbfb8aa3b, v48
	v_pk_mul_f32 v[112:113], v[112:113], v[124:125]
	v_exp_f32_e32 v48, v48
	v_add_f32_e32 v90, v46, v90
	v_mov_b32_dpp v118, v112 row_shr:1 row_mask:0xf bank_mask:0xf bound_ctrl:1
	v_mov_b32_dpp v119, v113 row_shr:1 row_mask:0xf bank_mask:0xf bound_ctrl:1
	v_add_f32_e32 v91, v47, v91
	v_pk_fma_f32 v[112:113], v[120:121], v[118:119], v[112:113]
	v_mul_f32_e32 v90, 0xbfb8aa3b, v90
	v_mul_f32_e32 v91, 0xbfb8aa3b, v91
	v_add_f32_e32 v44, v44, v60
	v_mov_b32_dpp v118, v112 row_shr:2 row_mask:0xf bank_mask:0xf bound_ctrl:1
	v_mov_b32_dpp v119, v113 row_shr:2 row_mask:0xf bank_mask:0xf bound_ctrl:1
	v_add_f32_e32 v94, 1.0, v94
	v_exp_f32_e32 v90, v90
	v_add_f32_e32 v95, 1.0, v95
	v_exp_f32_e32 v91, v91
	v_mul_f32_e32 v44, 0xbfb8aa3b, v44
	v_pk_fma_f32 v[112:113], v[126:127], v[118:119], v[112:113]
	v_rcp_f32_e32 v94, v94
	v_rcp_f32_e32 v95, v95
	v_add_f32_e32 v48, 1.0, v48
	v_exp_f32_e32 v44, v44
	v_mov_b32_dpp v118, v112 row_shr:4 row_mask:0xf bank_mask:0xf bound_ctrl:1
	v_mov_b32_dpp v119, v113 row_shr:4 row_mask:0xf bank_mask:0xf bound_ctrl:1
	v_rcp_f32_e32 v52, v48
	v_pk_fma_f32 v[112:113], v[128:129], v[118:119], v[112:113]
	v_add_f32_e32 v90, 1.0, v90
	v_add_f32_e32 v91, 1.0, v91
	v_mov_b32_dpp v118, v112 row_shr:8 row_mask:0xf bank_mask:0xf bound_ctrl:1
	v_mov_b32_dpp v119, v113 row_shr:8 row_mask:0xf bank_mask:0xf bound_ctrl:1
	v_pk_fma_f32 v[112:113], v[130:131], v[118:119], v[112:113]
	v_rcp_f32_e32 v118, v90
	v_mul_f32_e32 v90, 0xc1000000, v94
	v_rcp_f32_e32 v119, v91
	v_mul_f32_e32 v91, 0xc1000000, v95
	v_add_f32_e32 v44, 1.0, v44
	v_mul_f32_e32 v90, v135, v90
	v_mul_f32_e32 v91, v136, v91
	v_rcp_f32_e32 v48, v44
	v_mul_f32_e32 v44, 0xc1000000, v52
	v_mul_f32_e32 v90, 0x3fb8aa3b, v90
	v_mul_f32_e32 v91, 0x3fb8aa3b, v91
	v_mul_f32_e32 v2, v2, v44
	v_exp_f32_e32 v94, v90
	v_exp_f32_e32 v95, v91
	v_mul_f32_e32 v2, 0x3fb8aa3b, v2
	v_exp_f32_e32 v54, v2
	v_fma_f32 v90, -v94, v94, 1.0
	v_fma_f32 v91, -v95, v95, 1.0
	v_sqrt_f32_e32 v120, v90
	v_mov_b32_e32 v90, 1.0
	v_sqrt_f32_e32 v121, v91
	v_mov_b32_e32 v91, 1.0
	v_fma_f32 v2, -v54, v54, 1.0
	v_mov_b32_dpp v90, v94 row_shr:1 row_mask:0xf bank_mask:0xf
	v_mov_b32_dpp v91, v95 row_shr:1 row_mask:0xf bank_mask:0xf
	v_sqrt_f32_e32 v56, v2
	v_add_f32_e32 v2, v49, v57
	v_pk_mul_f32 v[124:125], v[94:95], v[90:91]
	v_mov_b32_e32 v90, 1.0
	v_mov_b32_e32 v91, 1.0
	v_mul_f32_e32 v2, 0xbfb8aa3b, v2
	v_mov_b32_dpp v90, v124 row_shr:2 row_mask:0xf bank_mask:0xf
	v_mov_b32_dpp v91, v125 row_shr:2 row_mask:0xf bank_mask:0xf
	v_exp_f32_e32 v2, v2
	v_pk_mul_f32 v[126:127], v[124:125], v[90:91]
	v_mov_b32_e32 v90, 1.0
	v_mov_b32_e32 v91, 1.0
	v_add_f32_e32 v2, 1.0, v2
	v_mov_b32_dpp v90, v126 row_shr:4 row_mask:0xf bank_mask:0xf
	v_mov_b32_dpp v91, v127 row_shr:4 row_mask:0xf bank_mask:0xf
	v_pk_mul_f32 v[128:129], v[126:127], v[90:91]
	v_mov_b32_e32 v90, 1.0
	v_mov_b32_e32 v91, 1.0
	v_rcp_f32_e32 v2, v2
	v_mov_b32_dpp v90, v128 row_shr:8 row_mask:0xf bank_mask:0xf
	v_mov_b32_dpp v91, v129 row_shr:8 row_mask:0xf bank_mask:0xf
	v_pk_mul_f32 v[130:131], v[128:129], v[90:91]
	v_add_u32_e32 v91, 0x2108, v145
	v_pk_fma_f32 v[112:113], v[132:133], v[110:111], v[112:113]
	ds_read2_b32 v[132:133], v91 offset1:1
	v_add_f32_e32 v45, v45, v61
	v_mul_f32_e32 v45, 0xbfb8aa3b, v45
	v_mul_f32_e32 v2, 0xc1000000, v2
	v_exp_f32_e32 v45, v45
	v_mul_f32_e32 v2, v134, v2
	s_waitcnt lgkmcnt(0)
	v_pk_mul_f32 v[118:119], v[118:119], v[132:133]
	v_mul_f32_e32 v2, 0x3fb8aa3b, v2
	v_pk_mul_f32 v[118:119], v[120:121], v[118:119]
	v_exp_f32_e32 v55, v2
	v_add_f32_e32 v45, 1.0, v45
	v_mov_b32_dpp v120, v118 row_shr:1 row_mask:0xf bank_mask:0xf bound_ctrl:1
	v_mov_b32_dpp v121, v119 row_shr:1 row_mask:0xf bank_mask:0xf bound_ctrl:1
	v_pk_fma_f32 v[94:95], v[94:95], v[120:121], v[118:119]
	v_mov_b32_e32 v44, 1.0
	v_rcp_f32_e32 v49, v45
	v_mov_b32_dpp v118, v94 row_shr:2 row_mask:0xf bank_mask:0xf bound_ctrl:1
	v_mov_b32_dpp v119, v95 row_shr:2 row_mask:0xf bank_mask:0xf bound_ctrl:1
	v_mov_b32_e32 v45, 1.0
	v_pk_fma_f32 v[94:95], v[124:125], v[118:119], v[94:95]
	v_mov_b32_dpp v44, v54 row_shr:1 row_mask:0xf bank_mask:0xf
	v_mov_b32_dpp v45, v55 row_shr:1 row_mask:0xf bank_mask:0xf
	v_mov_b32_dpp v118, v94 row_shr:4 row_mask:0xf bank_mask:0xf bound_ctrl:1
	v_mov_b32_dpp v119, v95 row_shr:4 row_mask:0xf bank_mask:0xf bound_ctrl:1
	v_pk_mul_f32 v[60:61], v[54:55], v[44:45]
	v_mov_b32_e32 v44, 1.0
	v_mov_b32_e32 v45, 1.0
	v_pk_fma_f32 v[94:95], v[126:127], v[118:119], v[94:95]
	v_mov_b32_dpp v44, v60 row_shr:2 row_mask:0xf bank_mask:0xf
	v_mov_b32_dpp v45, v61 row_shr:2 row_mask:0xf bank_mask:0xf
	ds_bpermute_b32 v88, v1, v92
	ds_bpermute_b32 v89, v1, v93
	v_mov_b32_dpp v118, v94 row_shr:8 row_mask:0xf bank_mask:0xf bound_ctrl:1
	v_mov_b32_dpp v119, v95 row_shr:8 row_mask:0xf bank_mask:0xf bound_ctrl:1
	v_pk_mul_f32 v[64:65], v[60:61], v[44:45]
	v_mov_b32_e32 v44, 1.0
	v_mov_b32_e32 v45, 1.0
	v_pk_fma_f32 v[94:95], v[128:129], v[118:119], v[94:95]
	v_mov_b32_dpp v44, v64 row_shr:4 row_mask:0xf bank_mask:0xf
	v_mov_b32_dpp v45, v65 row_shr:4 row_mask:0xf bank_mask:0xf
	v_pk_mul_f32 v[122:123], v[130:131], v[122:123]
	v_pk_fma_f32 v[108:109], v[130:131], v[108:109], v[94:95]
	v_pk_mul_f32 v[66:67], v[64:65], v[44:45]
	v_mov_b32_e32 v44, 1.0
	v_mov_b32_e32 v45, 1.0
	ds_bpermute_b32 v110, v1, v112
	ds_bpermute_b32 v111, v1, v113
	v_cvt_pk_bf16_f32 v112, v112, v113
	v_cvt_pk_bf16_f32 v113, v108, v109
	v_cvt_pk_bf16_f32 v92, v92, v93
	v_cvt_pk_bf16_f32 v93, v122, v123
	v_fma_f32 v2, -v55, v55, 1.0
	v_mov_b32_dpp v44, v66 row_shr:8 row_mask:0xf bank_mask:0xf
	v_mov_b32_dpp v45, v67 row_shr:8 row_mask:0xf bank_mask:0xf
	global_store_dwordx2 v[96:97], v[112:113], off offset:64
	global_store_dwordx2 v[98:99], v[92:93], off offset:64
	v_sqrt_f32_e32 v57, v2
	v_pk_mul_f32 v[92:93], v[66:67], v[44:45]
	v_add_u32_e32 v2, 0x3140, v145
	s_waitcnt lgkmcnt(0)
	v_pk_mul_f32 v[52:53], v[92:93], v[88:89]
	ds_read2_b32 v[88:89], v2 offset1:1
	v_add_f32_e32 v2, v50, v58
	v_mul_f32_e32 v2, 0xbfb8aa3b, v2
	v_exp_f32_e32 v2, v2
	v_add_f32_e32 v46, v46, v62
	v_add_f32_e32 v47, v47, v63
	v_mul_f32_e32 v46, 0xbfb8aa3b, v46
	v_add_f32_e32 v2, 1.0, v2
	v_rcp_f32_e32 v2, v2
	v_mul_f32_e32 v47, 0xbfb8aa3b, v47
	v_exp_f32_e32 v46, v46
	v_exp_f32_e32 v47, v47
	v_mul_f32_e32 v2, 0xc1000000, v2
	v_mul_f32_e32 v2, v135, v2
	v_mul_f32_e32 v2, 0x3fb8aa3b, v2
	v_exp_f32_e32 v50, v2
	s_waitcnt lgkmcnt(0)
	v_pk_mul_f32 v[48:49], v[88:89], v[48:49]
	v_add_f32_e32 v46, 1.0, v46
	v_pk_mul_f32 v[48:49], v[48:49], v[56:57]
	v_fma_f32 v2, -v50, v50, 1.0
	v_sqrt_f32_e32 v58, v2
	v_add_f32_e32 v2, v51, v59
	v_mul_f32_e32 v2, 0xbfb8aa3b, v2
	v_exp_f32_e32 v2, v2
	v_mov_b32_dpp v56, v48 row_shr:1 row_mask:0xf bank_mask:0xf bound_ctrl:1
	v_mov_b32_dpp v57, v49 row_shr:1 row_mask:0xf bank_mask:0xf bound_ctrl:1
	v_add_f32_e32 v47, 1.0, v47
	v_add_f32_e32 v2, 1.0, v2
	v_rcp_f32_e32 v2, v2
	v_pk_fma_f32 v[48:49], v[54:55], v[56:57], v[48:49]
	v_rcp_f32_e32 v56, v46
	v_mov_b32_e32 v46, 1.0
	v_mul_f32_e32 v2, 0xc1000000, v2
	v_mul_f32_e32 v2, v136, v2
	v_mul_f32_e32 v2, 0x3fb8aa3b, v2
	v_exp_f32_e32 v51, v2
	v_rcp_f32_e32 v57, v47
	v_mov_b32_e32 v47, 1.0
	v_mov_b32_dpp v54, v48 row_shr:2 row_mask:0xf bank_mask:0xf bound_ctrl:1
	v_mov_b32_dpp v55, v49 row_shr:2 row_mask:0xf bank_mask:0xf bound_ctrl:1
	v_mov_b32_dpp v46, v50 row_shr:1 row_mask:0xf bank_mask:0xf
	v_mov_b32_dpp v47, v51 row_shr:1 row_mask:0xf bank_mask:0xf
	v_pk_fma_f32 v[48:49], v[60:61], v[54:55], v[48:49]
	v_pk_mul_f32 v[62:63], v[50:51], v[46:47]
	v_mov_b32_e32 v46, 1.0
	v_mov_b32_e32 v47, 1.0
	v_mov_b32_dpp v54, v48 row_shr:4 row_mask:0xf bank_mask:0xf bound_ctrl:1
	v_mov_b32_dpp v55, v49 row_shr:4 row_mask:0xf bank_mask:0xf bound_ctrl:1
	v_mov_b32_dpp v46, v62 row_shr:2 row_mask:0xf bank_mask:0xf
	v_mov_b32_dpp v47, v63 row_shr:2 row_mask:0xf bank_mask:0xf
	ds_bpermute_b32 v90, v1, v122
	ds_bpermute_b32 v91, v1, v123
	v_pk_fma_f32 v[48:49], v[64:65], v[54:55], v[48:49]
	v_pk_mul_f32 v[64:65], v[62:63], v[46:47]
	v_mov_b32_e32 v46, 1.0
	v_mov_b32_e32 v47, 1.0
	v_mov_b32_dpp v54, v48 row_shr:8 row_mask:0xf bank_mask:0xf bound_ctrl:1
	v_mov_b32_dpp v55, v49 row_shr:8 row_mask:0xf bank_mask:0xf bound_ctrl:1
	v_mov_b32_dpp v46, v64 row_shr:4 row_mask:0xf bank_mask:0xf
	v_mov_b32_dpp v47, v65 row_shr:4 row_mask:0xf bank_mask:0xf
	v_pk_fma_f32 v[48:49], v[66:67], v[54:55], v[48:49]
	v_pk_mul_f32 v[66:67], v[64:65], v[46:47]
	v_mov_b32_e32 v46, 1.0
	v_mov_b32_e32 v47, 1.0
	v_fma_f32 v2, -v51, v51, 1.0
	v_mov_b32_dpp v46, v66 row_shr:8 row_mask:0xf bank_mask:0xf
	v_mov_b32_dpp v47, v67 row_shr:8 row_mask:0xf bank_mask:0xf
	v_sqrt_f32_e32 v59, v2
	v_pk_mul_f32 v[88:89], v[66:67], v[46:47]
	v_add_u32_e32 v2, 0x3148, v145
	s_waitcnt lgkmcnt(0)
	v_pk_mul_f32 v[60:61], v[88:89], v[90:91]
	ds_read2_b32 v[90:91], v2 offset1:1
	ds_bpermute_b32 v94, v1, v108
	ds_bpermute_b32 v95, v1, v109
	v_pk_fma_f32 v[54:55], v[92:93], v[110:111], v[48:49]
	ds_bpermute_b32 v44, v1, v52
	s_waitcnt lgkmcnt(0)
	v_pk_mul_f32 v[56:57], v[56:57], v[90:91]
	ds_bpermute_b32 v48, v1, v54
	v_pk_mul_f32 v[56:57], v[58:59], v[56:57]
	ds_bpermute_b32 v49, v1, v55
	ds_bpermute_b32 v45, v1, v53
	v_mov_b32_dpp v58, v56 row_shr:1 row_mask:0xf bank_mask:0xf bound_ctrl:1
	v_mov_b32_dpp v59, v57 row_shr:1 row_mask:0xf bank_mask:0xf bound_ctrl:1
	v_pk_fma_f32 v[50:51], v[50:51], v[58:59], v[56:57]
	ds_bpermute_b32 v46, v1, v60
	ds_bpermute_b32 v47, v1, v61
	v_mov_b32_dpp v56, v50 row_shr:2 row_mask:0xf bank_mask:0xf bound_ctrl:1
	v_mov_b32_dpp v57, v51 row_shr:2 row_mask:0xf bank_mask:0xf bound_ctrl:1
	v_pk_fma_f32 v[50:51], v[62:63], v[56:57], v[50:51]
	v_cvt_pk_bf16_f32 v54, v54, v55
	v_cvt_pk_bf16_f32 v52, v52, v53
	v_mov_b32_dpp v56, v50 row_shr:4 row_mask:0xf bank_mask:0xf bound_ctrl:1
	v_mov_b32_dpp v57, v51 row_shr:4 row_mask:0xf bank_mask:0xf bound_ctrl:1
	v_pk_fma_f32 v[50:51], v[64:65], v[56:57], v[50:51]
	v_cvt_pk_bf16_f32 v53, v60, v61
	s_nop 0
	v_mov_b32_dpp v56, v50 row_shr:8 row_mask:0xf bank_mask:0xf bound_ctrl:1
	v_mov_b32_dpp v57, v51 row_shr:8 row_mask:0xf bank_mask:0xf bound_ctrl:1
	v_pk_fma_f32 v[50:51], v[66:67], v[56:57], v[50:51]
	s_nop 0
	v_pk_fma_f32 v[56:57], v[88:89], v[94:95], v[50:51]
	ds_bpermute_b32 v50, v1, v56
	ds_bpermute_b32 v51, v1, v57
	v_cvt_pk_bf16_f32 v55, v56, v57
	global_store_dwordx2 v[114:115], v[54:55], off offset:64
	global_store_dwordx2 v[116:117], v[52:53], off offset:64
	s_and_saveexec_b64 s[34:35], vcc
	s_cbranch_execz .LBB0_527
	v_add_u32_e32 v52, 32, v0
	v_ashrrev_i32_e32 v53, 31, v52
	v_lshl_add_u64 v[52:53], s[42:43], 0, v[52:53]
	v_lshlrev_b64 v[52:53], 2, v[52:53]
	v_lshl_add_u64 v[54:55], s[84:85], 0, v[52:53]
	v_lshl_add_u64 v[52:53], s[86:87], 0, v[52:53]
	s_waitcnt lgkmcnt(0)
	global_store_dwordx4 v[54:55], v[44:47], off
	global_store_dwordx4 v[52:53], v[48:51], off
.LBB0_527:
	s_or_b64 exec, exec, s[34:35]
	s_waitcnt vmcnt(10)
	s_nop 7
	ds_read2_b32 v[64:65], v145 offset0:50 offset1:51
	s_waitcnt lgkmcnt(0)
	s_nop 7
	s_nop 0
	s_nop 7
	s_nop 0
	s_nop 7
	s_nop 0
	s_nop 7
	s_nop 0
	s_nop 7
	s_nop 0
	s_nop 7
	s_nop 1
	s_nop 7
	s_nop 1
	s_nop 7
	s_nop 1
	s_nop 7
	v_mov_b32_e32 v58, v84
	s_nop 7
	s_nop 0
	s_nop 7
	s_nop 0
	s_nop 7
	s_nop 0
	s_nop 7
	s_nop 0
	s_nop 7
	s_nop 0
	s_nop 7
	s_nop 0
	s_nop 7
	s_nop 1
	s_nop 7
	s_nop 1
	s_nop 7
	s_nop 1
	s_nop 7
	v_mov_b32_e32 v60, v85
	s_nop 7
	s_nop 0
	s_nop 7
	s_nop 0
	s_nop 7
	s_nop 0
	s_nop 7
	s_nop 0
	s_nop 7
	s_nop 0
	s_nop 7
	s_nop 0
	s_nop 7
	s_nop 1
	s_nop 7
	s_nop 1
	s_nop 7
	s_nop 1
	s_nop 7
	v_mov_b32_e32 v2, v86
	s_nop 7
	s_nop 0
	s_nop 7
	s_nop 0
	s_nop 7
	s_nop 0
	s_nop 7
	s_nop 0
	s_nop 7
	s_nop 0
	s_nop 7
	s_nop 0
	s_nop 7
	ds_read2_b32 v[54:55], v145 offset0:48 offset1:49
	v_mov_b32_e32 v48, 1.0
	s_nop 7
	v_mov_b32_e32 v49, 1.0
	v_mov_b32_e32 v50, 1.0
	s_nop 7
	v_mov_b32_e32 v51, 1.0
	v_mov_b32_e32 v52, 1.0
	s_nop 7
	v_mov_b32_e32 v59, v87
	v_mfma_f32_16x16x32_bf16 v[44:47], v[68:71], v[16:19], 0
	v_mov_b32_e32 v53, 1.0
	v_mfma_f32_16x16x32_bf16 v[16:19], v[72:75], v[16:19], 0
	v_mfma_f32_16x16x32_bf16 v[44:47], v[76:79], v[32:35], v[44:47]
	v_mfma_f32_16x16x32_bf16 v[16:19], v[80:83], v[32:35], v[16:19]
	s_nop 6
	v_add_f32_e32 v32, v40, v44
	v_mul_f32_e32 v32, 0xbfb8aa3b, v32
	v_exp_f32_e32 v32, v32
	v_add_f32_e32 v16, v36, v16
	v_add_f32_e32 v17, v37, v17
	v_mul_f32_e32 v16, 0xbfb8aa3b, v16
	v_add_f32_e32 v32, 1.0, v32
	v_rcp_f32_e32 v32, v32
	v_mul_f32_e32 v17, 0xbfb8aa3b, v17
	v_exp_f32_e32 v16, v16
	v_exp_f32_e32 v17, v17
	v_mul_f32_e32 v32, 0xc1000000, v32
	v_mul_f32_e32 v32, v58, v32
	v_mul_f32_e32 v32, 0x3fb8aa3b, v32
	v_exp_f32_e32 v32, v32
	v_add_f32_e32 v16, 1.0, v16
	v_add_f32_e32 v17, 1.0, v17
	v_rcp_f32_e32 v16, v16
	v_fma_f32 v33, -v32, v32, 1.0
	v_sqrt_f32_e32 v34, v33
	v_add_f32_e32 v33, v41, v45
	v_mul_f32_e32 v33, 0xbfb8aa3b, v33
	v_exp_f32_e32 v33, v33
	v_rcp_f32_e32 v17, v17
	v_mov_b32_e32 v44, 1.0
	v_mov_b32_e32 v45, 1.0
	v_add_f32_e32 v33, 1.0, v33
	v_rcp_f32_e32 v33, v33
	s_waitcnt lgkmcnt(0)
	v_pk_mul_f32 v[16:17], v[54:55], v[16:17]
	v_mov_b32_dpp v44, v32 row_shr:1 row_mask:0xf bank_mask:0xf
	v_add_f32_e32 v18, v38, v18
	v_mul_f32_e32 v33, 0xc1000000, v33
	v_mul_f32_e32 v33, v60, v33
	v_mul_f32_e32 v33, 0x3fb8aa3b, v33
	v_exp_f32_e32 v33, v33
	v_add_f32_e32 v19, v39, v19
	v_mul_f32_e32 v18, 0xbfb8aa3b, v18
	v_mul_f32_e32 v19, 0xbfb8aa3b, v19
	v_fma_f32 v35, -v33, v33, 1.0
	v_sqrt_f32_e32 v35, v35
	v_mov_b32_dpp v45, v33 row_shr:1 row_mask:0xf bank_mask:0xf
	v_pk_mul_f32 v[44:45], v[32:33], v[44:45]
	v_exp_f32_e32 v18, v18
	v_pk_mul_f32 v[16:17], v[16:17], v[34:35]
	v_mov_b32_dpp v48, v44 row_shr:2 row_mask:0xf bank_mask:0xf
	v_mov_b32_dpp v49, v45 row_shr:2 row_mask:0xf bank_mask:0xf
	v_mov_b32_dpp v34, v16 row_shr:1 row_mask:0xf bank_mask:0xf bound_ctrl:1
	v_mov_b32_dpp v35, v17 row_shr:1 row_mask:0xf bank_mask:0xf bound_ctrl:1
	v_pk_fma_f32 v[16:17], v[32:33], v[34:35], v[16:17]
	v_pk_mul_f32 v[48:49], v[44:45], v[48:49]
	v_exp_f32_e32 v19, v19
	v_mov_b32_dpp v32, v16 row_shr:2 row_mask:0xf bank_mask:0xf bound_ctrl:1
	v_mov_b32_dpp v33, v17 row_shr:2 row_mask:0xf bank_mask:0xf bound_ctrl:1
	v_pk_fma_f32 v[16:17], v[44:45], v[32:33], v[16:17]
	v_mov_b32_dpp v50, v48 row_shr:4 row_mask:0xf bank_mask:0xf
	v_mov_b32_dpp v51, v49 row_shr:4 row_mask:0xf bank_mask:0xf
	v_mov_b32_dpp v32, v16 row_shr:4 row_mask:0xf bank_mask:0xf bound_ctrl:1
	v_mov_b32_dpp v33, v17 row_shr:4 row_mask:0xf bank_mask:0xf bound_ctrl:1
	v_pk_fma_f32 v[16:17], v[48:49], v[32:33], v[16:17]
	v_pk_mul_f32 v[50:51], v[48:49], v[50:51]
	v_add_f32_e32 v18, 1.0, v18
	v_mov_b32_dpp v32, v16 row_shr:8 row_mask:0xf bank_mask:0xf bound_ctrl:1
	v_mov_b32_dpp v33, v17 row_shr:8 row_mask:0xf bank_mask:0xf bound_ctrl:1
	v_pk_fma_f32 v[16:17], v[50:51], v[32:33], v[16:17]
	v_add_f32_e32 v32, v42, v46
	v_mul_f32_e32 v32, 0xbfb8aa3b, v32
	v_exp_f32_e32 v32, v32
	v_add_f32_e32 v19, 1.0, v19
	v_rcp_f32_e32 v18, v18
	v_rcp_f32_e32 v19, v19
	v_add_f32_e32 v32, 1.0, v32
	v_rcp_f32_e32 v32, v32
	v_mov_b32_e32 v46, 1.0
	v_pk_mul_f32 v[18:19], v[18:19], v[64:65]
	v_mov_b32_dpp v52, v50 row_shr:8 row_mask:0xf bank_mask:0xf
	v_mul_f32_e32 v32, 0xc1000000, v32
	v_mul_f32_e32 v32, v2, v32
	v_mul_f32_e32 v32, 0x3fb8aa3b, v32
	v_exp_f32_e32 v32, v32
	v_mov_b32_dpp v53, v51 row_shr:8 row_mask:0xf bank_mask:0xf
	v_pk_mul_f32 v[52:53], v[50:51], v[52:53]
	ds_bpermute_b32 v56, v1, v52
	v_fma_f32 v33, -v32, v32, 1.0
	v_sqrt_f32_e32 v44, v33
	v_add_f32_e32 v33, v43, v47
	v_mul_f32_e32 v33, 0xbfb8aa3b, v33
	v_exp_f32_e32 v33, v33
	v_mov_b32_e32 v47, 1.0
	v_mov_b32_dpp v46, v32 row_shr:1 row_mask:0xf bank_mask:0xf
	v_pk_fma_f32 v[16:17], v[52:53], 0, v[16:17] op_sel_hi:[1,0,1]
	v_add_f32_e32 v33, 1.0, v33
	v_rcp_f32_e32 v33, v33
	ds_bpermute_b32 v34, v1, v16
	ds_bpermute_b32 v35, v1, v17
	v_cvt_pk_bf16_f32 v16, v16, v17
	v_mul_f32_e32 v33, 0xc1000000, v33
	v_mul_f32_e32 v33, v59, v33
	v_mul_f32_e32 v33, 0x3fb8aa3b, v33
	v_exp_f32_e32 v33, v33
	ds_bpermute_b32 v57, v1, v53
	v_fma_f32 v45, -v33, v33, 1.0
	v_sqrt_f32_e32 v45, v45
	v_mov_b32_dpp v47, v33 row_shr:1 row_mask:0xf bank_mask:0xf
	v_pk_mul_f32 v[48:49], v[32:33], v[46:47]
	v_mov_b32_e32 v46, 1.0
	v_pk_mul_f32 v[18:19], v[44:45], v[18:19]
	v_mov_b32_e32 v47, 1.0
	v_mov_b32_dpp v46, v48 row_shr:2 row_mask:0xf bank_mask:0xf
	v_mov_b32_dpp v44, v18 row_shr:1 row_mask:0xf bank_mask:0xf bound_ctrl:1
	v_mov_b32_dpp v45, v19 row_shr:1 row_mask:0xf bank_mask:0xf bound_ctrl:1
	v_pk_fma_f32 v[18:19], v[32:33], v[44:45], v[18:19]
	v_mov_b32_dpp v47, v49 row_shr:2 row_mask:0xf bank_mask:0xf
	v_pk_mul_f32 v[50:51], v[48:49], v[46:47]
	v_mov_b32_dpp v32, v18 row_shr:2 row_mask:0xf bank_mask:0xf bound_ctrl:1
	v_mov_b32_dpp v33, v19 row_shr:2 row_mask:0xf bank_mask:0xf bound_ctrl:1
	v_mov_b32_e32 v46, 1.0
	v_mov_b32_e32 v47, 1.0
	v_pk_fma_f32 v[18:19], v[48:49], v[32:33], v[18:19]
	v_mov_b32_dpp v46, v50 row_shr:4 row_mask:0xf bank_mask:0xf
	v_mov_b32_dpp v47, v51 row_shr:4 row_mask:0xf bank_mask:0xf
	v_mov_b32_dpp v32, v18 row_shr:4 row_mask:0xf bank_mask:0xf bound_ctrl:1
	v_mov_b32_dpp v33, v19 row_shr:4 row_mask:0xf bank_mask:0xf bound_ctrl:1
	v_pk_mul_f32 v[54:55], v[50:51], v[46:47]
	v_mov_b32_e32 v46, 1.0
	v_mov_b32_e32 v47, 1.0
	v_pk_fma_f32 v[18:19], v[50:51], v[32:33], v[18:19]
	v_mov_b32_dpp v46, v54 row_shr:8 row_mask:0xf bank_mask:0xf
	v_mov_b32_dpp v47, v55 row_shr:8 row_mask:0xf bank_mask:0xf
	v_mov_b32_dpp v32, v18 row_shr:8 row_mask:0xf bank_mask:0xf bound_ctrl:1
	v_mov_b32_dpp v33, v19 row_shr:8 row_mask:0xf bank_mask:0xf bound_ctrl:1
	v_pk_mul_f32 v[62:63], v[54:55], v[46:47]
	v_pk_fma_f32 v[18:19], v[54:55], v[32:33], v[18:19]
	ds_bpermute_b32 v46, v1, v62
	v_pk_fma_f32 v[18:19], v[62:63], 0, v[18:19] op_sel_hi:[1,0,1]
	ds_bpermute_b32 v32, v1, v18
	v_cvt_pk_bf16_f32 v17, v18, v19
	global_store_dwordx2 v[100:101], v[16:17], off offset:96
	v_cvt_pk_bf16_f32 v16, v52, v53
	v_cvt_pk_bf16_f32 v17, v62, v63
	ds_bpermute_b32 v33, v1, v19
	global_store_dwordx2 v[102:103], v[16:17], off offset:96
	v_mfma_f32_16x16x32_bf16 v[16:19], v[68:71], v[12:15], 0
	ds_bpermute_b32 v47, v1, v63
	v_mfma_f32_16x16x32_bf16 v[12:15], v[72:75], v[12:15], 0
	v_mfma_f32_16x16x32_bf16 v[16:19], v[76:79], v[28:31], v[16:19]
	v_mfma_f32_16x16x32_bf16 v[12:15], v[80:83], v[28:31], v[12:15]
	s_nop 6
	v_add_f32_e32 v16, v40, v16
	v_mul_f32_e32 v16, 0xbfb8aa3b, v16
	v_exp_f32_e32 v16, v16
	v_add_f32_e32 v12, v36, v12
	v_mul_f32_e32 v12, 0xbfb8aa3b, v12
	v_exp_f32_e32 v12, v12
	v_add_f32_e32 v16, 1.0, v16
	v_rcp_f32_e32 v16, v16
	v_add_f32_e32 v13, v37, v13
	v_add_f32_e32 v12, 1.0, v12
	v_rcp_f32_e32 v28, v12
	v_mul_f32_e32 v12, 0xc1000000, v16
	v_add_f32_e32 v16, v41, v17
	v_mul_f32_e32 v16, 0xbfb8aa3b, v16
	v_exp_f32_e32 v16, v16
	v_mul_f32_e32 v13, 0xbfb8aa3b, v13
	v_exp_f32_e32 v13, v13
	v_mul_f32_e32 v12, v58, v12
	v_add_f32_e32 v16, 1.0, v16
	v_rcp_f32_e32 v16, v16
	v_add_f32_e32 v13, 1.0, v13
	v_rcp_f32_e32 v29, v13
	v_mul_f32_e32 v12, 0x3fb8aa3b, v12
	v_mul_f32_e32 v13, 0xc1000000, v16
	v_mul_f32_e32 v13, v60, v13
	v_mul_f32_e32 v13, 0x3fb8aa3b, v13
	v_exp_f32_e32 v30, v12
	v_exp_f32_e32 v31, v13
	v_add_f32_e32 v18, v42, v18
	v_add_f32_e32 v19, v43, v19
	v_fma_f32 v12, -v30, v30, 1.0
	v_fma_f32 v13, -v31, v31, 1.0
	v_sqrt_f32_e32 v44, v12
	v_mov_b32_e32 v12, 1.0
	v_sqrt_f32_e32 v45, v13
	v_mov_b32_e32 v13, 1.0
	v_mov_b32_dpp v12, v30 row_shr:1 row_mask:0xf bank_mask:0xf
	v_mul_f32_e32 v18, 0xbfb8aa3b, v18
	v_mov_b32_dpp v13, v31 row_shr:1 row_mask:0xf bank_mask:0xf
	v_pk_mul_f32 v[48:49], v[30:31], v[12:13]
	v_mov_b32_e32 v12, 1.0
	v_mov_b32_e32 v13, 1.0
	v_mul_f32_e32 v19, 0xbfb8aa3b, v19
	v_mov_b32_dpp v12, v48 row_shr:2 row_mask:0xf bank_mask:0xf
	v_mov_b32_dpp v13, v49 row_shr:2 row_mask:0xf bank_mask:0xf
	v_pk_mul_f32 v[50:51], v[48:49], v[12:13]
	v_mov_b32_e32 v12, 1.0
	v_mov_b32_e32 v13, 1.0
	v_exp_f32_e32 v18, v18
	v_mov_b32_dpp v12, v50 row_shr:4 row_mask:0xf bank_mask:0xf
	v_mov_b32_dpp v13, v51 row_shr:4 row_mask:0xf bank_mask:0xf
	v_pk_mul_f32 v[52:53], v[50:51], v[12:13]
	v_mov_b32_e32 v12, 1.0
	v_mov_b32_e32 v13, 1.0
	v_exp_f32_e32 v19, v19
	v_mov_b32_dpp v12, v52 row_shr:8 row_mask:0xf bank_mask:0xf
	v_mov_b32_dpp v13, v53 row_shr:8 row_mask:0xf bank_mask:0xf
	v_pk_mul_f32 v[54:55], v[52:53], v[12:13]
	v_add_u32_e32 v13, 0x1100, v145
	s_waitcnt lgkmcnt(0)
	v_pk_mul_f32 v[16:17], v[54:55], v[56:57]
	ds_read2_b32 v[56:57], v13 offset1:1
	v_add_f32_e32 v14, v38, v14
	v_add_f32_e32 v15, v39, v15
	v_mul_f32_e32 v14, 0xbfb8aa3b, v14
	v_mul_f32_e32 v15, 0xbfb8aa3b, v15
	s_waitcnt lgkmcnt(0)
	v_pk_mul_f32 v[28:29], v[56:57], v[28:29]
	v_add_f32_e32 v18, 1.0, v18
	v_pk_mul_f32 v[28:29], v[28:29], v[44:45]
	v_exp_f32_e32 v14, v14
	v_add_f32_e32 v19, 1.0, v19
	v_mov_b32_dpp v44, v28 row_shr:1 row_mask:0xf bank_mask:0xf bound_ctrl:1
	v_mov_b32_dpp v45, v29 row_shr:1 row_mask:0xf bank_mask:0xf bound_ctrl:1
	v_pk_fma_f32 v[28:29], v[30:31], v[44:45], v[28:29]
	v_exp_f32_e32 v15, v15
	v_rcp_f32_e32 v18, v18
	v_mov_b32_dpp v30, v28 row_shr:2 row_mask:0xf bank_mask:0xf bound_ctrl:1
	v_mov_b32_dpp v31, v29 row_shr:2 row_mask:0xf bank_mask:0xf bound_ctrl:1
	v_pk_fma_f32 v[28:29], v[48:49], v[30:31], v[28:29]
	v_rcp_f32_e32 v19, v19
	v_add_f32_e32 v14, 1.0, v14
	v_mov_b32_dpp v30, v28 row_shr:4 row_mask:0xf bank_mask:0xf bound_ctrl:1
	v_mov_b32_dpp v31, v29 row_shr:4 row_mask:0xf bank_mask:0xf bound_ctrl:1
	v_pk_fma_f32 v[28:29], v[50:51], v[30:31], v[28:29]
	v_add_f32_e32 v15, 1.0, v15
	ds_bpermute_b32 v12, v1, v16
	v_mov_b32_dpp v30, v28 row_shr:8 row_mask:0xf bank_mask:0xf bound_ctrl:1
	v_mov_b32_dpp v31, v29 row_shr:8 row_mask:0xf bank_mask:0xf bound_ctrl:1
	v_pk_fma_f32 v[28:29], v[52:53], v[30:31], v[28:29]
	ds_bpermute_b32 v13, v1, v17
	v_pk_fma_f32 v[30:31], v[54:55], v[34:35], v[28:29]
	v_rcp_f32_e32 v34, v14
	v_mul_f32_e32 v14, 0xc1000000, v18
	v_rcp_f32_e32 v35, v15
	v_mul_f32_e32 v15, 0xc1000000, v19
	v_mul_f32_e32 v14, v2, v14
	v_mul_f32_e32 v15, v59, v15
	v_mul_f32_e32 v14, 0x3fb8aa3b, v14
	v_mul_f32_e32 v15, 0x3fb8aa3b, v15
	v_exp_f32_e32 v18, v14
	v_exp_f32_e32 v19, v15
	ds_bpermute_b32 v28, v1, v30
	ds_bpermute_b32 v29, v1, v31
	v_fma_f32 v14, -v18, v18, 1.0
	v_fma_f32 v15, -v19, v19, 1.0
	v_sqrt_f32_e32 v44, v14
	v_mov_b32_e32 v14, 1.0
	v_sqrt_f32_e32 v45, v15
	v_mov_b32_e32 v15, 1.0
	v_mov_b32_dpp v14, v18 row_shr:1 row_mask:0xf bank_mask:0xf
	v_cvt_pk_bf16_f32 v30, v30, v31
	v_mov_b32_dpp v15, v19 row_shr:1 row_mask:0xf bank_mask:0xf
	v_pk_mul_f32 v[48:49], v[18:19], v[14:15]
	v_mov_b32_e32 v14, 1.0
	v_mov_b32_e32 v15, 1.0
	v_cvt_pk_bf16_f32 v16, v16, v17
	v_mov_b32_dpp v14, v48 row_shr:2 row_mask:0xf bank_mask:0xf
	v_mov_b32_dpp v15, v49 row_shr:2 row_mask:0xf bank_mask:0xf
	v_pk_mul_f32 v[50:51], v[48:49], v[14:15]
	v_mov_b32_e32 v14, 1.0
	v_mov_b32_e32 v15, 1.0
	s_nop 0
	v_mov_b32_dpp v14, v50 row_shr:4 row_mask:0xf bank_mask:0xf
	v_mov_b32_dpp v15, v51 row_shr:4 row_mask:0xf bank_mask:0xf
	v_pk_mul_f32 v[52:53], v[50:51], v[14:15]
	v_mov_b32_e32 v14, 1.0
	v_mov_b32_e32 v15, 1.0
	s_nop 0
	v_mov_b32_dpp v14, v52 row_shr:8 row_mask:0xf bank_mask:0xf
	v_mov_b32_dpp v15, v53 row_shr:8 row_mask:0xf bank_mask:0xf
	v_pk_mul_f32 v[54:55], v[52:53], v[14:15]
	v_add_u32_e32 v15, 0x1108, v145
	ds_read2_b32 v[56:57], v15 offset1:1
	v_pk_mul_f32 v[46:47], v[54:55], v[46:47]
	ds_bpermute_b32 v14, v1, v46
	v_cvt_pk_bf16_f32 v17, v46, v47
	ds_bpermute_b32 v15, v1, v47
	s_waitcnt lgkmcnt(0)
	v_pk_mul_f32 v[34:35], v[34:35], v[56:57]
	s_nop 0
	v_pk_mul_f32 v[34:35], v[44:45], v[34:35]
	s_nop 1
	v_mov_b32_dpp v44, v34 row_shr:1 row_mask:0xf bank_mask:0xf bound_ctrl:1
	v_mov_b32_dpp v45, v35 row_shr:1 row_mask:0xf bank_mask:0xf bound_ctrl:1
	v_pk_fma_f32 v[18:19], v[18:19], v[44:45], v[34:35]
	s_nop 1
	v_mov_b32_dpp v34, v18 row_shr:2 row_mask:0xf bank_mask:0xf bound_ctrl:1
	v_mov_b32_dpp v35, v19 row_shr:2 row_mask:0xf bank_mask:0xf bound_ctrl:1
	v_pk_fma_f32 v[18:19], v[48:49], v[34:35], v[18:19]
	s_nop 1
	v_mov_b32_dpp v34, v18 row_shr:4 row_mask:0xf bank_mask:0xf bound_ctrl:1
	v_mov_b32_dpp v35, v19 row_shr:4 row_mask:0xf bank_mask:0xf bound_ctrl:1
	v_pk_fma_f32 v[18:19], v[50:51], v[34:35], v[18:19]
	s_nop 1
	v_mov_b32_dpp v34, v18 row_shr:8 row_mask:0xf bank_mask:0xf bound_ctrl:1
	v_mov_b32_dpp v35, v19 row_shr:8 row_mask:0xf bank_mask:0xf bound_ctrl:1
	v_pk_fma_f32 v[18:19], v[52:53], v[34:35], v[18:19]
	s_nop 0
	v_pk_fma_f32 v[32:33], v[54:55], v[32:33], v[18:19]
	ds_bpermute_b32 v18, v1, v32
	v_cvt_pk_bf16_f32 v31, v32, v33
	ds_bpermute_b32 v19, v1, v33
	global_store_dwordx2 v[104:105], v[30:31], off offset:96
	v_mfma_f32_16x16x32_bf16 v[30:33], v[68:71], v[8:11], 0
	global_store_dwordx2 v[106:107], v[16:17], off offset:96
	v_mfma_f32_16x16x32_bf16 v[8:11], v[72:75], v[8:11], 0
	v_mfma_f32_16x16x32_bf16 v[30:33], v[76:79], v[24:27], v[30:33]
	v_mfma_f32_16x16x32_bf16 v[24:27], v[80:83], v[24:27], v[8:11]
	s_nop 6
	v_add_f32_e32 v8, v40, v30
	v_add_f32_e32 v9, v36, v24
	v_mul_f32_e32 v9, 0xbfb8aa3b, v9
	v_exp_f32_e32 v9, v9
	v_mul_f32_e32 v8, 0xbfb8aa3b, v8
	v_exp_f32_e32 v8, v8
	v_add_f32_e32 v11, v37, v25
	v_add_f32_e32 v9, 1.0, v9
	v_rcp_f32_e32 v10, v9
	v_add_f32_e32 v9, v41, v31
	v_mul_f32_e32 v9, 0xbfb8aa3b, v9
	v_exp_f32_e32 v9, v9
	v_add_f32_e32 v8, 1.0, v8
	v_rcp_f32_e32 v8, v8
	v_mul_f32_e32 v11, 0xbfb8aa3b, v11
	v_add_f32_e32 v9, 1.0, v9
	v_rcp_f32_e32 v9, v9
	v_mul_f32_e32 v8, 0xc1000000, v8
	v_mul_f32_e32 v8, v58, v8
	v_mul_f32_e32 v8, 0x3fb8aa3b, v8
	v_mul_f32_e32 v9, 0xc1000000, v9
	v_mul_f32_e32 v9, v60, v9
	v_mul_f32_e32 v9, 0x3fb8aa3b, v9
	v_exp_f32_e32 v16, v8
	v_exp_f32_e32 v17, v9
	v_exp_f32_e32 v11, v11
	v_fma_f32 v8, -v16, v16, 1.0
	v_fma_f32 v9, -v17, v17, 1.0
	v_sqrt_f32_e32 v30, v8
	v_mov_b32_e32 v8, 1.0
	v_sqrt_f32_e32 v31, v9
	v_mov_b32_e32 v9, 1.0
	v_mov_b32_dpp v8, v16 row_shr:1 row_mask:0xf bank_mask:0xf
	v_add_f32_e32 v11, 1.0, v11
	v_mov_b32_dpp v9, v17 row_shr:1 row_mask:0xf bank_mask:0xf
	v_pk_mul_f32 v[34:35], v[16:17], v[8:9]
	v_mov_b32_e32 v8, 1.0
	v_mov_b32_e32 v9, 1.0
	v_rcp_f32_e32 v11, v11
	v_mov_b32_dpp v8, v34 row_shr:2 row_mask:0xf bank_mask:0xf
	v_mov_b32_dpp v9, v35 row_shr:2 row_mask:0xf bank_mask:0xf
	v_pk_mul_f32 v[44:45], v[34:35], v[8:9]
	v_mov_b32_e32 v8, 1.0
	v_mov_b32_e32 v9, 1.0
	s_nop 0
	v_mov_b32_dpp v8, v44 row_shr:4 row_mask:0xf bank_mask:0xf
	v_mov_b32_dpp v9, v45 row_shr:4 row_mask:0xf bank_mask:0xf
	v_pk_mul_f32 v[46:47], v[44:45], v[8:9]
	v_mov_b32_e32 v8, 1.0
	v_mov_b32_e32 v9, 1.0
	s_nop 0
	v_mov_b32_dpp v8, v46 row_shr:8 row_mask:0xf bank_mask:0xf
	v_mov_b32_dpp v9, v47 row_shr:8 row_mask:0xf bank_mask:0xf
	v_pk_mul_f32 v[48:49], v[46:47], v[8:9]
	s_nop 0
	v_pk_mul_f32 v[8:9], v[48:49], v[12:13]
	v_add_u32_e32 v12, 0x2140, v145
	ds_read2_b32 v[12:13], v12 offset1:1
	ds_bpermute_b32 v24, v1, v8
	ds_bpermute_b32 v25, v1, v9
	v_cvt_pk_bf16_f32 v8, v8, v9
	s_waitcnt lgkmcnt(0)
	v_pk_mul_f32 v[10:11], v[12:13], v[10:11]
	s_nop 0
	v_pk_mul_f32 v[10:11], v[10:11], v[30:31]
	v_mov_b32_e32 v30, 1.0
	v_mov_b32_e32 v31, 1.0
	v_mov_b32_dpp v12, v10 row_shr:1 row_mask:0xf bank_mask:0xf bound_ctrl:1
	v_mov_b32_dpp v13, v11 row_shr:1 row_mask:0xf bank_mask:0xf bound_ctrl:1
	v_pk_fma_f32 v[10:11], v[16:17], v[12:13], v[10:11]
	s_nop 1
	v_mov_b32_dpp v12, v10 row_shr:2 row_mask:0xf bank_mask:0xf bound_ctrl:1
	v_mov_b32_dpp v13, v11 row_shr:2 row_mask:0xf bank_mask:0xf bound_ctrl:1
	v_pk_fma_f32 v[10:11], v[34:35], v[12:13], v[10:11]
	s_nop 1
	v_mov_b32_dpp v12, v10 row_shr:4 row_mask:0xf bank_mask:0xf bound_ctrl:1
	v_mov_b32_dpp v13, v11 row_shr:4 row_mask:0xf bank_mask:0xf bound_ctrl:1
	v_pk_fma_f32 v[10:11], v[44:45], v[12:13], v[10:11]
	s_nop 1
	v_mov_b32_dpp v12, v10 row_shr:8 row_mask:0xf bank_mask:0xf bound_ctrl:1
	v_mov_b32_dpp v13, v11 row_shr:8 row_mask:0xf bank_mask:0xf bound_ctrl:1
	v_pk_fma_f32 v[10:11], v[46:47], v[12:13], v[10:11]
	v_add_f32_e32 v12, v42, v32
	v_mul_f32_e32 v12, 0xbfb8aa3b, v12
	v_exp_f32_e32 v12, v12
	v_pk_fma_f32 v[10:11], v[48:49], v[28:29], v[10:11]
	v_mov_b32_e32 v32, 1.0
	ds_bpermute_b32 v16, v1, v10
	v_add_f32_e32 v12, 1.0, v12
	v_rcp_f32_e32 v13, v12
	v_add_f32_e32 v12, v38, v26
	v_mul_f32_e32 v12, 0xbfb8aa3b, v12
	v_exp_f32_e32 v12, v12
	v_mul_f32_e32 v13, 0xc1000000, v13
	v_mul_f32_e32 v13, v2, v13
	v_mul_f32_e32 v13, 0x3fb8aa3b, v13
	v_exp_f32_e32 v26, v13
	v_add_f32_e32 v12, 1.0, v12
	v_rcp_f32_e32 v12, v12
	ds_bpermute_b32 v17, v1, v11
	v_fma_f32 v13, -v26, v26, 1.0
	v_sqrt_f32_e32 v28, v13
	v_add_f32_e32 v13, v43, v33
	v_mul_f32_e32 v13, 0xbfb8aa3b, v13
	v_exp_f32_e32 v13, v13
	v_mov_b32_dpp v30, v26 row_shr:1 row_mask:0xf bank_mask:0xf
	v_mov_b32_e32 v33, 1.0
	v_cvt_pk_bf16_f32 v10, v10, v11
	v_add_f32_e32 v13, 1.0, v13
	v_rcp_f32_e32 v29, v13
	v_add_f32_e32 v13, v39, v27
	v_mul_f32_e32 v13, 0xbfb8aa3b, v13
	v_exp_f32_e32 v13, v13
	v_mul_f32_e32 v27, 0xc1000000, v29
	v_mul_f32_e32 v27, v59, v27
	v_mul_f32_e32 v27, 0x3fb8aa3b, v27
	v_exp_f32_e32 v27, v27
	v_add_f32_e32 v13, 1.0, v13
	v_rcp_f32_e32 v13, v13
	v_mov_b32_dpp v31, v27 row_shr:1 row_mask:0xf bank_mask:0xf
	v_pk_mul_f32 v[30:31], v[26:27], v[30:31]
	v_fma_f32 v29, -v27, v27, 1.0
	v_sqrt_f32_e32 v29, v29
	v_mov_b32_dpp v32, v30 row_shr:2 row_mask:0xf bank_mask:0xf
	v_mov_b32_dpp v33, v31 row_shr:2 row_mask:0xf bank_mask:0xf
	v_pk_mul_f32 v[34:35], v[30:31], v[32:33]
	v_mov_b32_e32 v32, 1.0
	v_mov_b32_e32 v33, 1.0
	s_nop 0
	v_mov_b32_dpp v32, v34 row_shr:4 row_mask:0xf bank_mask:0xf
	v_mov_b32_dpp v33, v35 row_shr:4 row_mask:0xf bank_mask:0xf
	v_pk_mul_f32 v[44:45], v[34:35], v[32:33]
	v_mov_b32_e32 v32, 1.0
	v_mov_b32_e32 v33, 1.0
	s_nop 0
	v_mov_b32_dpp v32, v44 row_shr:8 row_mask:0xf bank_mask:0xf
	v_mov_b32_dpp v33, v45 row_shr:8 row_mask:0xf bank_mask:0xf
	v_pk_mul_f32 v[46:47], v[44:45], v[32:33]
	v_add_u32_e32 v33, 0x2148, v145
	ds_read2_b32 v[48:49], v33 offset1:1
	v_pk_mul_f32 v[14:15], v[46:47], v[14:15]
	ds_bpermute_b32 v32, v1, v14
	v_cvt_pk_bf16_f32 v9, v14, v15
	ds_bpermute_b32 v33, v1, v15
	s_waitcnt lgkmcnt(0)
	v_pk_mul_f32 v[12:13], v[12:13], v[48:49]
	s_nop 0
	v_pk_mul_f32 v[12:13], v[28:29], v[12:13]
	s_nop 1
	v_mov_b32_dpp v28, v12 row_shr:1 row_mask:0xf bank_mask:0xf bound_ctrl:1
	v_mov_b32_dpp v29, v13 row_shr:1 row_mask:0xf bank_mask:0xf bound_ctrl:1
	v_pk_fma_f32 v[12:13], v[26:27], v[28:29], v[12:13]
	s_nop 1
	v_mov_b32_dpp v26, v12 row_shr:2 row_mask:0xf bank_mask:0xf bound_ctrl:1
	v_mov_b32_dpp v27, v13 row_shr:2 row_mask:0xf bank_mask:0xf bound_ctrl:1
	v_pk_fma_f32 v[12:13], v[30:31], v[26:27], v[12:13]
	s_nop 1
	v_mov_b32_dpp v26, v12 row_shr:4 row_mask:0xf bank_mask:0xf bound_ctrl:1
	v_mov_b32_dpp v27, v13 row_shr:4 row_mask:0xf bank_mask:0xf bound_ctrl:1
	v_pk_fma_f32 v[12:13], v[34:35], v[26:27], v[12:13]
	s_nop 1
	v_mov_b32_dpp v26, v12 row_shr:8 row_mask:0xf bank_mask:0xf bound_ctrl:1
	v_mov_b32_dpp v27, v13 row_shr:8 row_mask:0xf bank_mask:0xf bound_ctrl:1
	v_pk_fma_f32 v[12:13], v[44:45], v[26:27], v[12:13]
	s_nop 0
	v_pk_fma_f32 v[18:19], v[46:47], v[18:19], v[12:13]
	ds_bpermute_b32 v12, v1, v18
	v_cvt_pk_bf16_f32 v11, v18, v19
	global_store_dwordx2 v[96:97], v[10:11], off offset:96
	global_store_dwordx2 v[98:99], v[8:9], off offset:96
	v_mfma_f32_16x16x32_bf16 v[8:11], v[68:71], v[4:7], 0
	ds_bpermute_b32 v13, v1, v19
	v_mfma_f32_16x16x32_bf16 v[4:7], v[72:75], v[4:7], 0
	v_mfma_f32_16x16x32_bf16 v[8:11], v[76:79], v[20:23], v[8:11]
	v_mfma_f32_16x16x32_bf16 v[4:7], v[80:83], v[20:23], v[4:7]
	s_nop 6
	v_add_f32_e32 v8, v40, v8
	v_mul_f32_e32 v8, 0xbfb8aa3b, v8
	v_exp_f32_e32 v8, v8
	v_add_f32_e32 v4, v36, v4
	v_add_f32_e32 v9, v41, v9
	v_mul_f32_e32 v4, 0xbfb8aa3b, v4
	v_mul_f32_e32 v9, 0xbfb8aa3b, v9
	v_add_f32_e32 v8, 1.0, v8
	v_exp_f32_e32 v4, v4
	v_exp_f32_e32 v9, v9
	v_rcp_f32_e32 v14, v8
	v_add_f32_e32 v5, v37, v5
	v_mul_f32_e32 v5, 0xbfb8aa3b, v5
	v_add_f32_e32 v4, 1.0, v4
	v_add_f32_e32 v9, 1.0, v9
	v_exp_f32_e32 v5, v5
	v_rcp_f32_e32 v8, v4
	v_mul_f32_e32 v4, 0xc1000000, v14
	v_rcp_f32_e32 v14, v9
	v_add_f32_e32 v5, 1.0, v5
	v_rcp_f32_e32 v9, v5
	v_mul_f32_e32 v4, v58, v4
	v_mul_f32_e32 v5, 0xc1000000, v14
	v_mul_f32_e32 v5, v60, v5
	v_mul_f32_e32 v4, 0x3fb8aa3b, v4
	v_mul_f32_e32 v5, 0x3fb8aa3b, v5
	v_exp_f32_e32 v18, v4
	v_exp_f32_e32 v19, v5
	v_add_f32_e32 v10, v42, v10
	v_mul_f32_e32 v10, 0xbfb8aa3b, v10
	v_fma_f32 v4, -v18, v18, 1.0
	v_fma_f32 v5, -v19, v19, 1.0
	v_sqrt_f32_e32 v20, v4
	v_mov_b32_e32 v4, 1.0
	v_sqrt_f32_e32 v21, v5
	v_mov_b32_e32 v5, 1.0
	v_mov_b32_dpp v4, v18 row_shr:1 row_mask:0xf bank_mask:0xf
	v_exp_f32_e32 v10, v10
	v_mov_b32_dpp v5, v19 row_shr:1 row_mask:0xf bank_mask:0xf
	v_pk_mul_f32 v[22:23], v[18:19], v[4:5]
	v_mov_b32_e32 v4, 1.0
	v_mov_b32_e32 v5, 1.0
	v_add_f32_e32 v6, v38, v6
	v_mov_b32_dpp v4, v22 row_shr:2 row_mask:0xf bank_mask:0xf
	v_mov_b32_dpp v5, v23 row_shr:2 row_mask:0xf bank_mask:0xf
	v_pk_mul_f32 v[26:27], v[22:23], v[4:5]
	v_mov_b32_e32 v4, 1.0
	v_mov_b32_e32 v5, 1.0
	v_mul_f32_e32 v6, 0xbfb8aa3b, v6
	v_mov_b32_dpp v4, v26 row_shr:4 row_mask:0xf bank_mask:0xf
	v_mov_b32_dpp v5, v27 row_shr:4 row_mask:0xf bank_mask:0xf
	v_pk_mul_f32 v[28:29], v[26:27], v[4:5]
	v_mov_b32_e32 v4, 1.0
	v_mov_b32_e32 v5, 1.0
	v_add_f32_e32 v10, 1.0, v10
	v_mov_b32_dpp v4, v28 row_shr:8 row_mask:0xf bank_mask:0xf
	v_mov_b32_dpp v5, v29 row_shr:8 row_mask:0xf bank_mask:0xf
	v_pk_mul_f32 v[30:31], v[28:29], v[4:5]
	v_add_u32_e32 v5, 0x3180, v145
	v_pk_mul_f32 v[14:15], v[30:31], v[24:25]
	ds_read2_b32 v[24:25], v5 offset1:1
	v_exp_f32_e32 v6, v6
	v_rcp_f32_e32 v10, v10
	v_add_f32_e32 v7, v39, v7
	v_mul_f32_e32 v7, 0xbfb8aa3b, v7
	s_waitcnt lgkmcnt(0)
	v_pk_mul_f32 v[8:9], v[24:25], v[8:9]
	v_add_f32_e32 v6, 1.0, v6
	v_pk_mul_f32 v[8:9], v[8:9], v[20:21]
	v_exp_f32_e32 v7, v7
	ds_bpermute_b32 v4, v1, v14
	v_mov_b32_dpp v20, v8 row_shr:1 row_mask:0xf bank_mask:0xf bound_ctrl:1
	v_mov_b32_dpp v21, v9 row_shr:1 row_mask:0xf bank_mask:0xf bound_ctrl:1
	v_pk_fma_f32 v[8:9], v[18:19], v[20:21], v[8:9]
	v_add_f32_e32 v7, 1.0, v7
	ds_bpermute_b32 v5, v1, v15
	v_mov_b32_dpp v18, v8 row_shr:2 row_mask:0xf bank_mask:0xf bound_ctrl:1
	v_mov_b32_dpp v19, v9 row_shr:2 row_mask:0xf bank_mask:0xf bound_ctrl:1
	v_pk_fma_f32 v[8:9], v[22:23], v[18:19], v[8:9]
	s_nop 1
	v_mov_b32_dpp v18, v8 row_shr:4 row_mask:0xf bank_mask:0xf bound_ctrl:1
	v_mov_b32_dpp v19, v9 row_shr:4 row_mask:0xf bank_mask:0xf bound_ctrl:1
	v_pk_fma_f32 v[8:9], v[26:27], v[18:19], v[8:9]
	s_nop 1
	v_mov_b32_dpp v18, v8 row_shr:8 row_mask:0xf bank_mask:0xf bound_ctrl:1
	v_mov_b32_dpp v19, v9 row_shr:8 row_mask:0xf bank_mask:0xf bound_ctrl:1
	v_pk_fma_f32 v[8:9], v[28:29], v[18:19], v[8:9]
	v_rcp_f32_e32 v18, v6
	v_mul_f32_e32 v6, 0xc1000000, v10
	v_mul_f32_e32 v2, v2, v6
	v_mul_f32_e32 v2, 0x3fb8aa3b, v2
	v_exp_f32_e32 v10, v2
	v_mov_b32_e32 v6, 1.0
	v_rcp_f32_e32 v19, v7
	v_mov_b32_e32 v7, 1.0
	v_fma_f32 v2, -v10, v10, 1.0
	v_sqrt_f32_e32 v20, v2
	v_add_f32_e32 v2, v43, v11
	v_mul_f32_e32 v2, 0xbfb8aa3b, v2
	v_exp_f32_e32 v2, v2
	v_mov_b32_dpp v6, v10 row_shr:1 row_mask:0xf bank_mask:0xf
	v_pk_fma_f32 v[16:17], v[30:31], v[16:17], v[8:9]
	ds_bpermute_b32 v8, v1, v16
	v_add_f32_e32 v2, 1.0, v2
	v_rcp_f32_e32 v2, v2
	ds_bpermute_b32 v9, v1, v17
	v_cvt_pk_bf16_f32 v16, v16, v17
	v_mul_f32_e32 v2, 0xc1000000, v2
	v_mul_f32_e32 v2, v59, v2
	v_mul_f32_e32 v2, 0x3fb8aa3b, v2
	v_exp_f32_e32 v11, v2
	s_nop 0
	v_fma_f32 v2, -v11, v11, 1.0
	v_mov_b32_dpp v7, v11 row_shr:1 row_mask:0xf bank_mask:0xf
	v_pk_mul_f32 v[24:25], v[10:11], v[6:7]
	v_mov_b32_e32 v6, 1.0
	v_mov_b32_e32 v7, 1.0
	v_sqrt_f32_e32 v21, v2
	v_mov_b32_dpp v6, v24 row_shr:2 row_mask:0xf bank_mask:0xf
	v_mov_b32_dpp v7, v25 row_shr:2 row_mask:0xf bank_mask:0xf
	v_pk_mul_f32 v[26:27], v[24:25], v[6:7]
	v_mov_b32_e32 v6, 1.0
	v_mov_b32_e32 v7, 1.0
	v_add_u32_e32 v2, 0x3188, v145
	v_mov_b32_dpp v6, v26 row_shr:4 row_mask:0xf bank_mask:0xf
	v_mov_b32_dpp v7, v27 row_shr:4 row_mask:0xf bank_mask:0xf
	v_pk_mul_f32 v[28:29], v[26:27], v[6:7]
	v_mov_b32_e32 v6, 1.0
	v_mov_b32_e32 v7, 1.0
	s_nop 0
	v_mov_b32_dpp v6, v28 row_shr:8 row_mask:0xf bank_mask:0xf
	v_mov_b32_dpp v7, v29 row_shr:8 row_mask:0xf bank_mask:0xf
	v_pk_mul_f32 v[30:31], v[28:29], v[6:7]
	s_nop 0
	v_pk_mul_f32 v[22:23], v[30:31], v[32:33]
	ds_read2_b32 v[32:33], v2 offset1:1
	ds_bpermute_b32 v6, v1, v22
	ds_bpermute_b32 v7, v1, v23
	s_waitcnt lgkmcnt(0)
	v_pk_mul_f32 v[18:19], v[18:19], v[32:33]
	s_nop 0
	v_pk_mul_f32 v[18:19], v[20:21], v[18:19]
	s_nop 1
	v_mov_b32_dpp v20, v18 row_shr:1 row_mask:0xf bank_mask:0xf bound_ctrl:1
	v_mov_b32_dpp v21, v19 row_shr:1 row_mask:0xf bank_mask:0xf bound_ctrl:1
	v_pk_fma_f32 v[10:11], v[10:11], v[20:21], v[18:19]
	s_nop 1
	v_mov_b32_dpp v18, v10 row_shr:2 row_mask:0xf bank_mask:0xf bound_ctrl:1
	v_mov_b32_dpp v19, v11 row_shr:2 row_mask:0xf bank_mask:0xf bound_ctrl:1
	v_pk_fma_f32 v[10:11], v[24:25], v[18:19], v[10:11]
	s_nop 1
	v_mov_b32_dpp v18, v10 row_shr:4 row_mask:0xf bank_mask:0xf bound_ctrl:1
	v_mov_b32_dpp v19, v11 row_shr:4 row_mask:0xf bank_mask:0xf bound_ctrl:1
	v_pk_fma_f32 v[10:11], v[26:27], v[18:19], v[10:11]
	s_nop 1
	v_mov_b32_dpp v18, v10 row_shr:8 row_mask:0xf bank_mask:0xf bound_ctrl:1
	v_mov_b32_dpp v19, v11 row_shr:8 row_mask:0xf bank_mask:0xf bound_ctrl:1
	v_pk_fma_f32 v[10:11], v[28:29], v[18:19], v[10:11]
	s_nop 0
	v_pk_fma_f32 v[12:13], v[30:31], v[12:13], v[10:11]
	ds_bpermute_b32 v10, v1, v12
	ds_bpermute_b32 v11, v1, v13
	v_cvt_pk_bf16_f32 v17, v12, v13
	v_cvt_pk_bf16_f32 v12, v14, v15
	v_cvt_pk_bf16_f32 v13, v22, v23
	global_store_dwordx2 v[114:115], v[16:17], off offset:96
	global_store_dwordx2 v[116:117], v[12:13], off offset:96
	s_and_saveexec_b64 s[34:35], vcc
	s_cbranch_execz .LBB0_518
	v_add_u32_e32 v0, 48, v0
	v_ashrrev_i32_e32 v1, 31, v0
	v_lshl_add_u64 v[0:1], s[42:43], 0, v[0:1]
	v_lshlrev_b64 v[0:1], 2, v[0:1]
	v_lshl_add_u64 v[12:13], s[84:85], 0, v[0:1]
	v_lshl_add_u64 v[0:1], s[86:87], 0, v[0:1]
	global_store_dwordx4 v[12:13], v[4:7], off
	s_waitcnt lgkmcnt(0)
	global_store_dwordx4 v[0:1], v[8:11], off
	s_branch .LBB0_518
